# GEMM epilogue stores made agent-scope write-through (sc1) so the grid-barrier L2 writeback is short; plus hand-written LDS-DMA phase0 conversion
# speedup vs baseline: 1.0082x; 1.0041x over previous
; #define PG8_STAGE(bufoff, gbase, voff) do { _Pragma("unroll") for (int _i = 0; _i < 2; ++_i) \
;         __builtin_amdgcn_global_load_lds((const unsigned*)((const char*)(gbase) + (voff)[_i]), (PG8_LAS unsigned*)(lds + (bufoff) + ldsw + _i * 8192), 16, 0, 0); } while (0)
; #define PG8_LDA(dst, b, h) do { _Pragma("unroll") for (int m = 0; m < 4; ++m) _Pragma("unroll") for (int k = 0; k < 2; ++k) dst[m][k] = *(const PG8_LAS bf16x8*)(lds + PG8_SA(b, h) + aoff + m * 2048 + k * 1024); } while (0)
; #define PG8_LDB(dst, b, h) do { _Pragma("unroll") for (int n = 0; n < 2; ++n) _Pragma("unroll") for (int k = 0; k < 2; ++k) dst[n][k] = *(const PG8_LAS bf16x8*)(lds + PG8_SB(b, h) + boff + n * 2048 + k * 1024); } while (0)
; #define PG8_MMA(ai, bj, At, Bt) do { __builtin_amdgcn_s_setprio(1); _Pragma("unroll") for (int m = 0; m < 4; ++m) _Pragma("unroll") for (int n = 0; n < 2; ++n) _Pragma("unroll") for (int k = 0; k < 2; ++k) \
;         acc[ai][bj][m][n] = __builtin_amdgcn_mfma_f32_16x16x32_bf16(Bt[n][k], At[m][k], acc[ai][bj][m][n], 0, 0, 0); __builtin_amdgcn_s_setprio(0); } while (0)
; #define PG8_WAIT_V(n) asm volatile("s_waitcnt vmcnt(" #n ")" ::: "memory")
; #define PG8_WAIT_L(n) asm volatile("s_waitcnt lgkmcnt(" #n ")" ::: "memory")
; template <class Epi, class Sched>
; __device__ __forceinline__ void gemm_phase(PG8_LAS unsigned char* lds, const Gemm g, const Sched& S, const Epi& E) {
;     ...
;             const bool last = (t == nt - 2);
;             const char* a1 = cA + (size_t)(t + 1) * kstep;
;             const char* a2 = last ? nA : cA + (size_t)(t + 2) * kstep; const char* b2 = last ? nB : cB + (size_t)(t + 2) * kstep;
;             const char* a3 = a2 + kstep; const char* b3 = b2 + kstep;
;             if (last && has_next) S.a_ready(nxt);
;             PG8_LDB(B0, 0, 0); PG8_SCHED; PG8_LDA(At, 0, 0); PG8_STAGE(PG8_SA(1, 1), a1 + hstep, voffA);
;             PG8_WAIT_L(8); PG8_BAR; PG8_WAIT_L(0); PG8_MMA(0, 0, At, B0); PG8_BAR; PG8_SCHED;
;             PG8_LDB(B1, 0, 1); PG8_STAGE(PG8_SB(0, 0), b2, voffB);
;             PG8_BAR; PG8_WAIT_L(0); PG8_MMA(0, 1, At, B1); PG8_BAR;
;             PG8_LDA(At, 0, 1); PG8_STAGE(PG8_SA(0, 0), a2, voffA);
;             PG8_BAR; PG8_WAIT_L(0); PG8_MMA(1, 0, At, B0); PG8_BAR; PG8_SCHED;
;             PG8_STAGE(PG8_SB(0, 1), b2 + hstep, voffB);
;             PG8_WAIT_V(6); PG8_BAR; PG8_MMA(1, 1, At, B1); PG8_BAR;
.LBB0_101:
	s_add_u32 s26, s52, 0xfff80080
	s_addc_u32 s27, s53, -1
	s_add_i32 vcc_lo, 0, 0x10000
	v_add_u32_e32 v140, vcc_lo, v242
	ds_read_b128 v[128:131], v140
	ds_read_b128 v[132:135], v140 offset:1024
	ds_read_b128 v[136:139], v140 offset:2048
	ds_read_b128 v[140:143], v140 offset:3072
	s_cmp_eq_u32 s29, 28
	s_cselect_b32 s55, s8, s27
	s_cselect_b32 s54, s41, s26
	s_cselect_b32 s45, s9, s28
	s_cselect_b32 s44, s43, s47
	v_lshl_add_u64 v[192:193], s[52:53], 0, v[188:189]
	s_add_i32 m0, s62, 0xc000
	ds_read_b128 v[144:147], v243
	ds_read_b128 v[148:151], v243 offset:1024
	ds_read_b128 v[152:155], v243 offset:2048
	ds_read_b128 v[156:159], v243 offset:3072
	ds_read_b128 v[160:163], v243 offset:4096
	ds_read_b128 v[164:167], v243 offset:5120
	ds_read_b128 v[168:171], v243 offset:6144
	ds_read_b128 v[176:179], v243 offset:7168
	global_load_lds_dwordx4 v[192:193], off
	v_lshl_add_u64 v[192:193], s[52:53], 0, v[190:191]
	s_add_i32 m0, s62, 0xe000
	s_nop 0
	global_load_lds_dwordx4 v[192:193], off
	s_waitcnt lgkmcnt(8)
	s_barrier
	s_waitcnt lgkmcnt(0)
	s_setprio 1
	s_waitcnt lgkmcnt(0)
	v_mfma_f32_16x16x32_bf16 v[124:127], v[128:131], v[144:147], v[124:127]
	v_mfma_f32_16x16x32_bf16 v[120:123], v[136:139], v[144:147], v[120:123]
	v_mfma_f32_16x16x32_bf16 v[116:119], v[128:131], v[152:155], v[116:119]
	v_mfma_f32_16x16x32_bf16 v[112:115], v[136:139], v[152:155], v[112:115]
	v_mfma_f32_16x16x32_bf16 v[108:111], v[128:131], v[160:163], v[108:111]
	v_mfma_f32_16x16x32_bf16 v[104:107], v[136:139], v[160:163], v[104:107]
	v_mfma_f32_16x16x32_bf16 v[100:103], v[128:131], v[168:171], v[100:103]
	v_mfma_f32_16x16x32_bf16 v[96:99], v[136:139], v[168:171], v[96:99]
	v_mfma_f32_16x16x32_bf16 v[124:127], v[132:135], v[148:151], v[124:127]
	v_mfma_f32_16x16x32_bf16 v[120:123], v[140:143], v[148:151], v[120:123]
	v_mfma_f32_16x16x32_bf16 v[116:119], v[132:135], v[156:159], v[116:119]
	v_mfma_f32_16x16x32_bf16 v[112:115], v[140:143], v[156:159], v[112:115]
	v_mfma_f32_16x16x32_bf16 v[108:111], v[132:135], v[164:167], v[108:111]
	v_mfma_f32_16x16x32_bf16 v[104:107], v[140:143], v[164:167], v[104:107]
	v_mfma_f32_16x16x32_bf16 v[100:103], v[132:135], v[176:179], v[100:103]
	v_mfma_f32_16x16x32_bf16 v[96:99], v[140:143], v[176:179], v[96:99]
	s_setprio 0
	s_barrier
	s_add_i32 s26, 0, 0x14000
	s_add_i32 s27, vcc_lo, s59
	v_add_u32_e32 v172, s26, v242
	v_lshl_add_u64 v[208:209], s[44:45], 0, v[184:185]
	s_mov_b32 m0, s27
	ds_read_b128 v[192:195], v172
	ds_read_b128 v[196:199], v172 offset:1024
	ds_read_b128 v[200:203], v172 offset:2048
	ds_read_b128 v[204:207], v172 offset:3072
	global_load_lds_dwordx4 v[208:209], off
	v_lshl_add_u64 v[210:211], s[44:45], 0, v[180:181]
	s_add_i32 m0, s27, 0x2000
	s_nop 0
	global_load_lds_dwordx4 v[210:211], off
	s_barrier
	s_waitcnt lgkmcnt(0)
	s_setprio 1
	s_waitcnt lgkmcnt(0)
	v_mfma_f32_16x16x32_bf16 v[60:63], v[192:195], v[144:147], v[60:63]
	v_mfma_f32_16x16x32_bf16 v[56:59], v[200:203], v[144:147], v[56:59]
	v_mfma_f32_16x16x32_bf16 v[52:55], v[192:195], v[152:155], v[52:55]
	v_mfma_f32_16x16x32_bf16 v[48:51], v[200:203], v[152:155], v[48:51]
	v_mfma_f32_16x16x32_bf16 v[44:47], v[192:195], v[160:163], v[44:47]
	v_mfma_f32_16x16x32_bf16 v[40:43], v[200:203], v[160:163], v[40:43]
	v_mfma_f32_16x16x32_bf16 v[36:39], v[192:195], v[168:171], v[36:39]
	v_mfma_f32_16x16x32_bf16 v[32:35], v[200:203], v[168:171], v[32:35]
	v_mfma_f32_16x16x32_bf16 v[60:63], v[196:199], v[148:151], v[60:63]
	v_mfma_f32_16x16x32_bf16 v[56:59], v[204:207], v[148:151], v[56:59]
	v_mfma_f32_16x16x32_bf16 v[52:55], v[196:199], v[156:159], v[52:55]
	v_mfma_f32_16x16x32_bf16 v[48:51], v[204:207], v[156:159], v[48:51]
	v_mfma_f32_16x16x32_bf16 v[44:47], v[196:199], v[164:167], v[44:47]
	v_mfma_f32_16x16x32_bf16 v[40:43], v[204:207], v[164:167], v[40:43]
	v_mfma_f32_16x16x32_bf16 v[36:39], v[196:199], v[176:179], v[36:39]
	v_mfma_f32_16x16x32_bf16 v[32:35], v[204:207], v[176:179], v[32:35]
	s_setprio 0
	s_mov_b32 m0, s62
	v_lshl_add_u64 v[212:213], s[54:55], 0, v[186:187]
	s_barrier
	ds_read_b128 v[144:147], v243 offset:16384
	ds_read_b128 v[148:151], v243 offset:17408
	ds_read_b128 v[152:155], v243 offset:18432
	ds_read_b128 v[156:159], v243 offset:19456
	ds_read_b128 v[160:163], v243 offset:20480
	ds_read_b128 v[164:167], v243 offset:21504
	ds_read_b128 v[168:171], v243 offset:22528
	ds_read_b128 v[176:179], v243 offset:23552
	global_load_lds_dwordx4 v[212:213], off
	v_lshl_add_u64 v[214:215], s[54:55], 0, v[182:183]
	s_mov_b32 m0, s63
	s_nop 0
	global_load_lds_dwordx4 v[214:215], off
	s_barrier
	s_waitcnt lgkmcnt(0)
	s_setprio 1
	s_waitcnt lgkmcnt(0)
	v_mfma_f32_16x16x32_bf16 v[92:95], v[128:131], v[144:147], v[92:95]
	v_mfma_f32_16x16x32_bf16 v[88:91], v[136:139], v[144:147], v[88:91]
	v_mfma_f32_16x16x32_bf16 v[84:87], v[128:131], v[152:155], v[84:87]
	v_mfma_f32_16x16x32_bf16 v[80:83], v[136:139], v[152:155], v[80:83]
	v_mfma_f32_16x16x32_bf16 v[76:79], v[128:131], v[160:163], v[76:79]
	v_mfma_f32_16x16x32_bf16 v[72:75], v[136:139], v[160:163], v[72:75]
	v_mfma_f32_16x16x32_bf16 v[68:71], v[128:131], v[168:171], v[68:71]
	v_mfma_f32_16x16x32_bf16 v[64:67], v[136:139], v[168:171], v[64:67]
	v_mfma_f32_16x16x32_bf16 v[92:95], v[132:135], v[148:151], v[92:95]
	v_mfma_f32_16x16x32_bf16 v[88:91], v[140:143], v[148:151], v[88:91]
	v_mfma_f32_16x16x32_bf16 v[84:87], v[132:135], v[156:159], v[84:87]
	v_mfma_f32_16x16x32_bf16 v[80:83], v[140:143], v[156:159], v[80:83]
	v_mfma_f32_16x16x32_bf16 v[76:79], v[132:135], v[164:167], v[76:79]
	v_mfma_f32_16x16x32_bf16 v[72:75], v[140:143], v[164:167], v[72:75]
	v_mfma_f32_16x16x32_bf16 v[68:71], v[132:135], v[176:179], v[68:71]
	v_mfma_f32_16x16x32_bf16 v[64:67], v[140:143], v[176:179], v[64:67]
	s_setprio 0
	s_barrier
; #define PG8_STAGE(bufoff, gbase, voff) do { _Pragma("unroll") for (int _i = 0; _i < 2; ++_i) \
;         __builtin_amdgcn_global_load_lds((const unsigned*)((const char*)(gbase) + (voff)[_i]), (PG8_LAS unsigned*)(lds + (bufoff) + ldsw + _i * 8192), 16, 0, 0); } while (0)
; #define PG8_LDA(dst, b, h) do { _Pragma("unroll") for (int m = 0; m < 4; ++m) _Pragma("unroll") for (int k = 0; k < 2; ++k) dst[m][k] = *(const PG8_LAS bf16x8*)(lds + PG8_SA(b, h) + aoff + m * 2048 + k * 1024); } while (0)
; #define PG8_LDB(dst, b, h) do { _Pragma("unroll") for (int n = 0; n < 2; ++n) _Pragma("unroll") for (int k = 0; k < 2; ++k) dst[n][k] = *(const PG8_LAS bf16x8*)(lds + PG8_SB(b, h) + boff + n * 2048 + k * 1024); } while (0)
; #define PG8_MMA(ai, bj, At, Bt) do { __builtin_amdgcn_s_setprio(1); _Pragma("unroll") for (int m = 0; m < 4; ++m) _Pragma("unroll") for (int n = 0; n < 2; ++n) _Pragma("unroll") for (int k = 0; k < 2; ++k) \
;         acc[ai][bj][m][n] = __builtin_amdgcn_mfma_f32_16x16x32_bf16(Bt[n][k], At[m][k], acc[ai][bj][m][n], 0, 0, 0); __builtin_amdgcn_s_setprio(0); } while (0)
; #define PG8_WAIT_V(n) asm volatile("s_waitcnt vmcnt(" #n ")" ::: "memory")
; #define PG8_WAIT_L(n) asm volatile("s_waitcnt lgkmcnt(" #n ")" ::: "memory")
; #define PG8_BAR __builtin_amdgcn_s_barrier()
; #define PG8_SCHED __builtin_amdgcn_sched_barrier(0)
; template <class Epi, class Sched>
; __device__ __forceinline__ void gemm_phase(PG8_LAS unsigned char* lds, const Gemm g, const Sched& S, const Epi& E) {
;     ...
;             PG8_BAR; PG8_WAIT_L(0); PG8_MMA(1, 0, At, B0); PG8_BAR; PG8_SCHED;
;             PG8_STAGE(PG8_SB(0, 1), b2 + hstep, voffB);
;             PG8_WAIT_V(6); PG8_BAR; PG8_MMA(1, 1, At, B1); PG8_BAR;
;             PG8_LDB(B0, 1, 0); PG8_SCHED; PG8_LDA(At, 1, 0); PG8_STAGE(PG8_SA(0, 1), a2 + hstep, voffA);
;             PG8_WAIT_L(8); PG8_BAR; PG8_WAIT_L(0); PG8_MMA(0, 0, At, B0); PG8_BAR; PG8_SCHED;
;             PG8_LDB(B1, 1, 1); PG8_STAGE(PG8_SB(1, 0), b3, voffB);
;             PG8_BAR; PG8_WAIT_L(0); PG8_MMA(0, 1, At, B1); PG8_BAR;
	s_add_u32 vcc_lo, s44, 0x80000
	s_addc_u32 vcc_hi, s45, 0
	s_add_i32 s26, s26, s59
	v_lshl_add_u64 v[128:129], vcc, 0, v[184:185]
	s_mov_b32 m0, s26
	s_nop 0
	global_load_lds_dwordx4 v[128:129], off
	v_lshl_add_u64 v[128:129], vcc, 0, v[180:181]
	s_add_i32 m0, s26, 0x2000
	s_nop 0
	global_load_lds_dwordx4 v[128:129], off
	s_waitcnt vmcnt(6)
	s_barrier
	s_setprio 1
	v_mfma_f32_16x16x32_bf16 v[28:31], v[192:195], v[144:147], v[28:31]
	v_mfma_f32_16x16x32_bf16 v[24:27], v[200:203], v[144:147], v[24:27]
	v_mfma_f32_16x16x32_bf16 v[20:23], v[192:195], v[152:155], v[20:23]
	v_mfma_f32_16x16x32_bf16 v[16:19], v[200:203], v[152:155], v[16:19]
	v_mfma_f32_16x16x32_bf16 v[12:15], v[192:195], v[160:163], v[12:15]
	v_mfma_f32_16x16x32_bf16 v[8:11], v[200:203], v[160:163], v[8:11]
	v_mfma_f32_16x16x32_bf16 v[4:7], v[192:195], v[168:171], v[4:7]
	v_mfma_f32_16x16x32_bf16 v[0:3], v[200:203], v[168:171], v[0:3]
	v_mfma_f32_16x16x32_bf16 v[28:31], v[196:199], v[148:151], v[28:31]
	v_mfma_f32_16x16x32_bf16 v[24:27], v[204:207], v[148:151], v[24:27]
	v_mfma_f32_16x16x32_bf16 v[20:23], v[196:199], v[156:159], v[20:23]
	v_mfma_f32_16x16x32_bf16 v[16:19], v[204:207], v[156:159], v[16:19]
	v_mfma_f32_16x16x32_bf16 v[12:15], v[196:199], v[164:167], v[12:15]
	v_mfma_f32_16x16x32_bf16 v[8:11], v[204:207], v[164:167], v[8:11]
	v_mfma_f32_16x16x32_bf16 v[4:7], v[196:199], v[176:179], v[4:7]
	v_mfma_f32_16x16x32_bf16 v[0:3], v[204:207], v[176:179], v[0:3]
	s_setprio 0
	s_add_i32 s26, 0, 0x18000
	v_add_u32_e32 v140, s26, v242
	s_barrier
	ds_read_b128 v[128:131], v140
	ds_read_b128 v[132:135], v140 offset:1024
	ds_read_b128 v[136:139], v140 offset:2048
	ds_read_b128 v[140:143], v140 offset:3072
	s_add_u32 s54, s54, 0x80000
	s_addc_u32 s55, s55, 0
	s_mov_b32 m0, s56
	v_lshl_add_u64 v[192:193], s[54:55], 0, v[186:187]
	ds_read_b128 v[144:147], v243 offset:32768
	ds_read_b128 v[148:151], v243 offset:33792
	ds_read_b128 v[152:155], v243 offset:34816
	ds_read_b128 v[156:159], v243 offset:35840
	ds_read_b128 v[160:163], v243 offset:36864
	ds_read_b128 v[164:167], v243 offset:37888
	ds_read_b128 v[168:171], v243 offset:38912
	ds_read_b128 v[176:179], v243 offset:39936
	global_load_lds_dwordx4 v[192:193], off
	v_lshl_add_u64 v[192:193], s[54:55], 0, v[182:183]
	s_mov_b32 m0, s0
	s_nop 0
	global_load_lds_dwordx4 v[192:193], off
	s_waitcnt lgkmcnt(8)
	s_barrier
	s_waitcnt lgkmcnt(0)
	s_setprio 1
	s_waitcnt lgkmcnt(0)
	v_mfma_f32_16x16x32_bf16 v[124:127], v[128:131], v[144:147], v[124:127]
	v_mfma_f32_16x16x32_bf16 v[120:123], v[136:139], v[144:147], v[120:123]
	v_mfma_f32_16x16x32_bf16 v[116:119], v[128:131], v[152:155], v[116:119]
	v_mfma_f32_16x16x32_bf16 v[112:115], v[136:139], v[152:155], v[112:115]
	v_mfma_f32_16x16x32_bf16 v[108:111], v[128:131], v[160:163], v[108:111]
	v_mfma_f32_16x16x32_bf16 v[104:107], v[136:139], v[160:163], v[104:107]
	v_mfma_f32_16x16x32_bf16 v[100:103], v[128:131], v[168:171], v[100:103]
	v_mfma_f32_16x16x32_bf16 v[96:99], v[136:139], v[168:171], v[96:99]
	v_mfma_f32_16x16x32_bf16 v[124:127], v[132:135], v[148:151], v[124:127]
	v_mfma_f32_16x16x32_bf16 v[120:123], v[140:143], v[148:151], v[120:123]
	v_mfma_f32_16x16x32_bf16 v[116:119], v[132:135], v[156:159], v[116:119]
	v_mfma_f32_16x16x32_bf16 v[112:115], v[140:143], v[156:159], v[112:115]
	v_mfma_f32_16x16x32_bf16 v[108:111], v[132:135], v[164:167], v[108:111]
	v_mfma_f32_16x16x32_bf16 v[104:107], v[140:143], v[164:167], v[104:107]
	v_mfma_f32_16x16x32_bf16 v[100:103], v[132:135], v[176:179], v[100:103]
	v_mfma_f32_16x16x32_bf16 v[96:99], v[140:143], v[176:179], v[96:99]
	s_setprio 0
	s_barrier
	s_add_i32 s27, 0, 0x1c000
	s_add_i32 s26, s26, s59
	v_add_u32_e32 v172, s27, v242
	v_lshl_add_u64 v[208:209], v[208:209], 0, s[38:39]
	s_mov_b32 m0, s26
	ds_read_b128 v[192:195], v172
	ds_read_b128 v[196:199], v172 offset:1024
	ds_read_b128 v[200:203], v172 offset:2048
	ds_read_b128 v[204:207], v172 offset:3072
	global_load_lds_dwordx4 v[208:209], off
	v_lshl_add_u64 v[208:209], v[210:211], 0, s[38:39]
	s_add_i32 m0, s26, 0x2000
	s_nop 0
	global_load_lds_dwordx4 v[208:209], off
	s_barrier
	s_waitcnt lgkmcnt(0)
	s_setprio 1
	s_waitcnt lgkmcnt(0)
	v_mfma_f32_16x16x32_bf16 v[60:63], v[192:195], v[144:147], v[60:63]
	v_mfma_f32_16x16x32_bf16 v[56:59], v[200:203], v[144:147], v[56:59]
	v_mfma_f32_16x16x32_bf16 v[52:55], v[192:195], v[152:155], v[52:55]
	v_mfma_f32_16x16x32_bf16 v[48:51], v[200:203], v[152:155], v[48:51]
	v_mfma_f32_16x16x32_bf16 v[44:47], v[192:195], v[160:163], v[44:47]
	v_mfma_f32_16x16x32_bf16 v[40:43], v[200:203], v[160:163], v[40:43]
	v_mfma_f32_16x16x32_bf16 v[36:39], v[192:195], v[168:171], v[36:39]
	v_mfma_f32_16x16x32_bf16 v[32:35], v[200:203], v[168:171], v[32:35]
	v_mfma_f32_16x16x32_bf16 v[60:63], v[196:199], v[148:151], v[60:63]
	v_mfma_f32_16x16x32_bf16 v[56:59], v[204:207], v[148:151], v[56:59]
	v_mfma_f32_16x16x32_bf16 v[52:55], v[196:199], v[156:159], v[52:55]
	v_mfma_f32_16x16x32_bf16 v[48:51], v[204:207], v[156:159], v[48:51]
	v_mfma_f32_16x16x32_bf16 v[44:47], v[196:199], v[164:167], v[44:47]
	v_mfma_f32_16x16x32_bf16 v[40:43], v[204:207], v[164:167], v[40:43]
	v_mfma_f32_16x16x32_bf16 v[36:39], v[196:199], v[176:179], v[36:39]
	v_mfma_f32_16x16x32_bf16 v[32:35], v[204:207], v[176:179], v[32:35]
	s_setprio 0
	s_mov_b32 m0, s58
	v_lshl_add_u64 v[208:209], v[212:213], 0, s[38:39]
	s_barrier
	ds_read_b128 v[144:147], v243 offset:49152
	ds_read_b128 v[148:151], v243 offset:50176
	ds_read_b128 v[152:155], v243 offset:51200
	ds_read_b128 v[156:159], v243 offset:52224
	ds_read_b128 v[160:163], v243 offset:53248
	ds_read_b128 v[164:167], v243 offset:54272
	ds_read_b128 v[168:171], v243 offset:55296
	ds_read_b128 v[176:179], v243 offset:56320
	global_load_lds_dwordx4 v[208:209], off
	v_lshl_add_u64 v[208:209], v[214:215], 0, s[38:39]
	s_mov_b32 m0, s1
	s_nop 0
	global_load_lds_dwordx4 v[208:209], off
	s_barrier
; #define PG8_STAGE(bufoff, gbase, voff) do { _Pragma("unroll") for (int _i = 0; _i < 2; ++_i) \
;         __builtin_amdgcn_global_load_lds((const unsigned*)((const char*)(gbase) + (voff)[_i]), (PG8_LAS unsigned*)(lds + (bufoff) + ldsw + _i * 8192), 16, 0, 0); } while (0)
; #define PG8_LDA(dst, b, h) do { _Pragma("unroll") for (int m = 0; m < 4; ++m) _Pragma("unroll") for (int k = 0; k < 2; ++k) dst[m][k] = *(const PG8_LAS bf16x8*)(lds + PG8_SA(b, h) + aoff + m * 2048 + k * 1024); } while (0)
; #define PG8_WAIT_V(n) asm volatile("s_waitcnt vmcnt(" #n ")" ::: "memory")
; #define PG8_WAIT_L(n) asm volatile("s_waitcnt lgkmcnt(" #n ")" ::: "memory")
; #define PG8_BAR __builtin_amdgcn_s_barrier()
; template <class Epi, class Sched>
; __device__ __forceinline__ void gemm_phase(PG8_LAS unsigned char* lds, const Gemm g, const Sched& S, const Epi& E) {
;     ...
;             PG8_LDA(At, 1, 1); PG8_STAGE(PG8_SA(1, 0), a3, voffA);
;             PG8_BAR; PG8_WAIT_L(0); PG8_MMA(1, 0, At, B0); PG8_BAR; PG8_SCHED;
;             PG8_STAGE(PG8_SB(1, 1), b3 + hstep, voffB);
;             PG8_WAIT_V(6); PG8_BAR; PG8_MMA(1, 1, At, B1); PG8_BAR;
;         }
;     __device__ __forceinline__ void operator()(const f32x4 (&acc)[2][2][4][2], const pg8::Unit& u, int wr, int wc, int fr_, int fq_) const {
;     ...
;         const int row0 = u.pm * 256 + wr * 64 + fr, col0 = u.pn * 256 + wc * 32 + 8 * fq;
;         const bool ln = (Rraw == nullptr);
;         bf16_t* Z = (bf16_t*)(ws + OFF_X);
;         const float* st = (const float*)(ws + OFF_STATS); const float* gb = (const float*)(ws + OFF_GB);
;         if (ln) {
; #pragma unroll
;             for (int bj = 0; bj < 2; ++bj) {
;                 f32x4 gv[2], bv[2];
; #pragma unroll
;                 for (int n = 0; n < 2; ++n) { gv[n] = *(const f32x4*)(gb + col0 + bj * 128 + 4 * n); bv[n] = *(const f32x4*)(gb + DM + col0 + bj * 128 + 4 * n); }
;                 u32x4 r[2][4]; float mu[2][4], rs[2][4];
; #pragma unroll
;                 for (int ai = 0; ai < 2; ++ai)
; #pragma unroll
;                     for (int m = 0; m < 4; ++m) { const int row = row0 + ai * 128 + m * 16; const unsigned off = (unsigned)row * DM + (unsigned)(col0 + bj * 128);
;                         { const float2 ms = *(const float2*)(st + 2u * (unsigned)row); mu[ai][m] = ms.x; rs[ai][m] = ms.y; }
;                         r[ai][m] = *(const u32x4*)(Z + off); }
	s_waitcnt lgkmcnt(0)
	s_setprio 1
	s_waitcnt lgkmcnt(0)
	v_mfma_f32_16x16x32_bf16 v[92:95], v[128:131], v[144:147], v[92:95]
	v_mfma_f32_16x16x32_bf16 v[88:91], v[136:139], v[144:147], v[88:91]
	v_mfma_f32_16x16x32_bf16 v[84:87], v[128:131], v[152:155], v[84:87]
	v_mfma_f32_16x16x32_bf16 v[80:83], v[136:139], v[152:155], v[80:83]
	v_mfma_f32_16x16x32_bf16 v[76:79], v[128:131], v[160:163], v[76:79]
	v_mfma_f32_16x16x32_bf16 v[72:75], v[136:139], v[160:163], v[72:75]
	v_mfma_f32_16x16x32_bf16 v[68:71], v[128:131], v[168:171], v[68:71]
	v_mfma_f32_16x16x32_bf16 v[64:67], v[136:139], v[168:171], v[64:67]
	v_mfma_f32_16x16x32_bf16 v[92:95], v[132:135], v[148:151], v[92:95]
	v_mfma_f32_16x16x32_bf16 v[88:91], v[140:143], v[148:151], v[88:91]
	v_mfma_f32_16x16x32_bf16 v[84:87], v[132:135], v[156:159], v[84:87]
	v_mfma_f32_16x16x32_bf16 v[80:83], v[140:143], v[156:159], v[80:83]
	v_mfma_f32_16x16x32_bf16 v[76:79], v[132:135], v[164:167], v[76:79]
	v_mfma_f32_16x16x32_bf16 v[72:75], v[140:143], v[164:167], v[72:75]
	v_mfma_f32_16x16x32_bf16 v[68:71], v[132:135], v[176:179], v[68:71]
	v_mfma_f32_16x16x32_bf16 v[64:67], v[140:143], v[176:179], v[64:67]
	s_setprio 0
	s_barrier
	s_add_u32 s44, s44, 0x80080
	s_addc_u32 s45, s45, 0
	s_add_i32 s26, s27, s59
	v_lshl_add_u64 v[128:129], s[44:45], 0, v[184:185]
	s_mov_b32 m0, s26
	s_nop 0
	global_load_lds_dwordx4 v[128:129], off
	v_lshl_add_u64 v[128:129], s[44:45], 0, v[180:181]
	s_add_i32 m0, s26, 0x2000
	s_nop 0
	global_load_lds_dwordx4 v[128:129], off
	s_waitcnt vmcnt(6)
	s_barrier
	s_setprio 1
	v_mfma_f32_16x16x32_bf16 v[28:31], v[192:195], v[144:147], v[28:31]
	v_mfma_f32_16x16x32_bf16 v[24:27], v[200:203], v[144:147], v[24:27]
	v_mfma_f32_16x16x32_bf16 v[20:23], v[192:195], v[152:155], v[20:23]
	v_mfma_f32_16x16x32_bf16 v[16:19], v[200:203], v[152:155], v[16:19]
	v_mfma_f32_16x16x32_bf16 v[12:15], v[192:195], v[160:163], v[12:15]
	v_mfma_f32_16x16x32_bf16 v[8:11], v[200:203], v[160:163], v[8:11]
	v_mfma_f32_16x16x32_bf16 v[4:7], v[192:195], v[168:171], v[4:7]
	v_mfma_f32_16x16x32_bf16 v[0:3], v[200:203], v[168:171], v[0:3]
	v_mfma_f32_16x16x32_bf16 v[28:31], v[196:199], v[148:151], v[28:31]
	v_mfma_f32_16x16x32_bf16 v[24:27], v[204:207], v[148:151], v[24:27]
	v_mfma_f32_16x16x32_bf16 v[20:23], v[196:199], v[156:159], v[20:23]
	v_mfma_f32_16x16x32_bf16 v[16:19], v[204:207], v[156:159], v[16:19]
	v_mfma_f32_16x16x32_bf16 v[12:15], v[196:199], v[164:167], v[12:15]
	v_mfma_f32_16x16x32_bf16 v[8:11], v[204:207], v[164:167], v[8:11]
	v_mfma_f32_16x16x32_bf16 v[4:7], v[196:199], v[176:179], v[4:7]
	v_mfma_f32_16x16x32_bf16 v[0:3], v[204:207], v[176:179], v[0:3]
	s_setprio 0
	s_add_i32 s29, s29, 2
	s_add_u32 s52, s52, 0x100
	s_addc_u32 s53, s53, 0
	s_add_u32 s47, s47, 0x100
	s_addc_u32 s28, s28, 0
	s_cmp_gt_u32 s29, 29
	s_barrier
	s_cbranch_scc0 .LBB0_101
	s_lshl_b32 s8, s40, 8
	v_readlane_b32 s9, v255, 50
	v_mov_b32_e32 v128, v241
	v_mov_b32_e32 v129, v174
	s_add_i32 s8, s8, s9
	v_readlane_b32 s9, v255, 44
	v_add_u32_e32 v146, s8, v128
	s_lshl_b32 s8, s57, 8
	s_or_b32 s8, s8, s9
	v_lshl_add_u32 v194, v129, 3, s8
	v_ashrrev_i32_e32 v195, 31, v194
	v_readlane_b32 s8, v253, 29
	v_lshlrev_b64 v[128:129], 2, v[194:195]
	v_readlane_b32 s9, v253, 30
	v_lshlrev_b32_e32 v195, 11, v146
	v_add_u32_e32 v192, v195, v194
	v_lshl_add_u64 v[196:197], s[8:9], 0, v[128:129]
	v_readlane_b32 s8, v253, 31
	v_readlane_b32 s9, v253, 32
	v_mov_b32_e32 v193, v173
	v_readlane_b32 s26, v253, 24
	v_lshl_add_u64 v[198:199], s[8:9], 0, v[128:129]
	v_readlane_b32 s8, v253, 22
	v_readlane_b32 s9, v253, 23
	global_load_dwordx4 v[128:131], v[196:197], off offset:16
	global_load_dwordx4 v[136:139], v[196:197], off
	global_load_dwordx4 v[132:135], v[198:199], off offset:16
	global_load_dwordx4 v[140:143], v[198:199], off
	v_lshl_add_u64 v[232:233], v[192:193], 1, s[8:9]
	global_load_dwordx4 v[176:179], v[232:233], off
	v_lshlrev_b32_e32 v172, 1, v146
	v_readlane_b32 s27, v253, 25
	v_add_u32_e32 v145, 16, v146
	v_lshlrev_b32_e32 v193, 11, v145
	v_lshl_add_u64 v[200:201], v[172:173], 2, s[26:27]
	global_load_dwordx2 v[230:231], v[200:201], off
	v_add_u32_e32 v144, v193, v194
	v_lshlrev_b32_e32 v172, 1, v145
	v_mov_b32_e32 v145, v173
	v_lshl_add_u64 v[144:145], v[144:145], 1, s[8:9]
	global_load_dwordx4 v[168:171], v[144:145], off
	v_lshl_add_u64 v[202:203], v[172:173], 2, s[26:27]
	global_load_dwordx2 v[228:229], v[202:203], off
	v_add_u32_e32 v145, 32, v146
	v_lshlrev_b32_e32 v244, 11, v145
	v_add_u32_e32 v144, v244, v194
	v_lshlrev_b32_e32 v172, 1, v145
	v_mov_b32_e32 v145, v173
	v_lshl_add_u64 v[144:145], v[144:145], 1, s[8:9]
	global_load_dwordx4 v[164:167], v[144:145], off
	v_lshl_add_u64 v[204:205], v[172:173], 2, s[26:27]
	global_load_dwordx2 v[226:227], v[204:205], off
	v_add_u32_e32 v145, 48, v146
	v_lshlrev_b32_e32 v245, 11, v145
	v_add_u32_e32 v144, v245, v194
	v_lshlrev_b32_e32 v172, 1, v145
	v_mov_b32_e32 v145, v173
	v_lshl_add_u64 v[144:145], v[144:145], 1, s[8:9]
	global_load_dwordx4 v[160:163], v[144:145], off
	v_lshl_add_u64 v[206:207], v[172:173], 2, s[26:27]
	global_load_dwordx2 v[224:225], v[206:207], off
	v_add_u32_e32 v145, 0x80, v146
	v_lshlrev_b32_e32 v246, 11, v145
	v_add_u32_e32 v144, v246, v194
	v_lshlrev_b32_e32 v172, 1, v145
	v_mov_b32_e32 v145, v173
	v_lshl_add_u64 v[144:145], v[144:145], 1, s[8:9]
	global_load_dwordx4 v[156:159], v[144:145], off
	v_lshl_add_u64 v[208:209], v[172:173], 2, s[26:27]
	global_load_dwordx2 v[222:223], v[208:209], off
	v_add_u32_e32 v145, 0x90, v146
	v_lshlrev_b32_e32 v247, 11, v145
	v_add_u32_e32 v144, v247, v194
	v_lshlrev_b32_e32 v172, 1, v145
	v_mov_b32_e32 v145, v173
	v_lshl_add_u64 v[144:145], v[144:145], 1, s[8:9]
	global_load_dwordx4 v[152:155], v[144:145], off
	v_lshl_add_u64 v[210:211], v[172:173], 2, s[26:27]
	global_load_dwordx2 v[220:221], v[210:211], off
	v_add_u32_e32 v145, 0xa0, v146
	v_lshlrev_b32_e32 v248, 11, v145
	v_add_u32_e32 v144, v248, v194
	v_lshlrev_b32_e32 v172, 1, v145
	v_mov_b32_e32 v145, v173
	v_lshl_add_u64 v[144:145], v[144:145], 1, s[8:9]
	global_load_dwordx4 v[148:151], v[144:145], off
	v_lshl_add_u64 v[214:215], v[172:173], 2, s[26:27]
	global_load_dwordx2 v[218:219], v[214:215], off
	v_add_u32_e32 v145, 0xb0, v146
	v_lshlrev_b32_e32 v249, 11, v145
	v_add_u32_e32 v144, v249, v194
	v_lshlrev_b32_e32 v172, 1, v145
	v_mov_b32_e32 v145, v173
	v_lshl_add_u64 v[212:213], v[172:173], 2, s[26:27]
	v_lshl_add_u64 v[144:145], v[144:145], 1, s[8:9]
	global_load_dwordx2 v[216:217], v[212:213], off
	s_mov_b32 s57, s42
	global_load_dwordx4 v[144:147], v[144:145], off
	s_mov_b32 s40, s46
	s_mov_b64 s[44:45], s[50:51]
	s_mov_b64 s[52:53], s[48:49]
	s_waitcnt vmcnt(0)
; __device__ __forceinline__ u32x2 pack4h(f32x4 v) { const h16x4 h = __builtin_convertvector(v, h16x4); return __builtin_bit_cast(u32x2, h); }
; __device__ __forceinline__ f32x4 unpack4h(u32x2 w) { return __builtin_convertvector(__builtin_bit_cast(h16x4, w), f32x4); }
;     __device__ __forceinline__ void operator()(const f32x4 (&acc)[2][2][4][2], const pg8::Unit& u, int wr, int wc, int fr_, int fq_) const {
;     ...
; #pragma unroll
;                 for (int ai = 0; ai < 2; ++ai)
; #pragma unroll
;                     for (int m = 0; m < 4; ++m) { const unsigned off = (unsigned)(row0 + ai * 128 + m * 16) * DM + (unsigned)(col0 + bj * 128);
;                         u32x2 lo, hi; lo.x = r[ai][m].x; lo.y = r[ai][m].y; hi.x = r[ai][m].z; hi.y = r[ai][m].w;
;                         const f32x4 x0 = (unpack4h(lo) - mu[ai][m]) * rs[ai][m] * gv[0] + bv[0], x1 = (unpack4h(hi) - mu[ai][m]) * rs[ai][m] * gv[1] + bv[1];
;                         const u32x2 o0 = pack4h(x0 * ALPHA + acc[ai][bj][m][0] * s), o1 = pack4h(x1 * ALPHA + acc[ai][bj][m][1] * s);
;                         u32x4 w; w.x = o0.x; w.y = o0.y; w.z = o1.x; w.w = o1.y; *(u32x4*)(Z + off) = w; }
	v_cvt_f32_f16_sdwa v172, v176 dst_sel:DWORD dst_unused:UNUSED_PAD src0_sel:WORD_1
	v_cvt_f32_f16_sdwa v237, v177 dst_sel:DWORD dst_unused:UNUSED_PAD src0_sel:WORD_1
	v_cvt_f32_f16_e32 v236, v176
	v_cvt_f32_f16_e32 v176, v177
	v_cvt_f32_f16_e32 v240, v178
	v_cvt_f32_f16_sdwa v250, v179 dst_sel:DWORD dst_unused:UNUSED_PAD src0_sel:WORD_1
	v_sub_f32_e32 v177, v237, v230
	v_sub_f32_e32 v237, v172, v230
	v_cvt_f32_f16_sdwa v172, v178 dst_sel:DWORD dst_unused:UNUSED_PAD src0_sel:WORD_1
	v_cvt_f32_f16_e32 v178, v179
	v_sub_f32_e32 v176, v176, v230
	v_sub_f32_e32 v236, v236, v230
	v_sub_f32_e32 v179, v250, v230
	v_sub_f32_e32 v178, v178, v230
	v_sub_f32_e32 v250, v240, v230
	v_sub_f32_e32 v251, v172, v230
	v_pk_mul_f32 v[236:237], v[230:231], v[236:237] op_sel:[1,0]
	v_pk_mul_f32 v[176:177], v[230:231], v[176:177] op_sel:[1,0]
	v_pk_mul_f32 v[250:251], v[230:231], v[250:251] op_sel:[1,0]
	v_pk_mul_f32 v[178:179], v[230:231], v[178:179] op_sel:[1,0]
	v_pk_fma_f32 v[176:177], v[138:139], v[176:177], v[142:143]
	v_pk_fma_f32 v[236:237], v[136:137], v[236:237], v[140:141]
	v_pk_fma_f32 v[178:179], v[130:131], v[178:179], v[134:135]
	v_pk_fma_f32 v[230:231], v[128:129], v[250:251], v[132:133]
	v_pk_fma_f32 v[126:127], v[176:177], s[36:37], v[126:127] op_sel_hi:[1,0,1]
	v_pk_fma_f32 v[176:177], v[236:237], s[36:37], v[124:125] op_sel_hi:[1,0,1]
	v_pk_fma_f32 v[122:123], v[178:179], s[36:37], v[122:123] op_sel_hi:[1,0,1]
	v_pk_fma_f32 v[120:121], v[230:231], s[36:37], v[120:121] op_sel_hi:[1,0,1]
	v_cvt_pk_f16_f32 v125, v126, v127
	v_cvt_pk_f16_f32 v124, v176, v177
	v_cvt_pk_f16_f32 v127, v122, v123
	v_cvt_pk_f16_f32 v126, v120, v121
	global_store_dwordx4 v[232:233], v[124:127], off sc1
	v_cvt_f32_f16_sdwa v123, v168 dst_sel:DWORD dst_unused:UNUSED_PAD src0_sel:WORD_1
	v_cvt_f32_f16_e32 v122, v168
	v_cvt_f32_f16_sdwa v121, v169 dst_sel:DWORD dst_unused:UNUSED_PAD src0_sel:WORD_1
	v_cvt_f32_f16_e32 v120, v169
	v_cvt_f32_f16_sdwa v127, v170 dst_sel:DWORD dst_unused:UNUSED_PAD src0_sel:WORD_1
	v_cvt_f32_f16_e32 v126, v170
	v_cvt_f32_f16_sdwa v125, v171 dst_sel:DWORD dst_unused:UNUSED_PAD src0_sel:WORD_1
	v_cvt_f32_f16_e32 v124, v171
	v_sub_f32_e32 v120, v120, v228
	v_sub_f32_e32 v121, v121, v228
	v_sub_f32_e32 v122, v122, v228
	v_sub_f32_e32 v123, v123, v228
	v_sub_f32_e32 v124, v124, v228
	v_sub_f32_e32 v125, v125, v228
	v_sub_f32_e32 v126, v126, v228
	v_sub_f32_e32 v127, v127, v228
	v_pk_mul_f32 v[122:123], v[228:229], v[122:123] op_sel:[1,0]
	v_pk_mul_f32 v[120:121], v[228:229], v[120:121] op_sel:[1,0]
	v_pk_mul_f32 v[126:127], v[228:229], v[126:127] op_sel:[1,0]
	v_pk_mul_f32 v[124:125], v[228:229], v[124:125] op_sel:[1,0]
	v_pk_fma_f32 v[120:121], v[138:139], v[120:121], v[142:143]
	v_pk_fma_f32 v[122:123], v[136:137], v[122:123], v[140:141]
	v_pk_fma_f32 v[124:125], v[130:131], v[124:125], v[134:135]
	v_pk_fma_f32 v[126:127], v[128:129], v[126:127], v[132:133]
	v_add_u32_e32 v172, 0x8000, v192
	v_pk_fma_f32 v[118:119], v[120:121], s[36:37], v[118:119] op_sel_hi:[1,0,1]
	v_pk_fma_f32 v[120:121], v[122:123], s[36:37], v[116:117] op_sel_hi:[1,0,1]
	v_pk_fma_f32 v[114:115], v[124:125], s[36:37], v[114:115] op_sel_hi:[1,0,1]
	v_pk_fma_f32 v[112:113], v[126:127], s[36:37], v[112:113] op_sel_hi:[1,0,1]
	v_cvt_pk_f16_f32 v117, v118, v119
	v_cvt_pk_f16_f32 v116, v120, v121
	v_cvt_pk_f16_f32 v119, v114, v115
	v_cvt_pk_f16_f32 v118, v112, v113
	v_lshl_add_u64 v[112:113], v[172:173], 1, s[8:9]
	global_store_dwordx4 v[112:113], v[116:119], off sc1
	v_cvt_f32_f16_sdwa v115, v164 dst_sel:DWORD dst_unused:UNUSED_PAD src0_sel:WORD_1
	v_cvt_f32_f16_e32 v114, v164
	v_cvt_f32_f16_sdwa v113, v165 dst_sel:DWORD dst_unused:UNUSED_PAD src0_sel:WORD_1
	v_cvt_f32_f16_e32 v112, v165
	v_cvt_f32_f16_sdwa v119, v166 dst_sel:DWORD dst_unused:UNUSED_PAD src0_sel:WORD_1
	v_cvt_f32_f16_e32 v118, v166
	v_cvt_f32_f16_sdwa v117, v167 dst_sel:DWORD dst_unused:UNUSED_PAD src0_sel:WORD_1
	v_cvt_f32_f16_e32 v116, v167
	v_sub_f32_e32 v112, v112, v226
	v_sub_f32_e32 v113, v113, v226
	v_sub_f32_e32 v114, v114, v226
	v_sub_f32_e32 v115, v115, v226
	v_sub_f32_e32 v116, v116, v226
	v_sub_f32_e32 v117, v117, v226
	v_sub_f32_e32 v118, v118, v226
	v_sub_f32_e32 v119, v119, v226
	v_pk_mul_f32 v[114:115], v[226:227], v[114:115] op_sel:[1,0]
	v_pk_mul_f32 v[112:113], v[226:227], v[112:113] op_sel:[1,0]
	v_pk_mul_f32 v[118:119], v[226:227], v[118:119] op_sel:[1,0]
	v_pk_mul_f32 v[116:117], v[226:227], v[116:117] op_sel:[1,0]
	v_pk_fma_f32 v[112:113], v[138:139], v[112:113], v[142:143]
	v_pk_fma_f32 v[114:115], v[136:137], v[114:115], v[140:141]
	v_pk_fma_f32 v[116:117], v[130:131], v[116:117], v[134:135]
	v_pk_fma_f32 v[118:119], v[128:129], v[118:119], v[132:133]
	v_add_u32_e32 v172, 0x10000, v192
	v_pk_fma_f32 v[110:111], v[112:113], s[36:37], v[110:111] op_sel_hi:[1,0,1]
	v_pk_fma_f32 v[112:113], v[114:115], s[36:37], v[108:109] op_sel_hi:[1,0,1]
	v_pk_fma_f32 v[106:107], v[116:117], s[36:37], v[106:107] op_sel_hi:[1,0,1]
	v_pk_fma_f32 v[104:105], v[118:119], s[36:37], v[104:105] op_sel_hi:[1,0,1]
	v_cvt_pk_f16_f32 v109, v110, v111
	v_cvt_pk_f16_f32 v108, v112, v113
	v_cvt_pk_f16_f32 v111, v106, v107
	v_cvt_pk_f16_f32 v110, v104, v105
	v_lshl_add_u64 v[104:105], v[172:173], 1, s[8:9]
	global_store_dwordx4 v[104:105], v[108:111], off sc1
	v_cvt_f32_f16_sdwa v107, v160 dst_sel:DWORD dst_unused:UNUSED_PAD src0_sel:WORD_1
	v_cvt_f32_f16_e32 v106, v160
	v_cvt_f32_f16_sdwa v105, v161 dst_sel:DWORD dst_unused:UNUSED_PAD src0_sel:WORD_1
	v_cvt_f32_f16_e32 v104, v161
	v_cvt_f32_f16_sdwa v111, v162 dst_sel:DWORD dst_unused:UNUSED_PAD src0_sel:WORD_1
	v_cvt_f32_f16_e32 v110, v162
; __device__ __forceinline__ u32x2 pack4h(f32x4 v) { const h16x4 h = __builtin_convertvector(v, h16x4); return __builtin_bit_cast(u32x2, h); }
; __device__ __forceinline__ f32x4 unpack4h(u32x2 w) { return __builtin_convertvector(__builtin_bit_cast(h16x4, w), f32x4); }
;     __device__ __forceinline__ void operator()(const f32x4 (&acc)[2][2][4][2], const pg8::Unit& u, int wr, int wc, int fr_, int fq_) const {
;     ...
; #pragma unroll
;                 for (int ai = 0; ai < 2; ++ai)
; #pragma unroll
;                     for (int m = 0; m < 4; ++m) { const unsigned off = (unsigned)(row0 + ai * 128 + m * 16) * DM + (unsigned)(col0 + bj * 128);
;                         u32x2 lo, hi; lo.x = r[ai][m].x; lo.y = r[ai][m].y; hi.x = r[ai][m].z; hi.y = r[ai][m].w;
;                         const f32x4 x0 = (unpack4h(lo) - mu[ai][m]) * rs[ai][m] * gv[0] + bv[0], x1 = (unpack4h(hi) - mu[ai][m]) * rs[ai][m] * gv[1] + bv[1];
;                         const u32x2 o0 = pack4h(x0 * ALPHA + acc[ai][bj][m][0] * s), o1 = pack4h(x1 * ALPHA + acc[ai][bj][m][1] * s);
;                         u32x4 w; w.x = o0.x; w.y = o0.y; w.z = o1.x; w.w = o1.y; *(u32x4*)(Z + off) = w; }
	v_cvt_f32_f16_sdwa v109, v163 dst_sel:DWORD dst_unused:UNUSED_PAD src0_sel:WORD_1
	v_cvt_f32_f16_e32 v108, v163
	v_sub_f32_e32 v104, v104, v224
	v_sub_f32_e32 v105, v105, v224
	v_sub_f32_e32 v106, v106, v224
	v_sub_f32_e32 v107, v107, v224
	v_sub_f32_e32 v108, v108, v224
	v_sub_f32_e32 v109, v109, v224
	v_sub_f32_e32 v110, v110, v224
	v_sub_f32_e32 v111, v111, v224
	v_pk_mul_f32 v[106:107], v[224:225], v[106:107] op_sel:[1,0]
	v_pk_mul_f32 v[104:105], v[224:225], v[104:105] op_sel:[1,0]
	v_pk_mul_f32 v[110:111], v[224:225], v[110:111] op_sel:[1,0]
	v_pk_mul_f32 v[108:109], v[224:225], v[108:109] op_sel:[1,0]
	v_pk_fma_f32 v[104:105], v[138:139], v[104:105], v[142:143]
	v_pk_fma_f32 v[106:107], v[136:137], v[106:107], v[140:141]
	v_pk_fma_f32 v[108:109], v[130:131], v[108:109], v[134:135]
	v_pk_fma_f32 v[110:111], v[128:129], v[110:111], v[132:133]
	v_add_u32_e32 v172, 0x18000, v192
	v_pk_fma_f32 v[102:103], v[104:105], s[36:37], v[102:103] op_sel_hi:[1,0,1]
	v_pk_fma_f32 v[104:105], v[106:107], s[36:37], v[100:101] op_sel_hi:[1,0,1]
	v_pk_fma_f32 v[98:99], v[108:109], s[36:37], v[98:99] op_sel_hi:[1,0,1]
	v_pk_fma_f32 v[96:97], v[110:111], s[36:37], v[96:97] op_sel_hi:[1,0,1]
	v_cvt_pk_f16_f32 v101, v102, v103
	v_cvt_pk_f16_f32 v100, v104, v105
	v_cvt_pk_f16_f32 v103, v98, v99
	v_cvt_pk_f16_f32 v102, v96, v97
	v_lshl_add_u64 v[96:97], v[172:173], 1, s[8:9]
	global_store_dwordx4 v[96:97], v[100:103], off sc1
	v_cvt_f32_f16_sdwa v99, v156 dst_sel:DWORD dst_unused:UNUSED_PAD src0_sel:WORD_1
	v_cvt_f32_f16_e32 v98, v156
	v_cvt_f32_f16_sdwa v97, v157 dst_sel:DWORD dst_unused:UNUSED_PAD src0_sel:WORD_1
	v_cvt_f32_f16_e32 v96, v157
	v_cvt_f32_f16_sdwa v103, v158 dst_sel:DWORD dst_unused:UNUSED_PAD src0_sel:WORD_1
	v_cvt_f32_f16_e32 v102, v158
	v_cvt_f32_f16_sdwa v101, v159 dst_sel:DWORD dst_unused:UNUSED_PAD src0_sel:WORD_1
	v_cvt_f32_f16_e32 v100, v159
	v_sub_f32_e32 v96, v96, v222
	v_sub_f32_e32 v97, v97, v222
	v_sub_f32_e32 v98, v98, v222
	v_sub_f32_e32 v99, v99, v222
	v_sub_f32_e32 v100, v100, v222
	v_sub_f32_e32 v101, v101, v222
	v_sub_f32_e32 v102, v102, v222
	v_sub_f32_e32 v103, v103, v222
	v_pk_mul_f32 v[98:99], v[222:223], v[98:99] op_sel:[1,0]
	v_pk_mul_f32 v[96:97], v[222:223], v[96:97] op_sel:[1,0]
	v_pk_mul_f32 v[102:103], v[222:223], v[102:103] op_sel:[1,0]
	v_pk_mul_f32 v[100:101], v[222:223], v[100:101] op_sel:[1,0]
	v_pk_fma_f32 v[96:97], v[138:139], v[96:97], v[142:143]
	v_pk_fma_f32 v[98:99], v[136:137], v[98:99], v[140:141]
	v_pk_fma_f32 v[100:101], v[130:131], v[100:101], v[134:135]
	v_pk_fma_f32 v[102:103], v[128:129], v[102:103], v[132:133]
	v_add_u32_e32 v172, 0x40000, v192
	v_pk_fma_f32 v[94:95], v[96:97], s[36:37], v[94:95] op_sel_hi:[1,0,1]
	v_pk_fma_f32 v[96:97], v[98:99], s[36:37], v[92:93] op_sel_hi:[1,0,1]
	v_pk_fma_f32 v[90:91], v[100:101], s[36:37], v[90:91] op_sel_hi:[1,0,1]
	v_pk_fma_f32 v[88:89], v[102:103], s[36:37], v[88:89] op_sel_hi:[1,0,1]
	v_cvt_pk_f16_f32 v93, v94, v95
	v_cvt_pk_f16_f32 v92, v96, v97
	v_cvt_pk_f16_f32 v95, v90, v91
	v_cvt_pk_f16_f32 v94, v88, v89
	v_lshl_add_u64 v[88:89], v[172:173], 1, s[8:9]
	global_store_dwordx4 v[88:89], v[92:95], off sc1
	v_cvt_f32_f16_sdwa v91, v152 dst_sel:DWORD dst_unused:UNUSED_PAD src0_sel:WORD_1
	v_cvt_f32_f16_e32 v90, v152
	v_cvt_f32_f16_sdwa v89, v153 dst_sel:DWORD dst_unused:UNUSED_PAD src0_sel:WORD_1
	v_cvt_f32_f16_e32 v88, v153
	v_cvt_f32_f16_sdwa v95, v154 dst_sel:DWORD dst_unused:UNUSED_PAD src0_sel:WORD_1
	v_cvt_f32_f16_e32 v94, v154
	v_cvt_f32_f16_sdwa v93, v155 dst_sel:DWORD dst_unused:UNUSED_PAD src0_sel:WORD_1
	v_cvt_f32_f16_e32 v92, v155
	v_sub_f32_e32 v88, v88, v220
	v_sub_f32_e32 v89, v89, v220
	v_sub_f32_e32 v90, v90, v220
	v_sub_f32_e32 v91, v91, v220
	v_sub_f32_e32 v92, v92, v220
	v_sub_f32_e32 v93, v93, v220
	v_sub_f32_e32 v94, v94, v220
	v_sub_f32_e32 v95, v95, v220
	v_pk_mul_f32 v[90:91], v[220:221], v[90:91] op_sel:[1,0]
	v_pk_mul_f32 v[88:89], v[220:221], v[88:89] op_sel:[1,0]
	v_pk_mul_f32 v[94:95], v[220:221], v[94:95] op_sel:[1,0]
	v_pk_mul_f32 v[92:93], v[220:221], v[92:93] op_sel:[1,0]
	v_pk_fma_f32 v[88:89], v[138:139], v[88:89], v[142:143]
	v_pk_fma_f32 v[90:91], v[136:137], v[90:91], v[140:141]
	v_pk_fma_f32 v[92:93], v[130:131], v[92:93], v[134:135]
	v_pk_fma_f32 v[94:95], v[128:129], v[94:95], v[132:133]
	v_add_u32_e32 v172, 0x48000, v192
	v_pk_fma_f32 v[86:87], v[88:89], s[36:37], v[86:87] op_sel_hi:[1,0,1]
	v_pk_fma_f32 v[88:89], v[90:91], s[36:37], v[84:85] op_sel_hi:[1,0,1]
	v_pk_fma_f32 v[82:83], v[92:93], s[36:37], v[82:83] op_sel_hi:[1,0,1]
	v_pk_fma_f32 v[80:81], v[94:95], s[36:37], v[80:81] op_sel_hi:[1,0,1]
	v_cvt_pk_f16_f32 v85, v86, v87
	v_cvt_pk_f16_f32 v84, v88, v89
	v_cvt_pk_f16_f32 v87, v82, v83
	v_cvt_pk_f16_f32 v86, v80, v81
	v_lshl_add_u64 v[80:81], v[172:173], 1, s[8:9]
	global_store_dwordx4 v[80:81], v[84:87], off sc1
	v_cvt_f32_f16_sdwa v83, v148 dst_sel:DWORD dst_unused:UNUSED_PAD src0_sel:WORD_1
	v_cvt_f32_f16_e32 v82, v148
	v_cvt_f32_f16_sdwa v81, v149 dst_sel:DWORD dst_unused:UNUSED_PAD src0_sel:WORD_1
	v_cvt_f32_f16_e32 v80, v149
	v_cvt_f32_f16_sdwa v87, v150 dst_sel:DWORD dst_unused:UNUSED_PAD src0_sel:WORD_1
	v_cvt_f32_f16_e32 v86, v150
	v_cvt_f32_f16_sdwa v85, v151 dst_sel:DWORD dst_unused:UNUSED_PAD src0_sel:WORD_1
	v_cvt_f32_f16_e32 v84, v151
	v_sub_f32_e32 v80, v80, v218
	v_sub_f32_e32 v81, v81, v218
	v_sub_f32_e32 v82, v82, v218
	v_sub_f32_e32 v83, v83, v218
	v_sub_f32_e32 v84, v84, v218
	v_sub_f32_e32 v85, v85, v218
	v_sub_f32_e32 v86, v86, v218
	v_sub_f32_e32 v87, v87, v218
	v_pk_mul_f32 v[82:83], v[218:219], v[82:83] op_sel:[1,0]
	v_pk_mul_f32 v[80:81], v[218:219], v[80:81] op_sel:[1,0]
; __device__ __forceinline__ u32x2 pack4h(f32x4 v) { const h16x4 h = __builtin_convertvector(v, h16x4); return __builtin_bit_cast(u32x2, h); }
; __device__ __forceinline__ f32x4 unpack4h(u32x2 w) { return __builtin_convertvector(__builtin_bit_cast(h16x4, w), f32x4); }
;     __device__ __forceinline__ void operator()(const f32x4 (&acc)[2][2][4][2], const pg8::Unit& u, int wr, int wc, int fr_, int fq_) const {
;     ...
;             for (int bj = 0; bj < 2; ++bj) {
;                 f32x4 gv[2], bv[2];
; #pragma unroll
;                 for (int n = 0; n < 2; ++n) { gv[n] = *(const f32x4*)(gb + col0 + bj * 128 + 4 * n); bv[n] = *(const f32x4*)(gb + DM + col0 + bj * 128 + 4 * n); }
;                 u32x4 r[2][4]; float mu[2][4], rs[2][4];
; #pragma unroll
;                 for (int ai = 0; ai < 2; ++ai)
; #pragma unroll
;                     for (int m = 0; m < 4; ++m) { const int row = row0 + ai * 128 + m * 16; const unsigned off = (unsigned)row * DM + (unsigned)(col0 + bj * 128);
;                         { const float2 ms = *(const float2*)(st + 2u * (unsigned)row); mu[ai][m] = ms.x; rs[ai][m] = ms.y; }
;                         r[ai][m] = *(const u32x4*)(Z + off); }
;                 asm volatile("" ::: "memory");
; #pragma unroll
;                 for (int ai = 0; ai < 2; ++ai)
; #pragma unroll
;                     for (int m = 0; m < 4; ++m) { const unsigned off = (unsigned)(row0 + ai * 128 + m * 16) * DM + (unsigned)(col0 + bj * 128);
;                         u32x2 lo, hi; lo.x = r[ai][m].x; lo.y = r[ai][m].y; hi.x = r[ai][m].z; hi.y = r[ai][m].w;
;                         const f32x4 x0 = (unpack4h(lo) - mu[ai][m]) * rs[ai][m] * gv[0] + bv[0], x1 = (unpack4h(hi) - mu[ai][m]) * rs[ai][m] * gv[1] + bv[1];
;                         const u32x2 o0 = pack4h(x0 * ALPHA + acc[ai][bj][m][0] * s), o1 = pack4h(x1 * ALPHA + acc[ai][bj][m][1] * s);
;                         u32x4 w; w.x = o0.x; w.y = o0.y; w.z = o1.x; w.w = o1.y; *(u32x4*)(Z + off) = w; }
	v_pk_mul_f32 v[86:87], v[218:219], v[86:87] op_sel:[1,0]
	v_pk_mul_f32 v[84:85], v[218:219], v[84:85] op_sel:[1,0]
	v_pk_fma_f32 v[80:81], v[138:139], v[80:81], v[142:143]
	v_pk_fma_f32 v[82:83], v[136:137], v[82:83], v[140:141]
	v_pk_fma_f32 v[84:85], v[130:131], v[84:85], v[134:135]
	v_pk_fma_f32 v[86:87], v[128:129], v[86:87], v[132:133]
	v_add_u32_e32 v172, 0x50000, v192
	v_pk_fma_f32 v[78:79], v[80:81], s[36:37], v[78:79] op_sel_hi:[1,0,1]
	v_pk_fma_f32 v[80:81], v[82:83], s[36:37], v[76:77] op_sel_hi:[1,0,1]
	v_pk_fma_f32 v[74:75], v[84:85], s[36:37], v[74:75] op_sel_hi:[1,0,1]
	v_pk_fma_f32 v[72:73], v[86:87], s[36:37], v[72:73] op_sel_hi:[1,0,1]
	v_cvt_pk_f16_f32 v77, v78, v79
	v_cvt_pk_f16_f32 v76, v80, v81
	v_cvt_pk_f16_f32 v79, v74, v75
	v_cvt_pk_f16_f32 v78, v72, v73
	v_lshl_add_u64 v[72:73], v[172:173], 1, s[8:9]
	global_store_dwordx4 v[72:73], v[76:79], off sc1
	v_cvt_f32_f16_sdwa v75, v144 dst_sel:DWORD dst_unused:UNUSED_PAD src0_sel:WORD_1
	v_cvt_f32_f16_e32 v74, v144
	v_cvt_f32_f16_sdwa v73, v145 dst_sel:DWORD dst_unused:UNUSED_PAD src0_sel:WORD_1
	v_cvt_f32_f16_e32 v72, v145
	v_cvt_f32_f16_sdwa v79, v146 dst_sel:DWORD dst_unused:UNUSED_PAD src0_sel:WORD_1
	v_cvt_f32_f16_e32 v78, v146
	v_cvt_f32_f16_sdwa v77, v147 dst_sel:DWORD dst_unused:UNUSED_PAD src0_sel:WORD_1
	v_cvt_f32_f16_e32 v76, v147
	v_sub_f32_e32 v72, v72, v216
	v_sub_f32_e32 v73, v73, v216
	v_sub_f32_e32 v74, v74, v216
	v_sub_f32_e32 v75, v75, v216
	v_sub_f32_e32 v76, v76, v216
	v_sub_f32_e32 v77, v77, v216
	v_sub_f32_e32 v78, v78, v216
	v_sub_f32_e32 v79, v79, v216
	v_pk_mul_f32 v[74:75], v[216:217], v[74:75] op_sel:[1,0]
	v_pk_mul_f32 v[72:73], v[216:217], v[72:73] op_sel:[1,0]
	v_pk_mul_f32 v[78:79], v[216:217], v[78:79] op_sel:[1,0]
	v_pk_mul_f32 v[76:77], v[216:217], v[76:77] op_sel:[1,0]
	v_pk_fma_f32 v[72:73], v[138:139], v[72:73], v[142:143]
	v_pk_fma_f32 v[74:75], v[136:137], v[74:75], v[140:141]
	v_pk_fma_f32 v[76:77], v[130:131], v[76:77], v[134:135]
	v_pk_fma_f32 v[78:79], v[128:129], v[78:79], v[132:133]
	v_add_u32_e32 v172, 0x58000, v192
	v_pk_fma_f32 v[70:71], v[72:73], s[36:37], v[70:71] op_sel_hi:[1,0,1]
	v_pk_fma_f32 v[72:73], v[74:75], s[36:37], v[68:69] op_sel_hi:[1,0,1]
	v_pk_fma_f32 v[66:67], v[76:77], s[36:37], v[66:67] op_sel_hi:[1,0,1]
	v_pk_fma_f32 v[64:65], v[78:79], s[36:37], v[64:65] op_sel_hi:[1,0,1]
	v_add_u32_e32 v82, 0x80, v194
	v_cvt_pk_f16_f32 v69, v70, v71
	v_cvt_pk_f16_f32 v68, v72, v73
	v_cvt_pk_f16_f32 v71, v66, v67
	v_cvt_pk_f16_f32 v70, v64, v65
	v_lshl_add_u64 v[64:65], v[172:173], 1, s[8:9]
	v_add_u32_e32 v172, v82, v195
	global_store_dwordx4 v[64:65], v[68:71], off sc1
	v_lshl_add_u64 v[80:81], v[172:173], 1, s[8:9]
	global_load_dwordx4 v[64:67], v[196:197], off offset:528
	global_load_dwordx4 v[72:75], v[196:197], off offset:512
	global_load_dwordx4 v[68:71], v[198:199], off offset:528
	global_load_dwordx4 v[76:79], v[198:199], off offset:512
	global_load_dwordx2 v[126:127], v[200:201], off
	global_load_dwordx4 v[118:121], v[80:81], off
	v_add_u32_e32 v172, v82, v193
	v_lshl_add_u64 v[80:81], v[172:173], 1, s[8:9]
	global_load_dwordx2 v[116:117], v[202:203], off
	global_load_dwordx4 v[122:125], v[80:81], off
	v_add_u32_e32 v172, v82, v244
	v_lshl_add_u64 v[80:81], v[172:173], 1, s[8:9]
	global_load_dwordx2 v[114:115], v[204:205], off
	global_load_dwordx4 v[100:103], v[80:81], off
	v_add_u32_e32 v172, v82, v245
	v_lshl_add_u64 v[80:81], v[172:173], 1, s[8:9]
	global_load_dwordx2 v[112:113], v[206:207], off
	global_load_dwordx4 v[96:99], v[80:81], off
	v_add_u32_e32 v172, v82, v246
	v_lshl_add_u64 v[80:81], v[172:173], 1, s[8:9]
	global_load_dwordx2 v[110:111], v[208:209], off
	global_load_dwordx4 v[92:95], v[80:81], off
	v_add_u32_e32 v172, v82, v247
	v_lshl_add_u64 v[80:81], v[172:173], 1, s[8:9]
	global_load_dwordx2 v[108:109], v[210:211], off
	global_load_dwordx4 v[88:91], v[80:81], off
	v_add_u32_e32 v172, v82, v248
	v_lshl_add_u64 v[80:81], v[172:173], 1, s[8:9]
	global_load_dwordx4 v[84:87], v[80:81], off
	global_load_dwordx2 v[104:105], v[212:213], off
	global_load_dwordx2 v[106:107], v[214:215], off
	v_add_u32_e32 v172, v82, v249
	v_lshl_add_u64 v[80:81], v[172:173], 1, s[8:9]
	global_load_dwordx4 v[80:83], v[80:81], off
	v_add_u32_e32 v172, 0x80, v192
	s_waitcnt vmcnt(0)
; __device__ __forceinline__ u32x2 pack4h(f32x4 v) { const h16x4 h = __builtin_convertvector(v, h16x4); return __builtin_bit_cast(u32x2, h); }
; __device__ __forceinline__ f32x4 unpack4h(u32x2 w) { return __builtin_convertvector(__builtin_bit_cast(h16x4, w), f32x4); }
;     __device__ __forceinline__ void operator()(const f32x4 (&acc)[2][2][4][2], const pg8::Unit& u, int wr, int wc, int fr_, int fq_) const {
;     ...
; #pragma unroll
;                 for (int ai = 0; ai < 2; ++ai)
; #pragma unroll
;                     for (int m = 0; m < 4; ++m) { const unsigned off = (unsigned)(row0 + ai * 128 + m * 16) * DM + (unsigned)(col0 + bj * 128);
;                         u32x2 lo, hi; lo.x = r[ai][m].x; lo.y = r[ai][m].y; hi.x = r[ai][m].z; hi.y = r[ai][m].w;
;                         const f32x4 x0 = (unpack4h(lo) - mu[ai][m]) * rs[ai][m] * gv[0] + bv[0], x1 = (unpack4h(hi) - mu[ai][m]) * rs[ai][m] * gv[1] + bv[1];
;                         const u32x2 o0 = pack4h(x0 * ALPHA + acc[ai][bj][m][0] * s), o1 = pack4h(x1 * ALPHA + acc[ai][bj][m][1] * s);
;                         u32x4 w; w.x = o0.x; w.y = o0.y; w.z = o1.x; w.w = o1.y; *(u32x4*)(Z + off) = w; }
	v_cvt_f32_f16_sdwa v130, v119 dst_sel:DWORD dst_unused:UNUSED_PAD src0_sel:WORD_1
	v_cvt_f32_f16_sdwa v129, v118 dst_sel:DWORD dst_unused:UNUSED_PAD src0_sel:WORD_1
	v_cvt_f32_f16_e32 v128, v118
	v_cvt_f32_f16_e32 v118, v119
	v_sub_f32_e32 v119, v130, v126
	v_cvt_f32_f16_sdwa v131, v120 dst_sel:DWORD dst_unused:UNUSED_PAD src0_sel:WORD_1
	v_cvt_f32_f16_e32 v130, v120
	v_cvt_f32_f16_sdwa v132, v121 dst_sel:DWORD dst_unused:UNUSED_PAD src0_sel:WORD_1
	v_cvt_f32_f16_e32 v120, v121
	v_sub_f32_e32 v118, v118, v126
	v_sub_f32_e32 v128, v128, v126
	v_sub_f32_e32 v129, v129, v126
	v_sub_f32_e32 v120, v120, v126
	v_sub_f32_e32 v121, v132, v126
	v_sub_f32_e32 v130, v130, v126
	v_sub_f32_e32 v131, v131, v126
	v_pk_mul_f32 v[128:129], v[126:127], v[128:129] op_sel:[1,0]
	v_pk_mul_f32 v[118:119], v[126:127], v[118:119] op_sel:[1,0]
	v_pk_mul_f32 v[130:131], v[126:127], v[130:131] op_sel:[1,0]
	v_pk_mul_f32 v[120:121], v[126:127], v[120:121] op_sel:[1,0]
	v_pk_fma_f32 v[118:119], v[74:75], v[118:119], v[78:79]
	v_pk_fma_f32 v[128:129], v[72:73], v[128:129], v[76:77]
	v_pk_fma_f32 v[120:121], v[66:67], v[120:121], v[70:71]
	v_pk_fma_f32 v[126:127], v[64:65], v[130:131], v[68:69]
	v_pk_fma_f32 v[62:63], v[118:119], s[36:37], v[62:63] op_sel_hi:[1,0,1]
	v_pk_fma_f32 v[118:119], v[128:129], s[36:37], v[60:61] op_sel_hi:[1,0,1]
	v_pk_fma_f32 v[58:59], v[120:121], s[36:37], v[58:59] op_sel_hi:[1,0,1]
	v_pk_fma_f32 v[56:57], v[126:127], s[36:37], v[56:57] op_sel_hi:[1,0,1]
	v_cvt_pk_f16_f32 v61, v62, v63
	v_cvt_pk_f16_f32 v60, v118, v119
	v_cvt_pk_f16_f32 v63, v58, v59
	v_cvt_pk_f16_f32 v62, v56, v57
	v_lshl_add_u64 v[56:57], v[172:173], 1, s[8:9]
	global_store_dwordx4 v[56:57], v[60:63], off sc1
	v_cvt_f32_f16_sdwa v59, v122 dst_sel:DWORD dst_unused:UNUSED_PAD src0_sel:WORD_1
	v_cvt_f32_f16_e32 v58, v122
	v_cvt_f32_f16_sdwa v57, v123 dst_sel:DWORD dst_unused:UNUSED_PAD src0_sel:WORD_1
	v_cvt_f32_f16_e32 v56, v123
	v_cvt_f32_f16_sdwa v63, v124 dst_sel:DWORD dst_unused:UNUSED_PAD src0_sel:WORD_1
	v_cvt_f32_f16_e32 v62, v124
	v_cvt_f32_f16_sdwa v61, v125 dst_sel:DWORD dst_unused:UNUSED_PAD src0_sel:WORD_1
	v_cvt_f32_f16_e32 v60, v125
	v_sub_f32_e32 v56, v56, v116
	v_sub_f32_e32 v57, v57, v116
	v_sub_f32_e32 v58, v58, v116
	v_sub_f32_e32 v59, v59, v116
	v_sub_f32_e32 v60, v60, v116
	v_sub_f32_e32 v61, v61, v116
	v_sub_f32_e32 v62, v62, v116
	v_sub_f32_e32 v63, v63, v116
	v_pk_mul_f32 v[58:59], v[116:117], v[58:59] op_sel:[1,0]
	v_pk_mul_f32 v[56:57], v[116:117], v[56:57] op_sel:[1,0]
	v_pk_mul_f32 v[62:63], v[116:117], v[62:63] op_sel:[1,0]
	v_pk_mul_f32 v[60:61], v[116:117], v[60:61] op_sel:[1,0]
	v_pk_fma_f32 v[56:57], v[74:75], v[56:57], v[78:79]
	v_pk_fma_f32 v[58:59], v[72:73], v[58:59], v[76:77]
	v_pk_fma_f32 v[60:61], v[66:67], v[60:61], v[70:71]
	v_pk_fma_f32 v[62:63], v[64:65], v[62:63], v[68:69]
	v_add_u32_e32 v172, 0x8080, v192
	v_pk_fma_f32 v[54:55], v[56:57], s[36:37], v[54:55] op_sel_hi:[1,0,1]
	v_pk_fma_f32 v[56:57], v[58:59], s[36:37], v[52:53] op_sel_hi:[1,0,1]
	v_pk_fma_f32 v[50:51], v[60:61], s[36:37], v[50:51] op_sel_hi:[1,0,1]
	v_pk_fma_f32 v[48:49], v[62:63], s[36:37], v[48:49] op_sel_hi:[1,0,1]
	v_cvt_pk_f16_f32 v53, v54, v55
	v_cvt_pk_f16_f32 v52, v56, v57
	v_cvt_pk_f16_f32 v55, v50, v51
	v_cvt_pk_f16_f32 v54, v48, v49
	v_lshl_add_u64 v[48:49], v[172:173], 1, s[8:9]
	global_store_dwordx4 v[48:49], v[52:55], off sc1
	v_cvt_f32_f16_sdwa v51, v100 dst_sel:DWORD dst_unused:UNUSED_PAD src0_sel:WORD_1
	v_cvt_f32_f16_e32 v50, v100
	v_cvt_f32_f16_sdwa v49, v101 dst_sel:DWORD dst_unused:UNUSED_PAD src0_sel:WORD_1
	v_cvt_f32_f16_e32 v48, v101
	v_cvt_f32_f16_sdwa v55, v102 dst_sel:DWORD dst_unused:UNUSED_PAD src0_sel:WORD_1
	v_cvt_f32_f16_e32 v54, v102
	v_cvt_f32_f16_sdwa v53, v103 dst_sel:DWORD dst_unused:UNUSED_PAD src0_sel:WORD_1
	v_cvt_f32_f16_e32 v52, v103
	v_sub_f32_e32 v48, v48, v114
	v_sub_f32_e32 v49, v49, v114
	v_sub_f32_e32 v50, v50, v114
	v_sub_f32_e32 v51, v51, v114
	v_sub_f32_e32 v52, v52, v114
	v_sub_f32_e32 v53, v53, v114
	v_sub_f32_e32 v54, v54, v114
	v_sub_f32_e32 v55, v55, v114
	v_pk_mul_f32 v[50:51], v[114:115], v[50:51] op_sel:[1,0]
	v_pk_mul_f32 v[48:49], v[114:115], v[48:49] op_sel:[1,0]
	v_pk_mul_f32 v[54:55], v[114:115], v[54:55] op_sel:[1,0]
	v_pk_mul_f32 v[52:53], v[114:115], v[52:53] op_sel:[1,0]
	v_pk_fma_f32 v[48:49], v[74:75], v[48:49], v[78:79]
	v_pk_fma_f32 v[50:51], v[72:73], v[50:51], v[76:77]
	v_pk_fma_f32 v[52:53], v[66:67], v[52:53], v[70:71]
	v_pk_fma_f32 v[54:55], v[64:65], v[54:55], v[68:69]
	v_add_u32_e32 v172, 0x10080, v192
	v_pk_fma_f32 v[46:47], v[48:49], s[36:37], v[46:47] op_sel_hi:[1,0,1]
	v_pk_fma_f32 v[48:49], v[50:51], s[36:37], v[44:45] op_sel_hi:[1,0,1]
	v_pk_fma_f32 v[42:43], v[52:53], s[36:37], v[42:43] op_sel_hi:[1,0,1]
	v_pk_fma_f32 v[40:41], v[54:55], s[36:37], v[40:41] op_sel_hi:[1,0,1]
	v_cvt_pk_f16_f32 v45, v46, v47
	v_cvt_pk_f16_f32 v44, v48, v49
	v_cvt_pk_f16_f32 v47, v42, v43
	v_cvt_pk_f16_f32 v46, v40, v41
	v_lshl_add_u64 v[40:41], v[172:173], 1, s[8:9]
	global_store_dwordx4 v[40:41], v[44:47], off sc1
	v_cvt_f32_f16_sdwa v43, v96 dst_sel:DWORD dst_unused:UNUSED_PAD src0_sel:WORD_1
	v_cvt_f32_f16_e32 v42, v96
	v_cvt_f32_f16_sdwa v41, v97 dst_sel:DWORD dst_unused:UNUSED_PAD src0_sel:WORD_1
	v_cvt_f32_f16_e32 v40, v97
	v_cvt_f32_f16_sdwa v47, v98 dst_sel:DWORD dst_unused:UNUSED_PAD src0_sel:WORD_1
	v_cvt_f32_f16_e32 v46, v98
	v_cvt_f32_f16_sdwa v45, v99 dst_sel:DWORD dst_unused:UNUSED_PAD src0_sel:WORD_1
	v_cvt_f32_f16_e32 v44, v99
	v_sub_f32_e32 v40, v40, v112
	v_sub_f32_e32 v41, v41, v112
	v_sub_f32_e32 v42, v42, v112
	v_sub_f32_e32 v43, v43, v112
	v_sub_f32_e32 v44, v44, v112
; __device__ __forceinline__ u32x2 pack4h(f32x4 v) { const h16x4 h = __builtin_convertvector(v, h16x4); return __builtin_bit_cast(u32x2, h); }
; __device__ __forceinline__ f32x4 unpack4h(u32x2 w) { return __builtin_convertvector(__builtin_bit_cast(h16x4, w), f32x4); }
;     __device__ __forceinline__ void operator()(const f32x4 (&acc)[2][2][4][2], const pg8::Unit& u, int wr, int wc, int fr_, int fq_) const {
;     ...
; #pragma unroll
;                 for (int ai = 0; ai < 2; ++ai)
; #pragma unroll
;                     for (int m = 0; m < 4; ++m) { const unsigned off = (unsigned)(row0 + ai * 128 + m * 16) * DM + (unsigned)(col0 + bj * 128);
;                         u32x2 lo, hi; lo.x = r[ai][m].x; lo.y = r[ai][m].y; hi.x = r[ai][m].z; hi.y = r[ai][m].w;
;                         const f32x4 x0 = (unpack4h(lo) - mu[ai][m]) * rs[ai][m] * gv[0] + bv[0], x1 = (unpack4h(hi) - mu[ai][m]) * rs[ai][m] * gv[1] + bv[1];
;                         const u32x2 o0 = pack4h(x0 * ALPHA + acc[ai][bj][m][0] * s), o1 = pack4h(x1 * ALPHA + acc[ai][bj][m][1] * s);
;                         u32x4 w; w.x = o0.x; w.y = o0.y; w.z = o1.x; w.w = o1.y; *(u32x4*)(Z + off) = w; }
	v_sub_f32_e32 v45, v45, v112
	v_sub_f32_e32 v46, v46, v112
	v_sub_f32_e32 v47, v47, v112
	v_pk_mul_f32 v[42:43], v[112:113], v[42:43] op_sel:[1,0]
	v_pk_mul_f32 v[40:41], v[112:113], v[40:41] op_sel:[1,0]
	v_pk_mul_f32 v[46:47], v[112:113], v[46:47] op_sel:[1,0]
	v_pk_mul_f32 v[44:45], v[112:113], v[44:45] op_sel:[1,0]
	v_pk_fma_f32 v[40:41], v[74:75], v[40:41], v[78:79]
	v_pk_fma_f32 v[42:43], v[72:73], v[42:43], v[76:77]
	v_pk_fma_f32 v[44:45], v[66:67], v[44:45], v[70:71]
	v_pk_fma_f32 v[46:47], v[64:65], v[46:47], v[68:69]
	v_add_u32_e32 v172, 0x18080, v192
	v_pk_fma_f32 v[38:39], v[40:41], s[36:37], v[38:39] op_sel_hi:[1,0,1]
	v_pk_fma_f32 v[40:41], v[42:43], s[36:37], v[36:37] op_sel_hi:[1,0,1]
	v_pk_fma_f32 v[34:35], v[44:45], s[36:37], v[34:35] op_sel_hi:[1,0,1]
	v_pk_fma_f32 v[32:33], v[46:47], s[36:37], v[32:33] op_sel_hi:[1,0,1]
	v_cvt_pk_f16_f32 v37, v38, v39
	v_cvt_pk_f16_f32 v36, v40, v41
	v_cvt_pk_f16_f32 v39, v34, v35
	v_cvt_pk_f16_f32 v38, v32, v33
	v_lshl_add_u64 v[32:33], v[172:173], 1, s[8:9]
	global_store_dwordx4 v[32:33], v[36:39], off sc1
	v_cvt_f32_f16_sdwa v35, v92 dst_sel:DWORD dst_unused:UNUSED_PAD src0_sel:WORD_1
	v_cvt_f32_f16_e32 v34, v92
	v_cvt_f32_f16_sdwa v33, v93 dst_sel:DWORD dst_unused:UNUSED_PAD src0_sel:WORD_1
	v_cvt_f32_f16_e32 v32, v93
	v_cvt_f32_f16_sdwa v39, v94 dst_sel:DWORD dst_unused:UNUSED_PAD src0_sel:WORD_1
	v_cvt_f32_f16_e32 v38, v94
	v_cvt_f32_f16_sdwa v37, v95 dst_sel:DWORD dst_unused:UNUSED_PAD src0_sel:WORD_1
	v_cvt_f32_f16_e32 v36, v95
	v_sub_f32_e32 v32, v32, v110
	v_sub_f32_e32 v33, v33, v110
	v_sub_f32_e32 v34, v34, v110
	v_sub_f32_e32 v35, v35, v110
	v_sub_f32_e32 v36, v36, v110
	v_sub_f32_e32 v37, v37, v110
	v_sub_f32_e32 v38, v38, v110
	v_sub_f32_e32 v39, v39, v110
	v_pk_mul_f32 v[34:35], v[110:111], v[34:35] op_sel:[1,0]
	v_pk_mul_f32 v[32:33], v[110:111], v[32:33] op_sel:[1,0]
	v_pk_mul_f32 v[38:39], v[110:111], v[38:39] op_sel:[1,0]
	v_pk_mul_f32 v[36:37], v[110:111], v[36:37] op_sel:[1,0]
	v_pk_fma_f32 v[32:33], v[74:75], v[32:33], v[78:79]
	v_pk_fma_f32 v[34:35], v[72:73], v[34:35], v[76:77]
	v_pk_fma_f32 v[36:37], v[66:67], v[36:37], v[70:71]
	v_pk_fma_f32 v[38:39], v[64:65], v[38:39], v[68:69]
	v_add_u32_e32 v172, 0x40080, v192
	v_pk_fma_f32 v[30:31], v[32:33], s[36:37], v[30:31] op_sel_hi:[1,0,1]
	v_pk_fma_f32 v[32:33], v[34:35], s[36:37], v[28:29] op_sel_hi:[1,0,1]
	v_pk_fma_f32 v[26:27], v[36:37], s[36:37], v[26:27] op_sel_hi:[1,0,1]
	v_pk_fma_f32 v[24:25], v[38:39], s[36:37], v[24:25] op_sel_hi:[1,0,1]
	v_cvt_pk_f16_f32 v29, v30, v31
	v_cvt_pk_f16_f32 v28, v32, v33
	v_cvt_pk_f16_f32 v31, v26, v27
	v_cvt_pk_f16_f32 v30, v24, v25
	v_lshl_add_u64 v[24:25], v[172:173], 1, s[8:9]
	global_store_dwordx4 v[24:25], v[28:31], off sc1
	v_cvt_f32_f16_sdwa v27, v88 dst_sel:DWORD dst_unused:UNUSED_PAD src0_sel:WORD_1
	v_cvt_f32_f16_e32 v26, v88
	v_cvt_f32_f16_sdwa v25, v89 dst_sel:DWORD dst_unused:UNUSED_PAD src0_sel:WORD_1
	v_cvt_f32_f16_e32 v24, v89
	v_cvt_f32_f16_sdwa v31, v90 dst_sel:DWORD dst_unused:UNUSED_PAD src0_sel:WORD_1
	v_cvt_f32_f16_e32 v30, v90
	v_cvt_f32_f16_sdwa v29, v91 dst_sel:DWORD dst_unused:UNUSED_PAD src0_sel:WORD_1
	v_cvt_f32_f16_e32 v28, v91
	v_sub_f32_e32 v24, v24, v108
	v_sub_f32_e32 v25, v25, v108
	v_sub_f32_e32 v26, v26, v108
	v_sub_f32_e32 v27, v27, v108
	v_sub_f32_e32 v28, v28, v108
	v_sub_f32_e32 v29, v29, v108
	v_sub_f32_e32 v30, v30, v108
	v_sub_f32_e32 v31, v31, v108
	v_pk_mul_f32 v[26:27], v[108:109], v[26:27] op_sel:[1,0]
	v_pk_mul_f32 v[24:25], v[108:109], v[24:25] op_sel:[1,0]
	v_pk_mul_f32 v[30:31], v[108:109], v[30:31] op_sel:[1,0]
	v_pk_mul_f32 v[28:29], v[108:109], v[28:29] op_sel:[1,0]
	v_pk_fma_f32 v[24:25], v[74:75], v[24:25], v[78:79]
	v_pk_fma_f32 v[26:27], v[72:73], v[26:27], v[76:77]
	v_pk_fma_f32 v[28:29], v[66:67], v[28:29], v[70:71]
	v_pk_fma_f32 v[30:31], v[64:65], v[30:31], v[68:69]
	v_add_u32_e32 v172, 0x48080, v192
	v_pk_fma_f32 v[22:23], v[24:25], s[36:37], v[22:23] op_sel_hi:[1,0,1]
; #define PG8_WAIT_V(n) asm volatile("s_waitcnt vmcnt(" #n ")" ::: "memory")
; #define PG8_BAR __builtin_amdgcn_s_barrier()
; __device__ __forceinline__ u32x2 pack4h(f32x4 v) { const h16x4 h = __builtin_convertvector(v, h16x4); return __builtin_bit_cast(u32x2, h); }
; __device__ __forceinline__ f32x4 unpack4h(u32x2 w) { return __builtin_convertvector(__builtin_bit_cast(h16x4, w), f32x4); }
; template <class Epi, class Sched>
; __device__ __forceinline__ void gemm_phase(PG8_LAS unsigned char* lds, const Gemm g, const Sched& S, const Epi& E) {
;     ...
;         if constexpr (!Epi::AFTER_DRAIN) { E(acc, cur, wr, wc, fr, fq); S.done(cur); }
;         if (!has_next) break;
; #pragma unroll
;         for (int a = 0; a < 2; ++a)
; #pragma unroll
;             for (int b = 0; b < 2; ++b)
; #pragma unroll
;                 for (int m = 0; m < 4; ++m)
; #pragma unroll
;                     for (int n = 0; n < 2; ++n) acc[a][b][m][n] = (f32x4){0.f, 0.f, 0.f, 0.f};
;         cur = nxt; cA = nA; cB = nB; ++ui;
;     }
;     PG8_WAIT_V(0);
;     if (wr == 0) PG8_BAR;
;     __device__ __forceinline__ void operator()(const f32x4 (&acc)[2][2][4][2], const pg8::Unit& u, int wr, int wc, int fr_, int fq_) const {
;     ...
; #pragma unroll
;                 for (int ai = 0; ai < 2; ++ai)
; #pragma unroll
;                     for (int m = 0; m < 4; ++m) { const unsigned off = (unsigned)(row0 + ai * 128 + m * 16) * DM + (unsigned)(col0 + bj * 128);
;                         u32x2 lo, hi; lo.x = r[ai][m].x; lo.y = r[ai][m].y; hi.x = r[ai][m].z; hi.y = r[ai][m].w;
;                         const f32x4 x0 = (unpack4h(lo) - mu[ai][m]) * rs[ai][m] * gv[0] + bv[0], x1 = (unpack4h(hi) - mu[ai][m]) * rs[ai][m] * gv[1] + bv[1];
;                         const u32x2 o0 = pack4h(x0 * ALPHA + acc[ai][bj][m][0] * s), o1 = pack4h(x1 * ALPHA + acc[ai][bj][m][1] * s);
;                         u32x4 w; w.x = o0.x; w.y = o0.y; w.z = o1.x; w.w = o1.y; *(u32x4*)(Z + off) = w; }
	v_pk_fma_f32 v[24:25], v[26:27], s[36:37], v[20:21] op_sel_hi:[1,0,1]
	v_pk_fma_f32 v[18:19], v[28:29], s[36:37], v[18:19] op_sel_hi:[1,0,1]
	v_pk_fma_f32 v[16:17], v[30:31], s[36:37], v[16:17] op_sel_hi:[1,0,1]
	v_cvt_pk_f16_f32 v21, v22, v23
	v_cvt_pk_f16_f32 v20, v24, v25
	v_cvt_pk_f16_f32 v23, v18, v19
	v_cvt_pk_f16_f32 v22, v16, v17
	v_lshl_add_u64 v[16:17], v[172:173], 1, s[8:9]
	global_store_dwordx4 v[16:17], v[20:23], off sc1
	v_cvt_f32_f16_sdwa v19, v84 dst_sel:DWORD dst_unused:UNUSED_PAD src0_sel:WORD_1
	v_cvt_f32_f16_e32 v18, v84
	v_cvt_f32_f16_sdwa v17, v85 dst_sel:DWORD dst_unused:UNUSED_PAD src0_sel:WORD_1
	v_cvt_f32_f16_e32 v16, v85
	v_cvt_f32_f16_sdwa v23, v86 dst_sel:DWORD dst_unused:UNUSED_PAD src0_sel:WORD_1
	v_cvt_f32_f16_e32 v22, v86
	v_cvt_f32_f16_sdwa v21, v87 dst_sel:DWORD dst_unused:UNUSED_PAD src0_sel:WORD_1
	v_cvt_f32_f16_e32 v20, v87
	v_sub_f32_e32 v16, v16, v106
	v_sub_f32_e32 v17, v17, v106
	v_sub_f32_e32 v18, v18, v106
	v_sub_f32_e32 v19, v19, v106
	v_sub_f32_e32 v20, v20, v106
	v_sub_f32_e32 v21, v21, v106
	v_sub_f32_e32 v22, v22, v106
	v_sub_f32_e32 v23, v23, v106
	v_pk_mul_f32 v[18:19], v[106:107], v[18:19] op_sel:[1,0]
	v_pk_mul_f32 v[16:17], v[106:107], v[16:17] op_sel:[1,0]
	v_pk_mul_f32 v[22:23], v[106:107], v[22:23] op_sel:[1,0]
	v_pk_mul_f32 v[20:21], v[106:107], v[20:21] op_sel:[1,0]
	v_pk_fma_f32 v[16:17], v[74:75], v[16:17], v[78:79]
	v_pk_fma_f32 v[18:19], v[72:73], v[18:19], v[76:77]
	v_pk_fma_f32 v[20:21], v[66:67], v[20:21], v[70:71]
	v_pk_fma_f32 v[22:23], v[64:65], v[22:23], v[68:69]
	v_add_u32_e32 v172, 0x50080, v192
	v_pk_fma_f32 v[14:15], v[16:17], s[36:37], v[14:15] op_sel_hi:[1,0,1]
	v_pk_fma_f32 v[16:17], v[18:19], s[36:37], v[12:13] op_sel_hi:[1,0,1]
	v_pk_fma_f32 v[10:11], v[20:21], s[36:37], v[10:11] op_sel_hi:[1,0,1]
	v_pk_fma_f32 v[8:9], v[22:23], s[36:37], v[8:9] op_sel_hi:[1,0,1]
	v_cvt_pk_f16_f32 v13, v14, v15
	v_cvt_pk_f16_f32 v12, v16, v17
	v_cvt_pk_f16_f32 v15, v10, v11
	v_cvt_pk_f16_f32 v14, v8, v9
	v_lshl_add_u64 v[8:9], v[172:173], 1, s[8:9]
	global_store_dwordx4 v[8:9], v[12:15], off sc1
	v_cvt_f32_f16_sdwa v9, v81 dst_sel:DWORD dst_unused:UNUSED_PAD src0_sel:WORD_1
	v_cvt_f32_f16_e32 v8, v81
	v_cvt_f32_f16_sdwa v15, v82 dst_sel:DWORD dst_unused:UNUSED_PAD src0_sel:WORD_1
	v_cvt_f32_f16_e32 v14, v82
	v_cvt_f32_f16_sdwa v11, v80 dst_sel:DWORD dst_unused:UNUSED_PAD src0_sel:WORD_1
	v_cvt_f32_f16_e32 v10, v80
	v_cvt_f32_f16_sdwa v13, v83 dst_sel:DWORD dst_unused:UNUSED_PAD src0_sel:WORD_1
	v_cvt_f32_f16_e32 v12, v83
	v_sub_f32_e32 v8, v8, v104
	v_sub_f32_e32 v9, v9, v104
	v_sub_f32_e32 v14, v14, v104
	v_sub_f32_e32 v15, v15, v104
	v_sub_f32_e32 v10, v10, v104
	v_sub_f32_e32 v11, v11, v104
	v_pk_mul_f32 v[8:9], v[104:105], v[8:9] op_sel:[1,0]
	v_pk_mul_f32 v[14:15], v[104:105], v[14:15] op_sel:[1,0]
	v_pk_mul_f32 v[10:11], v[104:105], v[10:11] op_sel:[1,0]
	v_pk_fma_f32 v[8:9], v[74:75], v[8:9], v[78:79]
	v_sub_f32_e32 v12, v12, v104
	v_sub_f32_e32 v13, v13, v104
	v_pk_fma_f32 v[14:15], v[64:65], v[14:15], v[68:69]
	v_add_u32_e32 v172, 0x58080, v192
	v_pk_fma_f32 v[10:11], v[72:73], v[10:11], v[76:77]
	v_pk_mul_f32 v[12:13], v[104:105], v[12:13] op_sel:[1,0]
	v_pk_fma_f32 v[6:7], v[8:9], s[36:37], v[6:7] op_sel_hi:[1,0,1]
	v_pk_fma_f32 v[0:1], v[14:15], s[36:37], v[0:1] op_sel_hi:[1,0,1]
	v_pk_fma_f32 v[12:13], v[66:67], v[12:13], v[70:71]
	v_pk_fma_f32 v[8:9], v[10:11], s[36:37], v[4:5] op_sel_hi:[1,0,1]
	v_cvt_pk_f16_f32 v5, v6, v7
	v_cvt_pk_f16_f32 v6, v0, v1
	v_lshl_add_u64 v[0:1], v[172:173], 1, s[8:9]
	v_readlane_b32 s8, v255, 52
	v_pk_fma_f32 v[2:3], v[12:13], s[36:37], v[2:3] op_sel_hi:[1,0,1]
	v_readlane_b32 s9, v255, 53
	v_cvt_pk_f16_f32 v4, v8, v9
	v_cvt_pk_f16_f32 v7, v2, v3
	s_and_b64 vcc, exec, s[8:9]
	global_store_dwordx4 v[0:1], v[4:7], off sc1
	s_cbranch_vccz .LBB0_94
	s_waitcnt vmcnt(0)
	v_readlane_b32 s0, v255, 60
	s_cmpk_gt_u32 s0, 0xff
	v_readlane_b32 s45, v255, 56
	s_cbranch_scc1 .LBB0_105
	s_barrier

; #define PG8_STAGE(bufoff, gbase, voff) do { _Pragma("unroll") for (int _i = 0; _i < 2; ++_i) \
;         __builtin_amdgcn_global_load_lds((const unsigned*)((const char*)(gbase) + (voff)[_i]), (PG8_LAS unsigned*)(lds + (bufoff) + ldsw + _i * 8192), 16, 0, 0); } while (0)
; #define PG8_LDA(dst, b, h) do { _Pragma("unroll") for (int m = 0; m < 4; ++m) _Pragma("unroll") for (int k = 0; k < 2; ++k) dst[m][k] = *(const PG8_LAS bf16x8*)(lds + PG8_SA(b, h) + aoff + m * 2048 + k * 1024); } while (0)
; #define PG8_LDB(dst, b, h) do { _Pragma("unroll") for (int n = 0; n < 2; ++n) _Pragma("unroll") for (int k = 0; k < 2; ++k) dst[n][k] = *(const PG8_LAS bf16x8*)(lds + PG8_SB(b, h) + boff + n * 2048 + k * 1024); } while (0)
; #define PG8_MMA(ai, bj, At, Bt) do { __builtin_amdgcn_s_setprio(1); _Pragma("unroll") for (int m = 0; m < 4; ++m) _Pragma("unroll") for (int n = 0; n < 2; ++n) _Pragma("unroll") for (int k = 0; k < 2; ++k) \
;         acc[ai][bj][m][n] = __builtin_amdgcn_mfma_f32_16x16x32_bf16(Bt[n][k], At[m][k], acc[ai][bj][m][n], 0, 0, 0); __builtin_amdgcn_s_setprio(0); } while (0)
; #define PG8_WAIT_V(n) asm volatile("s_waitcnt vmcnt(" #n ")" ::: "memory")
; #define PG8_WAIT_L(n) asm volatile("s_waitcnt lgkmcnt(" #n ")" ::: "memory")
; template <class Epi, class Sched>
; __device__ __forceinline__ void gemm_phase(PG8_LAS unsigned char* lds, const Gemm g, const Sched& S, const Epi& E) {
;     ...
;             const bool last = (t == nt - 2);
;             const char* a1 = cA + (size_t)(t + 1) * kstep;
;             const char* a2 = last ? nA : cA + (size_t)(t + 2) * kstep; const char* b2 = last ? nB : cB + (size_t)(t + 2) * kstep;
;             const char* a3 = a2 + kstep; const char* b3 = b2 + kstep;
;             if (last && has_next) S.a_ready(nxt);
;             PG8_LDB(B0, 0, 0); PG8_SCHED; PG8_LDA(At, 0, 0); PG8_STAGE(PG8_SA(1, 1), a1 + hstep, voffA);
;             PG8_WAIT_L(8); PG8_BAR; PG8_WAIT_L(0); PG8_MMA(0, 0, At, B0); PG8_BAR; PG8_SCHED;
;             PG8_LDB(B1, 0, 1); PG8_STAGE(PG8_SB(0, 0), b2, voffB);
;             PG8_BAR; PG8_WAIT_L(0); PG8_MMA(0, 1, At, B1); PG8_BAR;
;             PG8_LDA(At, 0, 1); PG8_STAGE(PG8_SA(0, 0), a2, voffA);
;             PG8_BAR; PG8_WAIT_L(0); PG8_MMA(1, 0, At, B0); PG8_BAR; PG8_SCHED;
;             PG8_STAGE(PG8_SB(0, 1), b2 + hstep, voffB);
;             PG8_WAIT_V(6); PG8_BAR; PG8_MMA(1, 1, At, B1); PG8_BAR;
.LBB0_539:
	s_add_u32 s26, s48, 0xfff80080
	s_addc_u32 s27, s49, -1
	s_add_i32 vcc_lo, 0, 0x10000
	v_add_u32_e32 v154, vcc_lo, v143
	ds_read_b128 v[138:141], v154
	ds_read_b128 v[146:149], v154 offset:1024
	ds_read_b128 v[150:153], v154 offset:2048
	ds_read_b128 v[154:157], v154 offset:3072
	s_cmp_eq_u32 s29, 28
	s_cselect_b32 s53, s43, s27
	s_cselect_b32 s52, s40, s26
	s_cselect_b32 s51, s1, s28
	s_cselect_b32 s50, s9, s41
	v_lshl_add_u64 v[170:171], s[48:49], 0, v[134:135]
	s_add_i32 m0, s57, 0xc000
	ds_read_b128 v[158:161], v145
	ds_read_b128 v[162:165], v145 offset:1024
	ds_read_b128 v[166:169], v145 offset:2048
	ds_read_b128 v[180:183], v145 offset:3072
	ds_read_b128 v[184:187], v145 offset:4096
	ds_read_b128 v[188:191], v145 offset:5120
	ds_read_b128 v[192:195], v145 offset:6144
	ds_read_b128 v[196:199], v145 offset:7168
	global_load_lds_dwordx4 v[170:171], off
	v_lshl_add_u64 v[170:171], s[48:49], 0, v[136:137]
	s_add_i32 m0, s57, 0xe000
	s_nop 0
	global_load_lds_dwordx4 v[170:171], off
	s_waitcnt lgkmcnt(8)
	s_barrier
	s_waitcnt lgkmcnt(0)
	s_setprio 1
	s_waitcnt lgkmcnt(0)
	v_mfma_f32_16x16x32_bf16 v[124:127], v[138:141], v[158:161], v[124:127]
	v_mfma_f32_16x16x32_bf16 v[120:123], v[150:153], v[158:161], v[120:123]
	v_mfma_f32_16x16x32_bf16 v[116:119], v[138:141], v[166:169], v[116:119]
	v_mfma_f32_16x16x32_bf16 v[108:111], v[150:153], v[166:169], v[108:111]
	v_mfma_f32_16x16x32_bf16 v[100:103], v[138:141], v[184:187], v[100:103]
	v_mfma_f32_16x16x32_bf16 v[92:95], v[150:153], v[184:187], v[92:95]
	v_mfma_f32_16x16x32_bf16 v[84:87], v[138:141], v[192:195], v[84:87]
	v_mfma_f32_16x16x32_bf16 v[76:79], v[150:153], v[192:195], v[76:79]
	v_mfma_f32_16x16x32_bf16 v[124:127], v[146:149], v[162:165], v[124:127]
	v_mfma_f32_16x16x32_bf16 v[120:123], v[154:157], v[162:165], v[120:123]
	v_mfma_f32_16x16x32_bf16 v[116:119], v[146:149], v[180:183], v[116:119]
	v_mfma_f32_16x16x32_bf16 v[108:111], v[154:157], v[180:183], v[108:111]
	v_mfma_f32_16x16x32_bf16 v[100:103], v[146:149], v[188:191], v[100:103]
	v_mfma_f32_16x16x32_bf16 v[92:95], v[154:157], v[188:191], v[92:95]
	v_mfma_f32_16x16x32_bf16 v[84:87], v[146:149], v[196:199], v[84:87]
	v_mfma_f32_16x16x32_bf16 v[76:79], v[154:157], v[196:199], v[76:79]
	s_setprio 0
	s_barrier
	s_add_i32 s26, 0, 0x14000
	v_add_u32_e32 v170, s26, v143
	s_add_i32 s27, vcc_lo, s56
	ds_read_b128 v[200:203], v170
	ds_read_b128 v[204:207], v170 offset:1024
	ds_read_b128 v[208:211], v170 offset:2048
	ds_read_b128 v[212:215], v170 offset:3072
	v_lshl_add_u64 v[170:171], s[50:51], 0, v[172:173]
	s_mov_b32 m0, s27
	v_lshl_add_u64 v[176:177], s[50:51], 0, v[128:129]
	global_load_lds_dwordx4 v[170:171], off
	s_add_i32 m0, s27, 0x2000
	s_nop 0
	global_load_lds_dwordx4 v[176:177], off
	s_barrier
	s_waitcnt lgkmcnt(0)
	s_setprio 1
	s_waitcnt lgkmcnt(0)
	v_mfma_f32_16x16x32_bf16 v[112:115], v[200:203], v[158:161], v[112:115]
	v_mfma_f32_16x16x32_bf16 v[104:107], v[208:211], v[158:161], v[104:107]
	v_mfma_f32_16x16x32_bf16 v[96:99], v[200:203], v[166:169], v[96:99]
	v_mfma_f32_16x16x32_bf16 v[88:91], v[208:211], v[166:169], v[88:91]
	v_mfma_f32_16x16x32_bf16 v[80:83], v[200:203], v[184:187], v[80:83]
	v_mfma_f32_16x16x32_bf16 v[72:75], v[208:211], v[184:187], v[72:75]
	v_mfma_f32_16x16x32_bf16 v[68:71], v[200:203], v[192:195], v[68:71]
	v_mfma_f32_16x16x32_bf16 v[64:67], v[208:211], v[192:195], v[64:67]
	v_mfma_f32_16x16x32_bf16 v[112:115], v[204:207], v[162:165], v[112:115]
	v_mfma_f32_16x16x32_bf16 v[104:107], v[212:215], v[162:165], v[104:107]
	v_mfma_f32_16x16x32_bf16 v[96:99], v[204:207], v[180:183], v[96:99]
	v_mfma_f32_16x16x32_bf16 v[88:91], v[212:215], v[180:183], v[88:91]
	v_mfma_f32_16x16x32_bf16 v[80:83], v[204:207], v[188:191], v[80:83]
	v_mfma_f32_16x16x32_bf16 v[72:75], v[212:215], v[188:191], v[72:75]
	v_mfma_f32_16x16x32_bf16 v[68:71], v[204:207], v[196:199], v[68:71]
	v_mfma_f32_16x16x32_bf16 v[64:67], v[212:215], v[196:199], v[64:67]
	s_setprio 0
	s_mov_b32 m0, s57
	v_lshl_add_u64 v[178:179], s[52:53], 0, v[132:133]
	s_barrier
	ds_read_b128 v[158:161], v145 offset:16384
	ds_read_b128 v[162:165], v145 offset:17408
	ds_read_b128 v[166:169], v145 offset:18432
	ds_read_b128 v[180:183], v145 offset:19456
	ds_read_b128 v[184:187], v145 offset:20480
	ds_read_b128 v[188:191], v145 offset:21504
	ds_read_b128 v[192:195], v145 offset:22528
	ds_read_b128 v[196:199], v145 offset:23552
	global_load_lds_dwordx4 v[178:179], off
	v_lshl_add_u64 v[216:217], s[52:53], 0, v[130:131]
	s_mov_b32 m0, s58
	s_nop 0
	global_load_lds_dwordx4 v[216:217], off
	s_barrier
	s_waitcnt lgkmcnt(0)
	s_setprio 1
	s_waitcnt lgkmcnt(0)
	v_mfma_f32_16x16x32_bf16 v[60:63], v[138:141], v[158:161], v[60:63]
	v_mfma_f32_16x16x32_bf16 v[56:59], v[150:153], v[158:161], v[56:59]
	v_mfma_f32_16x16x32_bf16 v[52:55], v[138:141], v[166:169], v[52:55]
	v_mfma_f32_16x16x32_bf16 v[44:47], v[150:153], v[166:169], v[44:47]
	v_mfma_f32_16x16x32_bf16 v[36:39], v[138:141], v[184:187], v[36:39]
	v_mfma_f32_16x16x32_bf16 v[28:31], v[150:153], v[184:187], v[28:31]
	v_mfma_f32_16x16x32_bf16 v[20:23], v[138:141], v[192:195], v[20:23]
	v_mfma_f32_16x16x32_bf16 v[12:15], v[150:153], v[192:195], v[12:15]
	v_mfma_f32_16x16x32_bf16 v[60:63], v[146:149], v[162:165], v[60:63]
	v_mfma_f32_16x16x32_bf16 v[56:59], v[154:157], v[162:165], v[56:59]
	v_mfma_f32_16x16x32_bf16 v[52:55], v[146:149], v[180:183], v[52:55]
	v_mfma_f32_16x16x32_bf16 v[44:47], v[154:157], v[180:183], v[44:47]
	v_mfma_f32_16x16x32_bf16 v[36:39], v[146:149], v[188:191], v[36:39]
	v_mfma_f32_16x16x32_bf16 v[28:31], v[154:157], v[188:191], v[28:31]
	v_mfma_f32_16x16x32_bf16 v[20:23], v[146:149], v[196:199], v[20:23]
	v_mfma_f32_16x16x32_bf16 v[12:15], v[154:157], v[196:199], v[12:15]
	s_setprio 0
	s_barrier
; #define PG8_STAGE(bufoff, gbase, voff) do { _Pragma("unroll") for (int _i = 0; _i < 2; ++_i) \
;         __builtin_amdgcn_global_load_lds((const unsigned*)((const char*)(gbase) + (voff)[_i]), (PG8_LAS unsigned*)(lds + (bufoff) + ldsw + _i * 8192), 16, 0, 0); } while (0)
; #define PG8_LDA(dst, b, h) do { _Pragma("unroll") for (int m = 0; m < 4; ++m) _Pragma("unroll") for (int k = 0; k < 2; ++k) dst[m][k] = *(const PG8_LAS bf16x8*)(lds + PG8_SA(b, h) + aoff + m * 2048 + k * 1024); } while (0)
; #define PG8_LDB(dst, b, h) do { _Pragma("unroll") for (int n = 0; n < 2; ++n) _Pragma("unroll") for (int k = 0; k < 2; ++k) dst[n][k] = *(const PG8_LAS bf16x8*)(lds + PG8_SB(b, h) + boff + n * 2048 + k * 1024); } while (0)
; #define PG8_MMA(ai, bj, At, Bt) do { __builtin_amdgcn_s_setprio(1); _Pragma("unroll") for (int m = 0; m < 4; ++m) _Pragma("unroll") for (int n = 0; n < 2; ++n) _Pragma("unroll") for (int k = 0; k < 2; ++k) \
;         acc[ai][bj][m][n] = __builtin_amdgcn_mfma_f32_16x16x32_bf16(Bt[n][k], At[m][k], acc[ai][bj][m][n], 0, 0, 0); __builtin_amdgcn_s_setprio(0); } while (0)
; #define PG8_WAIT_V(n) asm volatile("s_waitcnt vmcnt(" #n ")" ::: "memory")
; #define PG8_WAIT_L(n) asm volatile("s_waitcnt lgkmcnt(" #n ")" ::: "memory")
; #define PG8_BAR __builtin_amdgcn_s_barrier()
; #define PG8_SCHED __builtin_amdgcn_sched_barrier(0)
; template <class Epi, class Sched>
; __device__ __forceinline__ void gemm_phase(PG8_LAS unsigned char* lds, const Gemm g, const Sched& S, const Epi& E) {
;     ...
;             PG8_BAR; PG8_WAIT_L(0); PG8_MMA(1, 0, At, B0); PG8_BAR; PG8_SCHED;
;             PG8_STAGE(PG8_SB(0, 1), b2 + hstep, voffB);
;             PG8_WAIT_V(6); PG8_BAR; PG8_MMA(1, 1, At, B1); PG8_BAR;
;             PG8_LDB(B0, 1, 0); PG8_SCHED; PG8_LDA(At, 1, 0); PG8_STAGE(PG8_SA(0, 1), a2 + hstep, voffA);
;             PG8_WAIT_L(8); PG8_BAR; PG8_WAIT_L(0); PG8_MMA(0, 0, At, B0); PG8_BAR; PG8_SCHED;
;             PG8_LDB(B1, 1, 1); PG8_STAGE(PG8_SB(1, 0), b3, voffB);
;             PG8_BAR; PG8_WAIT_L(0); PG8_MMA(0, 1, At, B1); PG8_BAR;
	s_add_u32 vcc_lo, s50, 0x80000
	s_addc_u32 vcc_hi, s51, 0
	s_add_i32 s26, s26, s56
	v_lshl_add_u64 v[138:139], vcc, 0, v[172:173]
	s_mov_b32 m0, s26
	s_nop 0
	global_load_lds_dwordx4 v[138:139], off
	v_lshl_add_u64 v[138:139], vcc, 0, v[128:129]
	s_add_i32 m0, s26, 0x2000
	s_nop 0
	global_load_lds_dwordx4 v[138:139], off
	s_waitcnt vmcnt(6)
	s_barrier
	s_setprio 1
	v_mfma_f32_16x16x32_bf16 v[48:51], v[200:203], v[158:161], v[48:51]
	v_mfma_f32_16x16x32_bf16 v[40:43], v[208:211], v[158:161], v[40:43]
	v_mfma_f32_16x16x32_bf16 v[32:35], v[200:203], v[166:169], v[32:35]
	v_mfma_f32_16x16x32_bf16 v[24:27], v[208:211], v[166:169], v[24:27]
	v_mfma_f32_16x16x32_bf16 v[16:19], v[200:203], v[184:187], v[16:19]
	v_mfma_f32_16x16x32_bf16 v[8:11], v[208:211], v[184:187], v[8:11]
	v_mfma_f32_16x16x32_bf16 v[4:7], v[200:203], v[192:195], v[4:7]
	v_mfma_f32_16x16x32_bf16 v[0:3], v[208:211], v[192:195], v[0:3]
	v_mfma_f32_16x16x32_bf16 v[48:51], v[204:207], v[162:165], v[48:51]
	v_mfma_f32_16x16x32_bf16 v[40:43], v[212:215], v[162:165], v[40:43]
	v_mfma_f32_16x16x32_bf16 v[32:35], v[204:207], v[180:183], v[32:35]
	v_mfma_f32_16x16x32_bf16 v[24:27], v[212:215], v[180:183], v[24:27]
	v_mfma_f32_16x16x32_bf16 v[16:19], v[204:207], v[188:191], v[16:19]
	v_mfma_f32_16x16x32_bf16 v[8:11], v[212:215], v[188:191], v[8:11]
	v_mfma_f32_16x16x32_bf16 v[4:7], v[204:207], v[196:199], v[4:7]
	v_mfma_f32_16x16x32_bf16 v[0:3], v[212:215], v[196:199], v[0:3]
	s_setprio 0
	s_add_i32 s26, 0, 0x18000
	v_add_u32_e32 v154, s26, v143
	s_barrier
	ds_read_b128 v[138:141], v154
	ds_read_b128 v[146:149], v154 offset:1024
	ds_read_b128 v[150:153], v154 offset:2048
	ds_read_b128 v[154:157], v154 offset:3072
	s_add_u32 s52, s52, 0x80000
	s_addc_u32 s53, s53, 0
	s_mov_b32 m0, s59
	v_lshl_add_u64 v[200:201], s[52:53], 0, v[132:133]
	ds_read_b128 v[158:161], v145 offset:32768
	ds_read_b128 v[162:165], v145 offset:33792
	ds_read_b128 v[166:169], v145 offset:34816
	ds_read_b128 v[180:183], v145 offset:35840
	ds_read_b128 v[184:187], v145 offset:36864
	ds_read_b128 v[188:191], v145 offset:37888
	ds_read_b128 v[192:195], v145 offset:38912
	ds_read_b128 v[196:199], v145 offset:39936
	global_load_lds_dwordx4 v[200:201], off
	v_lshl_add_u64 v[200:201], s[52:53], 0, v[130:131]
	s_mov_b32 m0, s62
	s_nop 0
	global_load_lds_dwordx4 v[200:201], off
	s_waitcnt lgkmcnt(8)
	s_barrier
	s_waitcnt lgkmcnt(0)
	s_setprio 1
	s_waitcnt lgkmcnt(0)
	v_mfma_f32_16x16x32_bf16 v[124:127], v[138:141], v[158:161], v[124:127]
	v_mfma_f32_16x16x32_bf16 v[120:123], v[150:153], v[158:161], v[120:123]
	v_mfma_f32_16x16x32_bf16 v[116:119], v[138:141], v[166:169], v[116:119]
	v_mfma_f32_16x16x32_bf16 v[108:111], v[150:153], v[166:169], v[108:111]
	v_mfma_f32_16x16x32_bf16 v[100:103], v[138:141], v[184:187], v[100:103]
	v_mfma_f32_16x16x32_bf16 v[92:95], v[150:153], v[184:187], v[92:95]
	v_mfma_f32_16x16x32_bf16 v[84:87], v[138:141], v[192:195], v[84:87]
	v_mfma_f32_16x16x32_bf16 v[76:79], v[150:153], v[192:195], v[76:79]
	v_mfma_f32_16x16x32_bf16 v[124:127], v[146:149], v[162:165], v[124:127]
	v_mfma_f32_16x16x32_bf16 v[120:123], v[154:157], v[162:165], v[120:123]
	v_mfma_f32_16x16x32_bf16 v[116:119], v[146:149], v[180:183], v[116:119]
	v_mfma_f32_16x16x32_bf16 v[108:111], v[154:157], v[180:183], v[108:111]
	v_mfma_f32_16x16x32_bf16 v[100:103], v[146:149], v[188:191], v[100:103]
	v_mfma_f32_16x16x32_bf16 v[92:95], v[154:157], v[188:191], v[92:95]
	v_mfma_f32_16x16x32_bf16 v[84:87], v[146:149], v[196:199], v[84:87]
	v_mfma_f32_16x16x32_bf16 v[76:79], v[154:157], v[196:199], v[76:79]
	s_setprio 0
	s_barrier
	s_add_i32 s27, 0, 0x1c000
	s_add_i32 s26, s26, s56
	v_add_u32_e32 v174, s27, v143
	v_lshl_add_u64 v[170:171], v[170:171], 0, s[38:39]
	s_mov_b32 m0, s26
	ds_read_b128 v[200:203], v174
	ds_read_b128 v[204:207], v174 offset:1024
	ds_read_b128 v[208:211], v174 offset:2048
	ds_read_b128 v[212:215], v174 offset:3072
	global_load_lds_dwordx4 v[170:171], off
	v_lshl_add_u64 v[170:171], v[176:177], 0, s[38:39]
	s_add_i32 m0, s26, 0x2000
	s_nop 0
	global_load_lds_dwordx4 v[170:171], off
	s_barrier
	s_waitcnt lgkmcnt(0)
	s_setprio 1
	s_waitcnt lgkmcnt(0)
	v_mfma_f32_16x16x32_bf16 v[112:115], v[200:203], v[158:161], v[112:115]
	v_mfma_f32_16x16x32_bf16 v[104:107], v[208:211], v[158:161], v[104:107]
	v_mfma_f32_16x16x32_bf16 v[96:99], v[200:203], v[166:169], v[96:99]
	v_mfma_f32_16x16x32_bf16 v[88:91], v[208:211], v[166:169], v[88:91]
	v_mfma_f32_16x16x32_bf16 v[80:83], v[200:203], v[184:187], v[80:83]
	v_mfma_f32_16x16x32_bf16 v[72:75], v[208:211], v[184:187], v[72:75]
	v_mfma_f32_16x16x32_bf16 v[68:71], v[200:203], v[192:195], v[68:71]
	v_mfma_f32_16x16x32_bf16 v[64:67], v[208:211], v[192:195], v[64:67]
	v_mfma_f32_16x16x32_bf16 v[112:115], v[204:207], v[162:165], v[112:115]
	v_mfma_f32_16x16x32_bf16 v[104:107], v[212:215], v[162:165], v[104:107]
	v_mfma_f32_16x16x32_bf16 v[96:99], v[204:207], v[180:183], v[96:99]
	v_mfma_f32_16x16x32_bf16 v[88:91], v[212:215], v[180:183], v[88:91]
	v_mfma_f32_16x16x32_bf16 v[80:83], v[204:207], v[188:191], v[80:83]
	v_mfma_f32_16x16x32_bf16 v[72:75], v[212:215], v[188:191], v[72:75]
	v_mfma_f32_16x16x32_bf16 v[68:71], v[204:207], v[196:199], v[68:71]
	v_mfma_f32_16x16x32_bf16 v[64:67], v[212:215], v[196:199], v[64:67]
	s_setprio 0
	s_mov_b32 m0, s2
	v_lshl_add_u64 v[170:171], v[178:179], 0, s[38:39]
	s_barrier
	ds_read_b128 v[158:161], v145 offset:49152
	ds_read_b128 v[162:165], v145 offset:50176
	ds_read_b128 v[166:169], v145 offset:51200
	ds_read_b128 v[180:183], v145 offset:52224
	ds_read_b128 v[184:187], v145 offset:53248
	ds_read_b128 v[188:191], v145 offset:54272
	ds_read_b128 v[192:195], v145 offset:55296
	ds_read_b128 v[196:199], v145 offset:56320
	global_load_lds_dwordx4 v[170:171], off
	v_lshl_add_u64 v[170:171], v[216:217], 0, s[38:39]
	s_mov_b32 m0, s54
	s_nop 0
	global_load_lds_dwordx4 v[170:171], off
	s_barrier
; #define PG8_STAGE(bufoff, gbase, voff) do { _Pragma("unroll") for (int _i = 0; _i < 2; ++_i) \
;         __builtin_amdgcn_global_load_lds((const unsigned*)((const char*)(gbase) + (voff)[_i]), (PG8_LAS unsigned*)(lds + (bufoff) + ldsw + _i * 8192), 16, 0, 0); } while (0)
; #define PG8_LDA(dst, b, h) do { _Pragma("unroll") for (int m = 0; m < 4; ++m) _Pragma("unroll") for (int k = 0; k < 2; ++k) dst[m][k] = *(const PG8_LAS bf16x8*)(lds + PG8_SA(b, h) + aoff + m * 2048 + k * 1024); } while (0)
; #define PG8_MMA(ai, bj, At, Bt) do { __builtin_amdgcn_s_setprio(1); _Pragma("unroll") for (int m = 0; m < 4; ++m) _Pragma("unroll") for (int n = 0; n < 2; ++n) _Pragma("unroll") for (int k = 0; k < 2; ++k) \
;         acc[ai][bj][m][n] = __builtin_amdgcn_mfma_f32_16x16x32_bf16(Bt[n][k], At[m][k], acc[ai][bj][m][n], 0, 0, 0); __builtin_amdgcn_s_setprio(0); } while (0)
; #define PG8_WAIT_V(n) asm volatile("s_waitcnt vmcnt(" #n ")" ::: "memory")
; #define PG8_WAIT_L(n) asm volatile("s_waitcnt lgkmcnt(" #n ")" ::: "memory")
; #define PG8_BAR __builtin_amdgcn_s_barrier()
; #define PG8_SCHED __builtin_amdgcn_sched_barrier(0)
; template <class Epi, class Sched>
; __device__ __forceinline__ void gemm_phase(PG8_LAS unsigned char* lds, const Gemm g, const Sched& S, const Epi& E) {
;     ...
;             PG8_LDA(At, 1, 1); PG8_STAGE(PG8_SA(1, 0), a3, voffA);
;             PG8_BAR; PG8_WAIT_L(0); PG8_MMA(1, 0, At, B0); PG8_BAR; PG8_SCHED;
;             PG8_STAGE(PG8_SB(1, 1), b3 + hstep, voffB);
;             PG8_WAIT_V(6); PG8_BAR; PG8_MMA(1, 1, At, B1); PG8_BAR;
	s_waitcnt lgkmcnt(0)
	s_setprio 1
	s_waitcnt lgkmcnt(0)
	v_mfma_f32_16x16x32_bf16 v[60:63], v[138:141], v[158:161], v[60:63]
	v_mfma_f32_16x16x32_bf16 v[56:59], v[150:153], v[158:161], v[56:59]
	v_mfma_f32_16x16x32_bf16 v[52:55], v[138:141], v[166:169], v[52:55]
	v_mfma_f32_16x16x32_bf16 v[44:47], v[150:153], v[166:169], v[44:47]
	v_mfma_f32_16x16x32_bf16 v[36:39], v[138:141], v[184:187], v[36:39]
	v_mfma_f32_16x16x32_bf16 v[28:31], v[150:153], v[184:187], v[28:31]
	v_mfma_f32_16x16x32_bf16 v[20:23], v[138:141], v[192:195], v[20:23]
	v_mfma_f32_16x16x32_bf16 v[12:15], v[150:153], v[192:195], v[12:15]
	v_mfma_f32_16x16x32_bf16 v[60:63], v[146:149], v[162:165], v[60:63]
	v_mfma_f32_16x16x32_bf16 v[56:59], v[154:157], v[162:165], v[56:59]
	v_mfma_f32_16x16x32_bf16 v[52:55], v[146:149], v[180:183], v[52:55]
	v_mfma_f32_16x16x32_bf16 v[44:47], v[154:157], v[180:183], v[44:47]
	v_mfma_f32_16x16x32_bf16 v[36:39], v[146:149], v[188:191], v[36:39]
	v_mfma_f32_16x16x32_bf16 v[28:31], v[154:157], v[188:191], v[28:31]
	v_mfma_f32_16x16x32_bf16 v[20:23], v[146:149], v[196:199], v[20:23]
	v_mfma_f32_16x16x32_bf16 v[12:15], v[154:157], v[196:199], v[12:15]
	s_setprio 0
	s_barrier
	s_add_u32 s50, s50, 0x80080
	s_addc_u32 s51, s51, 0
	s_add_i32 s26, s27, s56
	v_lshl_add_u64 v[138:139], s[50:51], 0, v[172:173]
	s_mov_b32 m0, s26
	s_nop 0
	global_load_lds_dwordx4 v[138:139], off
	v_lshl_add_u64 v[138:139], s[50:51], 0, v[128:129]
	s_add_i32 m0, s26, 0x2000
	s_nop 0
	global_load_lds_dwordx4 v[138:139], off
	s_waitcnt vmcnt(6)
	s_barrier
	s_setprio 1
	v_mfma_f32_16x16x32_bf16 v[48:51], v[200:203], v[158:161], v[48:51]
	v_mfma_f32_16x16x32_bf16 v[40:43], v[208:211], v[158:161], v[40:43]
	v_mfma_f32_16x16x32_bf16 v[32:35], v[200:203], v[166:169], v[32:35]
	v_mfma_f32_16x16x32_bf16 v[24:27], v[208:211], v[166:169], v[24:27]
	v_mfma_f32_16x16x32_bf16 v[16:19], v[200:203], v[184:187], v[16:19]
	v_mfma_f32_16x16x32_bf16 v[8:11], v[208:211], v[184:187], v[8:11]
	v_mfma_f32_16x16x32_bf16 v[4:7], v[200:203], v[192:195], v[4:7]
	v_mfma_f32_16x16x32_bf16 v[0:3], v[208:211], v[192:195], v[0:3]
	v_mfma_f32_16x16x32_bf16 v[48:51], v[204:207], v[162:165], v[48:51]
	v_mfma_f32_16x16x32_bf16 v[40:43], v[212:215], v[162:165], v[40:43]
	v_mfma_f32_16x16x32_bf16 v[32:35], v[204:207], v[180:183], v[32:35]
	v_mfma_f32_16x16x32_bf16 v[24:27], v[212:215], v[180:183], v[24:27]
	v_mfma_f32_16x16x32_bf16 v[16:19], v[204:207], v[188:191], v[16:19]
	v_mfma_f32_16x16x32_bf16 v[8:11], v[212:215], v[188:191], v[8:11]
	v_mfma_f32_16x16x32_bf16 v[4:7], v[204:207], v[196:199], v[4:7]
	v_mfma_f32_16x16x32_bf16 v[0:3], v[212:215], v[196:199], v[0:3]
	s_setprio 0
	s_add_i32 s29, s29, 2
	s_add_u32 s48, s48, 0x100
	s_addc_u32 s49, s49, 0
	s_add_u32 s41, s41, 0x100
	s_addc_u32 s28, s28, 0
	s_cmp_gt_u32 s29, 29
	s_barrier
	s_cbranch_scc0 .LBB0_539
; __device__ __forceinline__ unsigned cvt_pk_bf16(float lo, float hi) { unsigned r; asm volatile("v_cvt_pk_bf16_f32 %0, %1, %2" : "=v"(r) : "v"(lo), "v"(hi)); return r; }
; #define PG8_WAIT_V(n) asm volatile("s_waitcnt vmcnt(" #n ")" ::: "memory")
; #define PG8_BAR __builtin_amdgcn_s_barrier()
; template <class Epi, class Sched>
; __device__ __forceinline__ void gemm_phase(PG8_LAS unsigned char* lds, const Gemm g, const Sched& S, const Epi& E) {
;     ...
;     PG8_WAIT_V(0);
;     if (wr == 0) PG8_BAR;
;     __device__ __forceinline__ void operator()(const f32x4 (&acc)[2][2][4][2], const pg8::Unit& u, int wr, int wc, int fr, int fq) const {
;         const int row0 = u.pm * 256 + wr * 64 + fr, col0 = u.pn * 256 + wc * 32 + 8 * fq;
; #pragma unroll
;         for (int ai = 0; ai < 2; ++ai)
; #pragma unroll
;             for (int m = 0; m < 4; ++m) {
;                 bf16_t* rowp = O + (size_t)(row0 + ai * 128 + m * 16) * ldc + col0;
; #pragma unroll
;                 for (int bj = 0; bj < 2; ++bj) { const f32x4 v0 = acc[ai][bj][m][0], v1 = acc[ai][bj][m][1];
;                     u32x4 w; w.x = cvt_pk_bf16(v0[0], v0[1]); w.y = cvt_pk_bf16(v0[2], v0[3]); w.z = cvt_pk_bf16(v1[0], v1[1]); w.w = cvt_pk_bf16(v1[2], v1[3]);
;                     *(u32x4*)(rowp + bj * 128) = w; }
;             }
;     }
	v_lshl_or_b32 v140, s8, 8, v144
	v_readlane_b32 s8, v254, 50
	v_readlane_b32 s9, v254, 51
	v_lshl_add_u32 v148, s55, 8, v142
	v_ashrrev_i32_e32 v141, 31, v140
	v_mov_b64_e32 v[138:139], s[8:9]
	v_mad_i64_i32 v[146:147], s[8:9], v148, s11, v[138:139]
	v_lshlrev_b64 v[140:141], 1, v[140:141]
	v_lshl_add_u64 v[146:147], v[146:147], 0, v[140:141]
	v_cvt_pk_bf16_f32 v124, v124, v125
	v_cvt_pk_bf16_f32 v125, v126, v127
	v_cvt_pk_bf16_f32 v126, v120, v121
	v_cvt_pk_bf16_f32 v127, v122, v123
	global_store_dwordx4 v[146:147], v[124:127], off sc1
	v_cvt_pk_bf16_f32 v112, v112, v113
	v_cvt_pk_bf16_f32 v113, v114, v115
	v_cvt_pk_bf16_f32 v114, v104, v105
	v_or_b32_e32 v104, 16, v148
	v_mad_i64_i32 v[104:105], s[8:9], v104, s11, v[138:139]
	v_cvt_pk_bf16_f32 v115, v106, v107
	global_store_dwordx4 v[146:147], v[112:115], off offset:256 sc1
	s_mov_b32 s55, s42
	s_mov_b64 s[50:51], s[46:47]
	v_lshl_add_u64 v[112:113], v[104:105], 0, v[140:141]
	v_cvt_pk_bf16_f32 v104, v116, v117
	v_cvt_pk_bf16_f32 v105, v118, v119
	v_cvt_pk_bf16_f32 v106, v108, v109
	v_cvt_pk_bf16_f32 v107, v110, v111
	global_store_dwordx4 v[112:113], v[104:107], off sc1
	v_cvt_pk_bf16_f32 v96, v96, v97
	v_cvt_pk_bf16_f32 v97, v98, v99
	v_cvt_pk_bf16_f32 v98, v88, v89
	v_or_b32_e32 v88, 32, v148
	v_mad_i64_i32 v[88:89], s[8:9], v88, s11, v[138:139]
	v_cvt_pk_bf16_f32 v99, v90, v91
	global_store_dwordx4 v[112:113], v[96:99], off offset:256 sc1
	s_mov_b64 s[48:49], s[44:45]
	s_nop 0
	v_lshl_add_u64 v[96:97], v[88:89], 0, v[140:141]
	v_cvt_pk_bf16_f32 v88, v100, v101
	v_cvt_pk_bf16_f32 v89, v102, v103
	v_cvt_pk_bf16_f32 v90, v92, v93
	v_cvt_pk_bf16_f32 v91, v94, v95
	global_store_dwordx4 v[96:97], v[88:91], off sc1
	v_cvt_pk_bf16_f32 v80, v80, v81
	v_cvt_pk_bf16_f32 v81, v82, v83
	v_cvt_pk_bf16_f32 v82, v72, v73
	v_or_b32_e32 v72, 48, v148
	v_mad_i64_i32 v[72:73], s[8:9], v72, s11, v[138:139]
	v_cvt_pk_bf16_f32 v83, v74, v75
	global_store_dwordx4 v[96:97], v[80:83], off offset:256 sc1
	s_nop 1
	v_lshl_add_u64 v[80:81], v[72:73], 0, v[140:141]
	v_cvt_pk_bf16_f32 v72, v84, v85
	v_cvt_pk_bf16_f32 v73, v86, v87
	v_cvt_pk_bf16_f32 v74, v76, v77
	v_cvt_pk_bf16_f32 v75, v78, v79
	global_store_dwordx4 v[80:81], v[72:75], off sc1
	v_cvt_pk_bf16_f32 v68, v68, v69
	v_cvt_pk_bf16_f32 v69, v70, v71
	v_cvt_pk_bf16_f32 v70, v64, v65
	v_add_u32_e32 v64, 0x80, v148
	v_mad_i64_i32 v[64:65], s[8:9], v64, s11, v[138:139]
	v_lshl_add_u64 v[64:65], v[64:65], 0, v[140:141]
	v_cvt_pk_bf16_f32 v71, v66, v67
	global_store_dwordx4 v[80:81], v[68:71], off offset:256 sc1
	v_cvt_pk_bf16_f32 v60, v60, v61
	v_cvt_pk_bf16_f32 v61, v62, v63
	v_cvt_pk_bf16_f32 v62, v56, v57
	v_cvt_pk_bf16_f32 v63, v58, v59
	global_store_dwordx4 v[64:65], v[60:63], off sc1
	v_cvt_pk_bf16_f32 v48, v48, v49
	v_cvt_pk_bf16_f32 v49, v50, v51
	v_cvt_pk_bf16_f32 v50, v40, v41
	v_add_u32_e32 v40, 0x90, v148
	v_mad_i64_i32 v[40:41], s[8:9], v40, s11, v[138:139]
	v_cvt_pk_bf16_f32 v51, v42, v43
	global_store_dwordx4 v[64:65], v[48:51], off offset:256 sc1
	s_nop 1
	v_lshl_add_u64 v[48:49], v[40:41], 0, v[140:141]
	v_cvt_pk_bf16_f32 v40, v52, v53
	v_cvt_pk_bf16_f32 v41, v54, v55
	v_cvt_pk_bf16_f32 v42, v44, v45
	v_cvt_pk_bf16_f32 v43, v46, v47
	global_store_dwordx4 v[48:49], v[40:43], off sc1
	v_cvt_pk_bf16_f32 v32, v32, v33
	v_cvt_pk_bf16_f32 v33, v34, v35
	v_cvt_pk_bf16_f32 v34, v24, v25
	v_add_u32_e32 v24, 0xa0, v148
	v_mad_i64_i32 v[24:25], s[8:9], v24, s11, v[138:139]
	v_cvt_pk_bf16_f32 v35, v26, v27
	global_store_dwordx4 v[48:49], v[32:35], off offset:256 sc1
	s_nop 1
	v_lshl_add_u64 v[32:33], v[24:25], 0, v[140:141]
	v_cvt_pk_bf16_f32 v24, v36, v37
	v_cvt_pk_bf16_f32 v25, v38, v39
	v_cvt_pk_bf16_f32 v26, v28, v29
	v_cvt_pk_bf16_f32 v27, v30, v31
	global_store_dwordx4 v[32:33], v[24:27], off sc1
	v_cvt_pk_bf16_f32 v16, v16, v17
	v_cvt_pk_bf16_f32 v17, v18, v19
	v_cvt_pk_bf16_f32 v18, v8, v9
	v_add_u32_e32 v8, 0xb0, v148
	v_mad_i64_i32 v[8:9], s[8:9], v8, s11, v[138:139]
	v_readlane_b32 s8, v255, 52
	v_readlane_b32 s9, v255, 53
	v_cvt_pk_bf16_f32 v19, v10, v11
	global_store_dwordx4 v[32:33], v[16:19], off offset:256 sc1
	s_and_b64 vcc, exec, s[8:9]
	s_mov_b32 s8, s0
	v_lshl_add_u64 v[16:17], v[8:9], 0, v[140:141]
	v_cvt_pk_bf16_f32 v8, v20, v21
	v_cvt_pk_bf16_f32 v9, v22, v23
	v_cvt_pk_bf16_f32 v10, v12, v13
	v_cvt_pk_bf16_f32 v11, v14, v15
	global_store_dwordx4 v[16:17], v[8:11], off sc1
	v_cvt_pk_bf16_f32 v4, v4, v5
	v_cvt_pk_bf16_f32 v5, v6, v7
	v_cvt_pk_bf16_f32 v6, v0, v1
	v_cvt_pk_bf16_f32 v7, v2, v3
	global_store_dwordx4 v[16:17], v[4:7], off offset:256 sc1
	s_cbranch_vccz .LBB0_536
	s_waitcnt vmcnt(0)
	v_readlane_b32 s0, v255, 44
	s_cmpk_gt_u32 s0, 0xff
	s_cbranch_scc1 .LBB0_543
	s_barrier

; __device__ __forceinline__ u32x2 pack4h(f32x4 v) { const h16x4 h = __builtin_convertvector(v, h16x4); return __builtin_bit_cast(u32x2, h); }
; __device__ __forceinline__ f32x4 unpack4h(u32x2 w) { return __builtin_convertvector(__builtin_bit_cast(h16x4, w), f32x4); }
;     __device__ __forceinline__ void operator()(const f32x4 (&acc)[2][2][4][2], const pg8::Unit& u, int wr, int wc, int fr_, int fq_) const {
;     ...
;             for (int bj = 0; bj < 2; ++bj) {
;                 f32x4 gv[2], bv[2];
; #pragma unroll
;                 for (int n = 0; n < 2; ++n) { gv[n] = *(const f32x4*)(gb + col0 + bj * 128 + 4 * n); bv[n] = *(const f32x4*)(gb + DM + col0 + bj * 128 + 4 * n); }
;                 u32x4 r[2][4]; float mu[2][4], rs[2][4];
; #pragma unroll
;                 for (int ai = 0; ai < 2; ++ai)
; #pragma unroll
;                     for (int m = 0; m < 4; ++m) { const int row = row0 + ai * 128 + m * 16; const unsigned off = (unsigned)row * DM + (unsigned)(col0 + bj * 128);
;                         { const float2 ms = *(const float2*)(st + 2u * (unsigned)row); mu[ai][m] = ms.x; rs[ai][m] = ms.y; }
;                         r[ai][m] = *(const u32x4*)(Z + off); }
;                 asm volatile("" ::: "memory");
; #pragma unroll
;                 for (int ai = 0; ai < 2; ++ai)
; #pragma unroll
;                     for (int m = 0; m < 4; ++m) { const unsigned off = (unsigned)(row0 + ai * 128 + m * 16) * DM + (unsigned)(col0 + bj * 128);
;                         u32x2 lo, hi; lo.x = r[ai][m].x; lo.y = r[ai][m].y; hi.x = r[ai][m].z; hi.y = r[ai][m].w;
;                         const f32x4 x0 = (unpack4h(lo) - mu[ai][m]) * rs[ai][m] * gv[0] + bv[0], x1 = (unpack4h(hi) - mu[ai][m]) * rs[ai][m] * gv[1] + bv[1];
;                         const u32x2 o0 = pack4h(x0 * ALPHA + acc[ai][bj][m][0] * s), o1 = pack4h(x1 * ALPHA + acc[ai][bj][m][1] * s);
;                         u32x4 w; w.x = o0.x; w.y = o0.y; w.z = o1.x; w.w = o1.y; *(u32x4*)(Z + off) = w; }
.LBB0_587:
	v_lshlrev_b32_e32 v221, 11, v138
	v_readlane_b32 s26, v253, 22
	v_add_u32_e32 v186, v221, v184
	v_mov_b32_e32 v187, v173
	v_readlane_b32 s27, v253, 23
	v_readlane_b32 s28, v253, 24
	v_lshlrev_b32_e32 v172, 1, v138
	v_lshl_add_u64 v[176:177], v[186:187], 1, s[26:27]
	global_load_dwordx4 v[228:231], v[176:177], off
	v_readlane_b32 s29, v253, 25
	v_readlane_b32 s44, v253, 29
	v_lshlrev_b64 v[128:129], 2, v[184:185]
	v_lshl_add_u64 v[188:189], v[172:173], 2, s[28:29]
	v_readlane_b32 s45, v253, 30
	global_load_dwordx2 v[178:179], v[188:189], off
	v_lshlrev_b32_e32 v185, 11, v156
	v_lshl_add_u64 v[190:191], s[44:45], 0, v[128:129]
	v_readlane_b32 s44, v253, 31
	v_readlane_b32 s45, v253, 32
	v_lshlrev_b32_e32 v172, 1, v156
	v_mov_b32_e32 v159, v173
	v_lshl_add_u64 v[192:193], s[44:45], 0, v[128:129]
	global_load_dwordx4 v[136:139], v[192:193], off
	global_load_dwordx4 v[140:143], v[190:191], off
	global_load_dwordx4 v[128:131], v[190:191], off offset:16
	global_load_dwordx4 v[132:135], v[192:193], off offset:16
	v_add_u32_e32 v158, v185, v184
	v_lshl_add_u64 v[194:195], v[172:173], 2, s[28:29]
	v_lshl_add_u64 v[158:159], v[158:159], 1, s[26:27]
	global_load_dwordx2 v[232:233], v[194:195], off
	global_load_dwordx4 v[242:245], v[158:159], off
	v_lshlrev_b32_e32 v187, 11, v154
	v_lshlrev_b32_e32 v172, 1, v154
	v_mov_b32_e32 v157, v173
	v_add_u32_e32 v156, v187, v184
	v_lshl_add_u64 v[202:203], v[172:173], 2, s[28:29]
	v_lshl_add_u64 v[154:155], v[156:157], 1, s[26:27]
	global_load_dwordx2 v[250:251], v[202:203], off
	global_load_dwordx4 v[246:249], v[154:155], off
	v_lshlrev_b32_e32 v222, 11, v152
	v_lshlrev_b32_e32 v223, 11, v150
	v_lshlrev_b32_e32 v172, 1, v152
	v_mov_b32_e32 v161, v173
	v_mov_b32_e32 v163, v173
	v_add_u32_e32 v160, v222, v184
	v_add_u32_e32 v162, v223, v184
	v_lshl_add_u64 v[204:205], v[172:173], 2, s[28:29]
	v_lshl_add_u64 v[156:157], v[160:161], 1, s[26:27]
	v_lshl_add_u64 v[200:201], v[162:163], 1, s[26:27]
	global_load_dwordx2 v[216:217], v[204:205], off
	global_load_dwordx4 v[160:163], v[156:157], off
	v_lshlrev_b32_e32 v224, 11, v148
	v_mov_b32_e32 v197, v173
	v_lshlrev_b32_e32 v225, 11, v146
	v_add_u32_e32 v196, v224, v184
	v_lshlrev_b32_e32 v172, 1, v150
	v_mov_b32_e32 v159, v173
	v_add_u32_e32 v158, v225, v184
	v_lshl_add_u64 v[206:207], v[196:197], 1, s[26:27]
	v_lshl_add_u64 v[196:197], v[172:173], 2, s[28:29]
	v_lshl_add_u64 v[208:209], v[158:159], 1, s[26:27]
	global_load_dwordx2 v[214:215], v[196:197], off
	global_load_dwordx4 v[156:159], v[200:201], off
	v_lshlrev_b32_e32 v226, 11, v144
	v_mov_b32_e32 v199, v173
	v_add_u32_e32 v198, v226, v184
	v_lshlrev_b32_e32 v172, 1, v148
	v_lshl_add_u64 v[240:241], v[198:199], 1, s[26:27]
	v_lshl_add_u64 v[198:199], v[172:173], 2, s[28:29]
	global_load_dwordx2 v[212:213], v[198:199], off
	global_load_dwordx4 v[152:155], v[206:207], off
	v_lshlrev_b32_e32 v172, 1, v146
	v_lshl_add_u64 v[200:201], v[172:173], 2, s[28:29]
	global_load_dwordx2 v[210:211], v[200:201], off
	global_load_dwordx4 v[148:151], v[208:209], off
	v_lshlrev_b32_e32 v172, 1, v144
	v_lshl_add_u64 v[206:207], v[172:173], 2, s[28:29]
	global_load_dwordx2 v[208:209], v[206:207], off
	global_load_dwordx4 v[144:147], v[240:241], off
	s_waitcnt vmcnt(0)
	v_cvt_f32_f16_sdwa v172, v229 dst_sel:DWORD dst_unused:UNUSED_PAD src0_sel:WORD_1
	v_cvt_f32_f16_e32 v227, v229
	v_cvt_f32_f16_sdwa v229, v228 dst_sel:DWORD dst_unused:UNUSED_PAD src0_sel:WORD_1
	v_cvt_f32_f16_e32 v228, v228
	v_cvt_f32_f16_sdwa v237, v231 dst_sel:DWORD dst_unused:UNUSED_PAD src0_sel:WORD_1
	v_cvt_f32_f16_e32 v236, v231
	v_cvt_f32_f16_sdwa v241, v230 dst_sel:DWORD dst_unused:UNUSED_PAD src0_sel:WORD_1
	v_cvt_f32_f16_e32 v240, v230
	v_sub_f32_e32 v228, v228, v178
	v_sub_f32_e32 v229, v229, v178
	v_sub_f32_e32 v230, v227, v178
	v_sub_f32_e32 v231, v172, v178
	v_sub_f32_e32 v240, v240, v178
	v_sub_f32_e32 v241, v241, v178
	v_pk_mul_f32 v[230:231], v[178:179], v[230:231] op_sel:[1,0]
	v_pk_mul_f32 v[228:229], v[178:179], v[228:229] op_sel:[1,0]
	v_sub_f32_e32 v236, v236, v178
	v_sub_f32_e32 v237, v237, v178
	v_pk_fma_f32 v[228:229], v[140:141], v[228:229], v[136:137]
	v_pk_fma_f32 v[230:231], v[142:143], v[230:231], v[138:139]
	v_pk_mul_f32 v[236:237], v[178:179], v[236:237] op_sel:[1,0]
	v_pk_mul_f32 v[178:179], v[178:179], v[240:241] op_sel:[1,0]
	v_pk_fma_f32 v[236:237], v[130:131], v[236:237], v[134:135]
	v_pk_fma_f32 v[178:179], v[128:129], v[178:179], v[132:133]
	v_pk_mul_f32 v[230:231], v[230:231], s[36:37] op_sel_hi:[1,0]
	v_pk_mul_f32 v[228:229], v[228:229], s[36:37] op_sel_hi:[1,0]
	v_pk_mul_f32 v[178:179], v[178:179], s[36:37] op_sel_hi:[1,0]
	v_pk_fma_f32 v[228:229], v[124:125], 0.5, v[228:229] op_sel_hi:[1,0,1]
	v_pk_fma_f32 v[124:125], v[126:127], 0.5, v[230:231] op_sel_hi:[1,0,1]
	v_pk_mul_f32 v[126:127], v[236:237], s[36:37] op_sel_hi:[1,0]
	v_pk_fma_f32 v[120:121], v[120:121], 0.5, v[178:179] op_sel_hi:[1,0,1]
	v_pk_fma_f32 v[122:123], v[122:123], 0.5, v[126:127] op_sel_hi:[1,0,1]
	v_cvt_pk_f16_f32 v126, v120, v121
	v_cvt_pk_f16_f32 v127, v122, v123
	v_cvt_f32_f16_e32 v120, v242
	v_cvt_f32_f16_sdwa v121, v242 dst_sel:DWORD dst_unused:UNUSED_PAD src0_sel:WORD_1
	v_cvt_f32_f16_e32 v122, v243
	v_cvt_f32_f16_sdwa v123, v243 dst_sel:DWORD dst_unused:UNUSED_PAD src0_sel:WORD_1
	v_cvt_pk_f16_f32 v125, v124, v125
	v_cvt_pk_f16_f32 v124, v228, v229
	global_store_dwordx4 v[176:177], v[124:127], off sc1
	v_sub_f32_e32 v120, v120, v232
	v_sub_f32_e32 v121, v121, v232
	v_cvt_f32_f16_e32 v124, v244
	v_cvt_f32_f16_sdwa v125, v244 dst_sel:DWORD dst_unused:UNUSED_PAD src0_sel:WORD_1
	v_cvt_f32_f16_e32 v126, v245
; __device__ __forceinline__ u32x2 pack4h(f32x4 v) { const h16x4 h = __builtin_convertvector(v, h16x4); return __builtin_bit_cast(u32x2, h); }
; __device__ __forceinline__ f32x4 unpack4h(u32x2 w) { return __builtin_convertvector(__builtin_bit_cast(h16x4, w), f32x4); }
;     __device__ __forceinline__ void operator()(const f32x4 (&acc)[2][2][4][2], const pg8::Unit& u, int wr, int wc, int fr_, int fq_) const {
;     ...
; #pragma unroll
;                 for (int ai = 0; ai < 2; ++ai)
; #pragma unroll
;                     for (int m = 0; m < 4; ++m) { const unsigned off = (unsigned)(row0 + ai * 128 + m * 16) * DM + (unsigned)(col0 + bj * 128);
;                         u32x2 lo, hi; lo.x = r[ai][m].x; lo.y = r[ai][m].y; hi.x = r[ai][m].z; hi.y = r[ai][m].w;
;                         const f32x4 x0 = (unpack4h(lo) - mu[ai][m]) * rs[ai][m] * gv[0] + bv[0], x1 = (unpack4h(hi) - mu[ai][m]) * rs[ai][m] * gv[1] + bv[1];
;                         const u32x2 o0 = pack4h(x0 * ALPHA + acc[ai][bj][m][0] * s), o1 = pack4h(x1 * ALPHA + acc[ai][bj][m][1] * s);
;                         u32x4 w; w.x = o0.x; w.y = o0.y; w.z = o1.x; w.w = o1.y; *(u32x4*)(Z + off) = w; }
	v_cvt_f32_f16_sdwa v127, v245 dst_sel:DWORD dst_unused:UNUSED_PAD src0_sel:WORD_1
	v_sub_f32_e32 v122, v122, v232
	v_sub_f32_e32 v123, v123, v232
	v_pk_mul_f32 v[122:123], v[232:233], v[122:123] op_sel:[1,0]
	v_pk_mul_f32 v[120:121], v[232:233], v[120:121] op_sel:[1,0]
	v_pk_fma_f32 v[122:123], v[142:143], v[122:123], v[138:139]
	v_pk_fma_f32 v[120:121], v[140:141], v[120:121], v[136:137]
	v_sub_f32_e32 v124, v124, v232
	v_sub_f32_e32 v125, v125, v232
	v_sub_f32_e32 v126, v126, v232
	v_sub_f32_e32 v127, v127, v232
	v_pk_mul_f32 v[126:127], v[232:233], v[126:127] op_sel:[1,0]
	v_pk_mul_f32 v[124:125], v[232:233], v[124:125] op_sel:[1,0]
	v_pk_mul_f32 v[122:123], v[122:123], s[36:37] op_sel_hi:[1,0]
	v_pk_mul_f32 v[120:121], v[120:121], s[36:37] op_sel_hi:[1,0]
	v_pk_fma_f32 v[124:125], v[128:129], v[124:125], v[132:133]
	v_pk_fma_f32 v[126:127], v[130:131], v[126:127], v[134:135]
	v_pk_fma_f32 v[120:121], v[116:117], 0.5, v[120:121] op_sel_hi:[1,0,1]
	v_pk_fma_f32 v[116:117], v[118:119], 0.5, v[122:123] op_sel_hi:[1,0,1]
	v_pk_mul_f32 v[118:119], v[126:127], s[36:37] op_sel_hi:[1,0]
	v_cvt_pk_f16_f32 v117, v116, v117
	v_cvt_pk_f16_f32 v116, v120, v121
	v_pk_mul_f32 v[120:121], v[124:125], s[36:37] op_sel_hi:[1,0]
	v_add_u32_e32 v172, 0x8000, v186
	v_pk_fma_f32 v[112:113], v[112:113], 0.5, v[120:121] op_sel_hi:[1,0,1]
	v_pk_fma_f32 v[114:115], v[114:115], 0.5, v[118:119] op_sel_hi:[1,0,1]
	v_cvt_pk_f16_f32 v118, v112, v113
	v_cvt_pk_f16_f32 v119, v114, v115
	v_lshl_add_u64 v[112:113], v[172:173], 1, s[26:27]
	global_store_dwordx4 v[112:113], v[116:119], off sc1
	v_cvt_f32_f16_e32 v112, v246
	v_cvt_f32_f16_sdwa v113, v246 dst_sel:DWORD dst_unused:UNUSED_PAD src0_sel:WORD_1
	v_cvt_f32_f16_e32 v114, v247
	v_cvt_f32_f16_sdwa v115, v247 dst_sel:DWORD dst_unused:UNUSED_PAD src0_sel:WORD_1
	v_cvt_f32_f16_e32 v116, v248
	v_cvt_f32_f16_sdwa v117, v248 dst_sel:DWORD dst_unused:UNUSED_PAD src0_sel:WORD_1
	v_cvt_f32_f16_e32 v118, v249
	v_cvt_f32_f16_sdwa v119, v249 dst_sel:DWORD dst_unused:UNUSED_PAD src0_sel:WORD_1
	v_sub_f32_e32 v112, v112, v250
	v_sub_f32_e32 v113, v113, v250
	v_sub_f32_e32 v114, v114, v250
	v_sub_f32_e32 v115, v115, v250
	v_pk_mul_f32 v[114:115], v[250:251], v[114:115] op_sel:[1,0]
	v_pk_mul_f32 v[112:113], v[250:251], v[112:113] op_sel:[1,0]
	v_pk_fma_f32 v[114:115], v[142:143], v[114:115], v[138:139]
	v_pk_fma_f32 v[112:113], v[140:141], v[112:113], v[136:137]
	v_sub_f32_e32 v116, v116, v250
	v_sub_f32_e32 v117, v117, v250
	v_sub_f32_e32 v118, v118, v250
	v_sub_f32_e32 v119, v119, v250
	v_pk_mul_f32 v[118:119], v[250:251], v[118:119] op_sel:[1,0]
	v_pk_mul_f32 v[116:117], v[250:251], v[116:117] op_sel:[1,0]
	v_pk_mul_f32 v[114:115], v[114:115], s[36:37] op_sel_hi:[1,0]
	v_pk_mul_f32 v[112:113], v[112:113], s[36:37] op_sel_hi:[1,0]
	v_pk_fma_f32 v[116:117], v[128:129], v[116:117], v[132:133]
	v_pk_fma_f32 v[118:119], v[130:131], v[118:119], v[134:135]
	v_pk_fma_f32 v[112:113], v[108:109], 0.5, v[112:113] op_sel_hi:[1,0,1]
	v_pk_fma_f32 v[108:109], v[110:111], 0.5, v[114:115] op_sel_hi:[1,0,1]
	v_pk_mul_f32 v[110:111], v[118:119], s[36:37] op_sel_hi:[1,0]
	v_cvt_pk_f16_f32 v109, v108, v109
	v_cvt_pk_f16_f32 v108, v112, v113
	v_pk_mul_f32 v[112:113], v[116:117], s[36:37] op_sel_hi:[1,0]
	v_add_u32_e32 v172, 0x10000, v186
	v_pk_fma_f32 v[104:105], v[104:105], 0.5, v[112:113] op_sel_hi:[1,0,1]
	v_pk_fma_f32 v[106:107], v[106:107], 0.5, v[110:111] op_sel_hi:[1,0,1]
	v_cvt_pk_f16_f32 v110, v104, v105
	v_cvt_pk_f16_f32 v111, v106, v107
	v_lshl_add_u64 v[104:105], v[172:173], 1, s[26:27]
	global_store_dwordx4 v[104:105], v[108:111], off sc1
	v_cvt_f32_f16_e32 v104, v160
	v_cvt_f32_f16_sdwa v105, v160 dst_sel:DWORD dst_unused:UNUSED_PAD src0_sel:WORD_1
	v_cvt_f32_f16_e32 v106, v161
	v_cvt_f32_f16_sdwa v107, v161 dst_sel:DWORD dst_unused:UNUSED_PAD src0_sel:WORD_1
	v_cvt_f32_f16_e32 v108, v162
	v_cvt_f32_f16_sdwa v109, v162 dst_sel:DWORD dst_unused:UNUSED_PAD src0_sel:WORD_1
	v_cvt_f32_f16_e32 v110, v163
	v_cvt_f32_f16_sdwa v111, v163 dst_sel:DWORD dst_unused:UNUSED_PAD src0_sel:WORD_1
	v_sub_f32_e32 v104, v104, v216
	v_sub_f32_e32 v105, v105, v216
	v_sub_f32_e32 v106, v106, v216
	v_sub_f32_e32 v107, v107, v216
	v_pk_mul_f32 v[106:107], v[216:217], v[106:107] op_sel:[1,0]
	v_pk_mul_f32 v[104:105], v[216:217], v[104:105] op_sel:[1,0]
	v_pk_fma_f32 v[106:107], v[142:143], v[106:107], v[138:139]
	v_pk_fma_f32 v[104:105], v[140:141], v[104:105], v[136:137]
	v_sub_f32_e32 v108, v108, v216
	v_sub_f32_e32 v109, v109, v216
	v_sub_f32_e32 v110, v110, v216
	v_sub_f32_e32 v111, v111, v216
	v_pk_mul_f32 v[110:111], v[216:217], v[110:111] op_sel:[1,0]
	v_pk_mul_f32 v[108:109], v[216:217], v[108:109] op_sel:[1,0]
	v_pk_mul_f32 v[106:107], v[106:107], s[36:37] op_sel_hi:[1,0]
	v_pk_mul_f32 v[104:105], v[104:105], s[36:37] op_sel_hi:[1,0]
	v_pk_fma_f32 v[108:109], v[128:129], v[108:109], v[132:133]
	v_pk_fma_f32 v[110:111], v[130:131], v[110:111], v[134:135]
	v_pk_fma_f32 v[104:105], v[100:101], 0.5, v[104:105] op_sel_hi:[1,0,1]
	v_pk_fma_f32 v[100:101], v[102:103], 0.5, v[106:107] op_sel_hi:[1,0,1]
	v_pk_mul_f32 v[102:103], v[110:111], s[36:37] op_sel_hi:[1,0]
	v_cvt_pk_f16_f32 v101, v100, v101
	v_cvt_pk_f16_f32 v100, v104, v105
	v_pk_mul_f32 v[104:105], v[108:109], s[36:37] op_sel_hi:[1,0]
	v_add_u32_e32 v172, 0x18000, v186
	v_pk_fma_f32 v[96:97], v[96:97], 0.5, v[104:105] op_sel_hi:[1,0,1]
	v_pk_fma_f32 v[98:99], v[98:99], 0.5, v[102:103] op_sel_hi:[1,0,1]
	v_cvt_pk_f16_f32 v102, v96, v97
	v_cvt_pk_f16_f32 v103, v98, v99
	v_lshl_add_u64 v[96:97], v[172:173], 1, s[26:27]
	global_store_dwordx4 v[96:97], v[100:103], off sc1
	v_cvt_f32_f16_e32 v96, v156
; __device__ __forceinline__ u32x2 pack4h(f32x4 v) { const h16x4 h = __builtin_convertvector(v, h16x4); return __builtin_bit_cast(u32x2, h); }
; __device__ __forceinline__ f32x4 unpack4h(u32x2 w) { return __builtin_convertvector(__builtin_bit_cast(h16x4, w), f32x4); }
;     __device__ __forceinline__ void operator()(const f32x4 (&acc)[2][2][4][2], const pg8::Unit& u, int wr, int wc, int fr_, int fq_) const {
;     ...
; #pragma unroll
;                 for (int ai = 0; ai < 2; ++ai)
; #pragma unroll
;                     for (int m = 0; m < 4; ++m) { const unsigned off = (unsigned)(row0 + ai * 128 + m * 16) * DM + (unsigned)(col0 + bj * 128);
;                         u32x2 lo, hi; lo.x = r[ai][m].x; lo.y = r[ai][m].y; hi.x = r[ai][m].z; hi.y = r[ai][m].w;
;                         const f32x4 x0 = (unpack4h(lo) - mu[ai][m]) * rs[ai][m] * gv[0] + bv[0], x1 = (unpack4h(hi) - mu[ai][m]) * rs[ai][m] * gv[1] + bv[1];
;                         const u32x2 o0 = pack4h(x0 * ALPHA + acc[ai][bj][m][0] * s), o1 = pack4h(x1 * ALPHA + acc[ai][bj][m][1] * s);
;                         u32x4 w; w.x = o0.x; w.y = o0.y; w.z = o1.x; w.w = o1.y; *(u32x4*)(Z + off) = w; }
	v_cvt_f32_f16_sdwa v97, v156 dst_sel:DWORD dst_unused:UNUSED_PAD src0_sel:WORD_1
	v_cvt_f32_f16_e32 v98, v157
	v_cvt_f32_f16_sdwa v99, v157 dst_sel:DWORD dst_unused:UNUSED_PAD src0_sel:WORD_1
	v_cvt_f32_f16_e32 v100, v158
	v_cvt_f32_f16_sdwa v101, v158 dst_sel:DWORD dst_unused:UNUSED_PAD src0_sel:WORD_1
	v_cvt_f32_f16_e32 v102, v159
	v_cvt_f32_f16_sdwa v103, v159 dst_sel:DWORD dst_unused:UNUSED_PAD src0_sel:WORD_1
	v_sub_f32_e32 v96, v96, v214
	v_sub_f32_e32 v97, v97, v214
	v_sub_f32_e32 v98, v98, v214
	v_sub_f32_e32 v99, v99, v214
	v_pk_mul_f32 v[98:99], v[214:215], v[98:99] op_sel:[1,0]
	v_pk_mul_f32 v[96:97], v[214:215], v[96:97] op_sel:[1,0]
	v_pk_fma_f32 v[98:99], v[142:143], v[98:99], v[138:139]
	v_pk_fma_f32 v[96:97], v[140:141], v[96:97], v[136:137]
	v_sub_f32_e32 v100, v100, v214
	v_sub_f32_e32 v101, v101, v214
	v_sub_f32_e32 v102, v102, v214
	v_sub_f32_e32 v103, v103, v214
	v_pk_mul_f32 v[102:103], v[214:215], v[102:103] op_sel:[1,0]
	v_pk_mul_f32 v[100:101], v[214:215], v[100:101] op_sel:[1,0]
	v_pk_mul_f32 v[98:99], v[98:99], s[36:37] op_sel_hi:[1,0]
	v_pk_mul_f32 v[96:97], v[96:97], s[36:37] op_sel_hi:[1,0]
	v_pk_fma_f32 v[100:101], v[128:129], v[100:101], v[132:133]
	v_pk_fma_f32 v[102:103], v[130:131], v[102:103], v[134:135]
	v_pk_fma_f32 v[96:97], v[92:93], 0.5, v[96:97] op_sel_hi:[1,0,1]
	v_pk_fma_f32 v[92:93], v[94:95], 0.5, v[98:99] op_sel_hi:[1,0,1]
	v_pk_mul_f32 v[94:95], v[102:103], s[36:37] op_sel_hi:[1,0]
	v_cvt_pk_f16_f32 v93, v92, v93
	v_cvt_pk_f16_f32 v92, v96, v97
	v_pk_mul_f32 v[96:97], v[100:101], s[36:37] op_sel_hi:[1,0]
	v_add_u32_e32 v172, 0x40000, v186
	v_pk_fma_f32 v[88:89], v[88:89], 0.5, v[96:97] op_sel_hi:[1,0,1]
	v_pk_fma_f32 v[90:91], v[90:91], 0.5, v[94:95] op_sel_hi:[1,0,1]
	v_cvt_pk_f16_f32 v94, v88, v89
	v_cvt_pk_f16_f32 v95, v90, v91
	v_lshl_add_u64 v[88:89], v[172:173], 1, s[26:27]
	global_store_dwordx4 v[88:89], v[92:95], off sc1
	v_cvt_f32_f16_e32 v88, v152
	v_cvt_f32_f16_sdwa v89, v152 dst_sel:DWORD dst_unused:UNUSED_PAD src0_sel:WORD_1
	v_cvt_f32_f16_e32 v90, v153
	v_cvt_f32_f16_sdwa v91, v153 dst_sel:DWORD dst_unused:UNUSED_PAD src0_sel:WORD_1
	v_cvt_f32_f16_e32 v92, v154
	v_cvt_f32_f16_sdwa v93, v154 dst_sel:DWORD dst_unused:UNUSED_PAD src0_sel:WORD_1
	v_cvt_f32_f16_e32 v94, v155
	v_cvt_f32_f16_sdwa v95, v155 dst_sel:DWORD dst_unused:UNUSED_PAD src0_sel:WORD_1
	v_sub_f32_e32 v88, v88, v212
	v_sub_f32_e32 v89, v89, v212
	v_sub_f32_e32 v90, v90, v212
	v_sub_f32_e32 v91, v91, v212
	v_pk_mul_f32 v[90:91], v[212:213], v[90:91] op_sel:[1,0]
	v_pk_mul_f32 v[88:89], v[212:213], v[88:89] op_sel:[1,0]
	v_pk_fma_f32 v[90:91], v[142:143], v[90:91], v[138:139]
	v_pk_fma_f32 v[88:89], v[140:141], v[88:89], v[136:137]
	v_sub_f32_e32 v92, v92, v212
	v_sub_f32_e32 v93, v93, v212
	v_sub_f32_e32 v94, v94, v212
	v_sub_f32_e32 v95, v95, v212
	v_pk_mul_f32 v[94:95], v[212:213], v[94:95] op_sel:[1,0]
	v_pk_mul_f32 v[92:93], v[212:213], v[92:93] op_sel:[1,0]
	v_pk_mul_f32 v[90:91], v[90:91], s[36:37] op_sel_hi:[1,0]
	v_pk_mul_f32 v[88:89], v[88:89], s[36:37] op_sel_hi:[1,0]
	v_pk_fma_f32 v[92:93], v[128:129], v[92:93], v[132:133]
	v_pk_fma_f32 v[94:95], v[130:131], v[94:95], v[134:135]
	v_pk_fma_f32 v[88:89], v[84:85], 0.5, v[88:89] op_sel_hi:[1,0,1]
	v_pk_fma_f32 v[84:85], v[86:87], 0.5, v[90:91] op_sel_hi:[1,0,1]
	v_pk_mul_f32 v[86:87], v[94:95], s[36:37] op_sel_hi:[1,0]
	v_cvt_pk_f16_f32 v85, v84, v85
	v_cvt_pk_f16_f32 v84, v88, v89
	v_pk_mul_f32 v[88:89], v[92:93], s[36:37] op_sel_hi:[1,0]
	v_add_u32_e32 v172, 0x48000, v186
	v_pk_fma_f32 v[80:81], v[80:81], 0.5, v[88:89] op_sel_hi:[1,0,1]
	v_pk_fma_f32 v[82:83], v[82:83], 0.5, v[86:87] op_sel_hi:[1,0,1]
	v_cvt_pk_f16_f32 v86, v80, v81
	v_cvt_pk_f16_f32 v87, v82, v83
	v_lshl_add_u64 v[80:81], v[172:173], 1, s[26:27]
	global_store_dwordx4 v[80:81], v[84:87], off sc1
	v_cvt_f32_f16_e32 v80, v148
	v_cvt_f32_f16_sdwa v81, v148 dst_sel:DWORD dst_unused:UNUSED_PAD src0_sel:WORD_1
	v_cvt_f32_f16_e32 v82, v149
	v_cvt_f32_f16_sdwa v83, v149 dst_sel:DWORD dst_unused:UNUSED_PAD src0_sel:WORD_1
	v_cvt_f32_f16_e32 v84, v150
	v_cvt_f32_f16_sdwa v85, v150 dst_sel:DWORD dst_unused:UNUSED_PAD src0_sel:WORD_1
	v_cvt_f32_f16_e32 v86, v151
	v_cvt_f32_f16_sdwa v87, v151 dst_sel:DWORD dst_unused:UNUSED_PAD src0_sel:WORD_1
	v_sub_f32_e32 v80, v80, v210
	v_sub_f32_e32 v81, v81, v210
	v_sub_f32_e32 v82, v82, v210
	v_sub_f32_e32 v83, v83, v210
	v_pk_mul_f32 v[82:83], v[210:211], v[82:83] op_sel:[1,0]
	v_pk_mul_f32 v[80:81], v[210:211], v[80:81] op_sel:[1,0]
	v_pk_fma_f32 v[82:83], v[142:143], v[82:83], v[138:139]
	v_pk_fma_f32 v[80:81], v[140:141], v[80:81], v[136:137]
	v_sub_f32_e32 v84, v84, v210
	v_sub_f32_e32 v85, v85, v210
	v_sub_f32_e32 v86, v86, v210
	v_sub_f32_e32 v87, v87, v210
	v_pk_mul_f32 v[86:87], v[210:211], v[86:87] op_sel:[1,0]
	v_pk_mul_f32 v[84:85], v[210:211], v[84:85] op_sel:[1,0]
	v_pk_mul_f32 v[82:83], v[82:83], s[36:37] op_sel_hi:[1,0]
	v_pk_mul_f32 v[80:81], v[80:81], s[36:37] op_sel_hi:[1,0]
	v_pk_fma_f32 v[84:85], v[128:129], v[84:85], v[132:133]
	v_pk_fma_f32 v[86:87], v[130:131], v[86:87], v[134:135]
	v_pk_fma_f32 v[80:81], v[76:77], 0.5, v[80:81] op_sel_hi:[1,0,1]
	v_pk_fma_f32 v[76:77], v[78:79], 0.5, v[82:83] op_sel_hi:[1,0,1]
	v_pk_mul_f32 v[78:79], v[86:87], s[36:37] op_sel_hi:[1,0]
	v_cvt_pk_f16_f32 v77, v76, v77
	v_cvt_pk_f16_f32 v76, v80, v81
	v_pk_mul_f32 v[80:81], v[84:85], s[36:37] op_sel_hi:[1,0]
	v_add_u32_e32 v172, 0x50000, v186
	v_pk_fma_f32 v[72:73], v[72:73], 0.5, v[80:81] op_sel_hi:[1,0,1]
	v_pk_fma_f32 v[74:75], v[74:75], 0.5, v[78:79] op_sel_hi:[1,0,1]
	v_cvt_pk_f16_f32 v78, v72, v73
	v_cvt_pk_f16_f32 v79, v74, v75
; __device__ __forceinline__ u32x2 pack4h(f32x4 v) { const h16x4 h = __builtin_convertvector(v, h16x4); return __builtin_bit_cast(u32x2, h); }
; __device__ __forceinline__ f32x4 unpack4h(u32x2 w) { return __builtin_convertvector(__builtin_bit_cast(h16x4, w), f32x4); }
;     __device__ __forceinline__ void operator()(const f32x4 (&acc)[2][2][4][2], const pg8::Unit& u, int wr, int wc, int fr_, int fq_) const {
;     ...
;             for (int bj = 0; bj < 2; ++bj) {
;                 f32x4 gv[2], bv[2];
; #pragma unroll
;                 for (int n = 0; n < 2; ++n) { gv[n] = *(const f32x4*)(gb + col0 + bj * 128 + 4 * n); bv[n] = *(const f32x4*)(gb + DM + col0 + bj * 128 + 4 * n); }
;                 u32x4 r[2][4]; float mu[2][4], rs[2][4];
; #pragma unroll
;                 for (int ai = 0; ai < 2; ++ai)
; #pragma unroll
;                     for (int m = 0; m < 4; ++m) { const int row = row0 + ai * 128 + m * 16; const unsigned off = (unsigned)row * DM + (unsigned)(col0 + bj * 128);
;                         { const float2 ms = *(const float2*)(st + 2u * (unsigned)row); mu[ai][m] = ms.x; rs[ai][m] = ms.y; }
;                         r[ai][m] = *(const u32x4*)(Z + off); }
;                 asm volatile("" ::: "memory");
; #pragma unroll
;                 for (int ai = 0; ai < 2; ++ai)
; #pragma unroll
;                     for (int m = 0; m < 4; ++m) { const unsigned off = (unsigned)(row0 + ai * 128 + m * 16) * DM + (unsigned)(col0 + bj * 128);
;                         u32x2 lo, hi; lo.x = r[ai][m].x; lo.y = r[ai][m].y; hi.x = r[ai][m].z; hi.y = r[ai][m].w;
;                         const f32x4 x0 = (unpack4h(lo) - mu[ai][m]) * rs[ai][m] * gv[0] + bv[0], x1 = (unpack4h(hi) - mu[ai][m]) * rs[ai][m] * gv[1] + bv[1];
;                         const u32x2 o0 = pack4h(x0 * ALPHA + acc[ai][bj][m][0] * s), o1 = pack4h(x1 * ALPHA + acc[ai][bj][m][1] * s);
;                         u32x4 w; w.x = o0.x; w.y = o0.y; w.z = o1.x; w.w = o1.y; *(u32x4*)(Z + off) = w; }
	v_lshl_add_u64 v[72:73], v[172:173], 1, s[26:27]
	global_store_dwordx4 v[72:73], v[76:79], off sc1
	v_cvt_f32_f16_e32 v72, v144
	v_cvt_f32_f16_sdwa v73, v144 dst_sel:DWORD dst_unused:UNUSED_PAD src0_sel:WORD_1
	v_cvt_f32_f16_e32 v74, v145
	v_cvt_f32_f16_sdwa v75, v145 dst_sel:DWORD dst_unused:UNUSED_PAD src0_sel:WORD_1
	v_cvt_f32_f16_e32 v76, v146
	v_cvt_f32_f16_sdwa v77, v146 dst_sel:DWORD dst_unused:UNUSED_PAD src0_sel:WORD_1
	v_cvt_f32_f16_e32 v78, v147
	v_cvt_f32_f16_sdwa v79, v147 dst_sel:DWORD dst_unused:UNUSED_PAD src0_sel:WORD_1
	v_sub_f32_e32 v72, v72, v208
	v_sub_f32_e32 v73, v73, v208
	v_sub_f32_e32 v74, v74, v208
	v_sub_f32_e32 v75, v75, v208
	v_pk_mul_f32 v[74:75], v[208:209], v[74:75] op_sel:[1,0]
	v_pk_mul_f32 v[72:73], v[208:209], v[72:73] op_sel:[1,0]
	v_pk_fma_f32 v[74:75], v[142:143], v[74:75], v[138:139]
	v_pk_fma_f32 v[72:73], v[140:141], v[72:73], v[136:137]
	v_sub_f32_e32 v76, v76, v208
	v_sub_f32_e32 v77, v77, v208
	v_sub_f32_e32 v78, v78, v208
	v_sub_f32_e32 v79, v79, v208
	v_pk_mul_f32 v[78:79], v[208:209], v[78:79] op_sel:[1,0]
	v_pk_mul_f32 v[76:77], v[208:209], v[76:77] op_sel:[1,0]
	v_pk_mul_f32 v[74:75], v[74:75], s[36:37] op_sel_hi:[1,0]
	v_pk_mul_f32 v[72:73], v[72:73], s[36:37] op_sel_hi:[1,0]
	v_pk_fma_f32 v[76:77], v[128:129], v[76:77], v[132:133]
	v_pk_fma_f32 v[78:79], v[130:131], v[78:79], v[134:135]
	v_pk_fma_f32 v[72:73], v[68:69], 0.5, v[72:73] op_sel_hi:[1,0,1]
	v_pk_fma_f32 v[68:69], v[70:71], 0.5, v[74:75] op_sel_hi:[1,0,1]
	v_pk_mul_f32 v[70:71], v[78:79], s[36:37] op_sel_hi:[1,0]
	v_cvt_pk_f16_f32 v69, v68, v69
	v_cvt_pk_f16_f32 v68, v72, v73
	v_pk_mul_f32 v[72:73], v[76:77], s[36:37] op_sel_hi:[1,0]
	v_add_u32_e32 v172, 0x58000, v186
	v_pk_fma_f32 v[64:65], v[64:65], 0.5, v[72:73] op_sel_hi:[1,0,1]
	v_pk_fma_f32 v[66:67], v[66:67], 0.5, v[70:71] op_sel_hi:[1,0,1]
	v_add_u32_e32 v84, 0x80, v184
	v_cvt_pk_f16_f32 v71, v66, v67
	v_cvt_pk_f16_f32 v70, v64, v65
	v_lshl_add_u64 v[64:65], v[172:173], 1, s[26:27]
	v_add_u32_e32 v172, v84, v221
	global_store_dwordx4 v[64:65], v[68:71], off sc1
	v_lshl_add_u64 v[64:65], v[172:173], 1, s[26:27]
	global_load_dwordx4 v[110:113], v[64:65], off
	global_load_dwordx2 v[122:123], v[188:189], off
	global_load_dwordx4 v[72:75], v[192:193], off offset:512
	global_load_dwordx4 v[76:79], v[190:191], off offset:512
	s_nop 0
	global_load_dwordx4 v[64:67], v[190:191], off offset:528
	global_load_dwordx4 v[68:71], v[192:193], off offset:528
	v_add_u32_e32 v172, v84, v185
	v_lshl_add_u64 v[80:81], v[172:173], 1, s[26:27]
	global_load_dwordx4 v[114:117], v[80:81], off
	global_load_dwordx2 v[124:125], v[194:195], off
	v_add_u32_e32 v172, v84, v187
	v_lshl_add_u64 v[80:81], v[172:173], 1, s[26:27]
	v_add_u32_e32 v172, v84, v222
	global_load_dwordx2 v[126:127], v[202:203], off
	global_load_dwordx2 v[108:109], v[204:205], off
	v_lshl_add_u64 v[82:83], v[172:173], 1, s[26:27]
	global_load_dwordx4 v[118:121], v[80:81], off
	global_load_dwordx4 v[96:99], v[82:83], off
	v_add_u32_e32 v172, v84, v223
	v_lshl_add_u64 v[80:81], v[172:173], 1, s[26:27]
	v_add_u32_e32 v172, v84, v224
	v_lshl_add_u64 v[82:83], v[172:173], 1, s[26:27]
	global_load_dwordx4 v[92:95], v[80:81], off
	global_load_dwordx4 v[88:91], v[82:83], off
	global_load_dwordx2 v[106:107], v[196:197], off
	global_load_dwordx2 v[104:105], v[198:199], off
	global_load_dwordx2 v[102:103], v[200:201], off
	global_load_dwordx2 v[100:101], v[206:207], off
	v_add_u32_e32 v172, v84, v225
	v_lshl_add_u64 v[80:81], v[172:173], 1, s[26:27]
	v_add_u32_e32 v172, v84, v226
	v_lshl_add_u64 v[82:83], v[172:173], 1, s[26:27]
	global_load_dwordx4 v[84:87], v[80:81], off
	s_nop 0
	global_load_dwordx4 v[80:83], v[82:83], off
	v_add_u32_e32 v172, 0x80, v186
	s_waitcnt vmcnt(0)
	v_cvt_f32_f16_e32 v128, v110
	v_cvt_f32_f16_sdwa v129, v110 dst_sel:DWORD dst_unused:UNUSED_PAD src0_sel:WORD_1
	v_cvt_f32_f16_e32 v130, v111
	v_cvt_f32_f16_sdwa v131, v111 dst_sel:DWORD dst_unused:UNUSED_PAD src0_sel:WORD_1
	v_sub_f32_e32 v110, v128, v122
	v_sub_f32_e32 v111, v129, v122
	v_sub_f32_e32 v128, v130, v122
	v_sub_f32_e32 v129, v131, v122
	v_cvt_f32_f16_e32 v130, v112
	v_cvt_f32_f16_sdwa v131, v112 dst_sel:DWORD dst_unused:UNUSED_PAD src0_sel:WORD_1
	v_cvt_f32_f16_e32 v132, v113
	v_cvt_f32_f16_sdwa v133, v113 dst_sel:DWORD dst_unused:UNUSED_PAD src0_sel:WORD_1
	v_pk_mul_f32 v[128:129], v[122:123], v[128:129] op_sel:[1,0]
	v_pk_mul_f32 v[110:111], v[122:123], v[110:111] op_sel:[1,0]
	v_pk_fma_f32 v[128:129], v[78:79], v[128:129], v[74:75]
	v_pk_fma_f32 v[110:111], v[76:77], v[110:111], v[72:73]
	v_sub_f32_e32 v112, v130, v122
	v_sub_f32_e32 v113, v131, v122
	v_sub_f32_e32 v130, v132, v122
	v_sub_f32_e32 v131, v133, v122
	v_pk_mul_f32 v[130:131], v[122:123], v[130:131] op_sel:[1,0]
	v_pk_mul_f32 v[112:113], v[122:123], v[112:113] op_sel:[1,0]
	v_pk_mul_f32 v[128:129], v[128:129], s[36:37] op_sel_hi:[1,0]
	v_pk_mul_f32 v[110:111], v[110:111], s[36:37] op_sel_hi:[1,0]
	v_pk_fma_f32 v[112:113], v[64:65], v[112:113], v[68:69]
	v_pk_fma_f32 v[122:123], v[66:67], v[130:131], v[70:71]
	v_pk_fma_f32 v[110:111], v[60:61], 0.5, v[110:111] op_sel_hi:[1,0,1]
	v_pk_fma_f32 v[60:61], v[62:63], 0.5, v[128:129] op_sel_hi:[1,0,1]
	v_pk_mul_f32 v[62:63], v[122:123], s[36:37] op_sel_hi:[1,0]
	v_cvt_pk_f16_f32 v61, v60, v61
	v_cvt_pk_f16_f32 v60, v110, v111
	v_pk_mul_f32 v[110:111], v[112:113], s[36:37] op_sel_hi:[1,0]
	v_pk_fma_f32 v[58:59], v[58:59], 0.5, v[62:63] op_sel_hi:[1,0,1]
	v_pk_fma_f32 v[56:57], v[56:57], 0.5, v[110:111] op_sel_hi:[1,0,1]
	v_cvt_pk_f16_f32 v63, v58, v59
	v_cvt_pk_f16_f32 v62, v56, v57
	v_lshl_add_u64 v[56:57], v[172:173], 1, s[26:27]
; __device__ __forceinline__ u32x2 pack4h(f32x4 v) { const h16x4 h = __builtin_convertvector(v, h16x4); return __builtin_bit_cast(u32x2, h); }
; __device__ __forceinline__ f32x4 unpack4h(u32x2 w) { return __builtin_convertvector(__builtin_bit_cast(h16x4, w), f32x4); }
;     __device__ __forceinline__ void operator()(const f32x4 (&acc)[2][2][4][2], const pg8::Unit& u, int wr, int wc, int fr_, int fq_) const {
;     ...
; #pragma unroll
;                 for (int ai = 0; ai < 2; ++ai)
; #pragma unroll
;                     for (int m = 0; m < 4; ++m) { const unsigned off = (unsigned)(row0 + ai * 128 + m * 16) * DM + (unsigned)(col0 + bj * 128);
;                         u32x2 lo, hi; lo.x = r[ai][m].x; lo.y = r[ai][m].y; hi.x = r[ai][m].z; hi.y = r[ai][m].w;
;                         const f32x4 x0 = (unpack4h(lo) - mu[ai][m]) * rs[ai][m] * gv[0] + bv[0], x1 = (unpack4h(hi) - mu[ai][m]) * rs[ai][m] * gv[1] + bv[1];
;                         const u32x2 o0 = pack4h(x0 * ALPHA + acc[ai][bj][m][0] * s), o1 = pack4h(x1 * ALPHA + acc[ai][bj][m][1] * s);
;                         u32x4 w; w.x = o0.x; w.y = o0.y; w.z = o1.x; w.w = o1.y; *(u32x4*)(Z + off) = w; }
	global_store_dwordx4 v[56:57], v[60:63], off sc1
	v_cvt_f32_f16_e32 v56, v114
	v_cvt_f32_f16_sdwa v57, v114 dst_sel:DWORD dst_unused:UNUSED_PAD src0_sel:WORD_1
	v_cvt_f32_f16_e32 v58, v115
	v_cvt_f32_f16_sdwa v59, v115 dst_sel:DWORD dst_unused:UNUSED_PAD src0_sel:WORD_1
	v_cvt_f32_f16_e32 v60, v116
	v_cvt_f32_f16_sdwa v61, v116 dst_sel:DWORD dst_unused:UNUSED_PAD src0_sel:WORD_1
	v_cvt_f32_f16_e32 v62, v117
	v_cvt_f32_f16_sdwa v63, v117 dst_sel:DWORD dst_unused:UNUSED_PAD src0_sel:WORD_1
	v_sub_f32_e32 v56, v56, v124
	v_sub_f32_e32 v57, v57, v124
	v_sub_f32_e32 v58, v58, v124
	v_sub_f32_e32 v59, v59, v124
	v_pk_mul_f32 v[58:59], v[124:125], v[58:59] op_sel:[1,0]
	v_pk_mul_f32 v[56:57], v[124:125], v[56:57] op_sel:[1,0]
	v_pk_fma_f32 v[58:59], v[78:79], v[58:59], v[74:75]
	v_pk_fma_f32 v[56:57], v[76:77], v[56:57], v[72:73]
	v_sub_f32_e32 v60, v60, v124
	v_sub_f32_e32 v61, v61, v124
	v_sub_f32_e32 v62, v62, v124
	v_sub_f32_e32 v63, v63, v124
	v_pk_mul_f32 v[62:63], v[124:125], v[62:63] op_sel:[1,0]
	v_pk_mul_f32 v[60:61], v[124:125], v[60:61] op_sel:[1,0]
	v_pk_mul_f32 v[58:59], v[58:59], s[36:37] op_sel_hi:[1,0]
	v_pk_mul_f32 v[56:57], v[56:57], s[36:37] op_sel_hi:[1,0]
	v_pk_fma_f32 v[60:61], v[64:65], v[60:61], v[68:69]
	v_pk_fma_f32 v[62:63], v[66:67], v[62:63], v[70:71]
	v_pk_fma_f32 v[56:57], v[52:53], 0.5, v[56:57] op_sel_hi:[1,0,1]
	v_pk_fma_f32 v[52:53], v[54:55], 0.5, v[58:59] op_sel_hi:[1,0,1]
	v_pk_mul_f32 v[54:55], v[62:63], s[36:37] op_sel_hi:[1,0]
	v_cvt_pk_f16_f32 v53, v52, v53
	v_cvt_pk_f16_f32 v52, v56, v57
	v_pk_mul_f32 v[56:57], v[60:61], s[36:37] op_sel_hi:[1,0]
	v_add_u32_e32 v172, 0x8080, v186
	v_pk_fma_f32 v[48:49], v[48:49], 0.5, v[56:57] op_sel_hi:[1,0,1]
	v_pk_fma_f32 v[50:51], v[50:51], 0.5, v[54:55] op_sel_hi:[1,0,1]
	v_cvt_pk_f16_f32 v54, v48, v49
	v_cvt_pk_f16_f32 v55, v50, v51
	v_lshl_add_u64 v[48:49], v[172:173], 1, s[26:27]
	global_store_dwordx4 v[48:49], v[52:55], off sc1
	v_cvt_f32_f16_e32 v48, v118
	v_cvt_f32_f16_sdwa v49, v118 dst_sel:DWORD dst_unused:UNUSED_PAD src0_sel:WORD_1
	v_cvt_f32_f16_e32 v50, v119
	v_cvt_f32_f16_sdwa v51, v119 dst_sel:DWORD dst_unused:UNUSED_PAD src0_sel:WORD_1
	v_cvt_f32_f16_e32 v52, v120
	v_cvt_f32_f16_sdwa v53, v120 dst_sel:DWORD dst_unused:UNUSED_PAD src0_sel:WORD_1
	v_cvt_f32_f16_e32 v54, v121
	v_cvt_f32_f16_sdwa v55, v121 dst_sel:DWORD dst_unused:UNUSED_PAD src0_sel:WORD_1
	v_sub_f32_e32 v48, v48, v126
	v_sub_f32_e32 v49, v49, v126
	v_sub_f32_e32 v50, v50, v126
	v_sub_f32_e32 v51, v51, v126
	v_pk_mul_f32 v[50:51], v[126:127], v[50:51] op_sel:[1,0]
	v_pk_mul_f32 v[48:49], v[126:127], v[48:49] op_sel:[1,0]
	v_pk_fma_f32 v[50:51], v[78:79], v[50:51], v[74:75]
	v_pk_fma_f32 v[48:49], v[76:77], v[48:49], v[72:73]
	v_sub_f32_e32 v52, v52, v126
	v_sub_f32_e32 v53, v53, v126
	v_sub_f32_e32 v54, v54, v126
	v_sub_f32_e32 v55, v55, v126
	v_pk_mul_f32 v[54:55], v[126:127], v[54:55] op_sel:[1,0]
	v_pk_mul_f32 v[52:53], v[126:127], v[52:53] op_sel:[1,0]
	v_pk_mul_f32 v[50:51], v[50:51], s[36:37] op_sel_hi:[1,0]
	v_pk_mul_f32 v[48:49], v[48:49], s[36:37] op_sel_hi:[1,0]
	v_pk_fma_f32 v[52:53], v[64:65], v[52:53], v[68:69]
	v_pk_fma_f32 v[54:55], v[66:67], v[54:55], v[70:71]
	v_pk_fma_f32 v[48:49], v[44:45], 0.5, v[48:49] op_sel_hi:[1,0,1]
	v_pk_fma_f32 v[44:45], v[46:47], 0.5, v[50:51] op_sel_hi:[1,0,1]
	v_pk_mul_f32 v[46:47], v[54:55], s[36:37] op_sel_hi:[1,0]
	v_cvt_pk_f16_f32 v45, v44, v45
	v_cvt_pk_f16_f32 v44, v48, v49
	v_pk_mul_f32 v[48:49], v[52:53], s[36:37] op_sel_hi:[1,0]
	v_add_u32_e32 v172, 0x10080, v186
	v_pk_fma_f32 v[40:41], v[40:41], 0.5, v[48:49] op_sel_hi:[1,0,1]
	v_pk_fma_f32 v[42:43], v[42:43], 0.5, v[46:47] op_sel_hi:[1,0,1]
	v_cvt_pk_f16_f32 v46, v40, v41
	v_cvt_pk_f16_f32 v47, v42, v43
	v_lshl_add_u64 v[40:41], v[172:173], 1, s[26:27]
	global_store_dwordx4 v[40:41], v[44:47], off sc1
	v_cvt_f32_f16_e32 v40, v96
	v_cvt_f32_f16_sdwa v41, v96 dst_sel:DWORD dst_unused:UNUSED_PAD src0_sel:WORD_1
	v_cvt_f32_f16_e32 v42, v97
	v_cvt_f32_f16_sdwa v43, v97 dst_sel:DWORD dst_unused:UNUSED_PAD src0_sel:WORD_1
	v_cvt_f32_f16_e32 v44, v98
	v_cvt_f32_f16_sdwa v45, v98 dst_sel:DWORD dst_unused:UNUSED_PAD src0_sel:WORD_1
	v_cvt_f32_f16_e32 v46, v99
	v_cvt_f32_f16_sdwa v47, v99 dst_sel:DWORD dst_unused:UNUSED_PAD src0_sel:WORD_1
	v_sub_f32_e32 v40, v40, v108
	v_sub_f32_e32 v41, v41, v108
	v_sub_f32_e32 v42, v42, v108
	v_sub_f32_e32 v43, v43, v108
	v_pk_mul_f32 v[42:43], v[108:109], v[42:43] op_sel:[1,0]
	v_pk_mul_f32 v[40:41], v[108:109], v[40:41] op_sel:[1,0]
	v_pk_fma_f32 v[42:43], v[78:79], v[42:43], v[74:75]
	v_pk_fma_f32 v[40:41], v[76:77], v[40:41], v[72:73]
	v_sub_f32_e32 v44, v44, v108
	v_sub_f32_e32 v45, v45, v108
	v_sub_f32_e32 v46, v46, v108
	v_sub_f32_e32 v47, v47, v108
	v_pk_mul_f32 v[46:47], v[108:109], v[46:47] op_sel:[1,0]
	v_pk_mul_f32 v[44:45], v[108:109], v[44:45] op_sel:[1,0]
	v_pk_mul_f32 v[42:43], v[42:43], s[36:37] op_sel_hi:[1,0]
	v_pk_mul_f32 v[40:41], v[40:41], s[36:37] op_sel_hi:[1,0]
	v_pk_fma_f32 v[44:45], v[64:65], v[44:45], v[68:69]
	v_pk_fma_f32 v[46:47], v[66:67], v[46:47], v[70:71]
	v_pk_fma_f32 v[40:41], v[36:37], 0.5, v[40:41] op_sel_hi:[1,0,1]
	v_pk_fma_f32 v[36:37], v[38:39], 0.5, v[42:43] op_sel_hi:[1,0,1]
	v_pk_mul_f32 v[38:39], v[46:47], s[36:37] op_sel_hi:[1,0]
	v_cvt_pk_f16_f32 v37, v36, v37
	v_cvt_pk_f16_f32 v36, v40, v41
	v_pk_mul_f32 v[40:41], v[44:45], s[36:37] op_sel_hi:[1,0]
	v_add_u32_e32 v172, 0x18080, v186
	v_pk_fma_f32 v[32:33], v[32:33], 0.5, v[40:41] op_sel_hi:[1,0,1]
	v_pk_fma_f32 v[34:35], v[34:35], 0.5, v[38:39] op_sel_hi:[1,0,1]
	v_cvt_pk_f16_f32 v38, v32, v33
	v_cvt_pk_f16_f32 v39, v34, v35
	v_lshl_add_u64 v[32:33], v[172:173], 1, s[26:27]
; __device__ __forceinline__ u32x2 pack4h(f32x4 v) { const h16x4 h = __builtin_convertvector(v, h16x4); return __builtin_bit_cast(u32x2, h); }
; __device__ __forceinline__ f32x4 unpack4h(u32x2 w) { return __builtin_convertvector(__builtin_bit_cast(h16x4, w), f32x4); }
;     __device__ __forceinline__ void operator()(const f32x4 (&acc)[2][2][4][2], const pg8::Unit& u, int wr, int wc, int fr_, int fq_) const {
;     ...
; #pragma unroll
;                 for (int ai = 0; ai < 2; ++ai)
; #pragma unroll
;                     for (int m = 0; m < 4; ++m) { const unsigned off = (unsigned)(row0 + ai * 128 + m * 16) * DM + (unsigned)(col0 + bj * 128);
;                         u32x2 lo, hi; lo.x = r[ai][m].x; lo.y = r[ai][m].y; hi.x = r[ai][m].z; hi.y = r[ai][m].w;
;                         const f32x4 x0 = (unpack4h(lo) - mu[ai][m]) * rs[ai][m] * gv[0] + bv[0], x1 = (unpack4h(hi) - mu[ai][m]) * rs[ai][m] * gv[1] + bv[1];
;                         const u32x2 o0 = pack4h(x0 * ALPHA + acc[ai][bj][m][0] * s), o1 = pack4h(x1 * ALPHA + acc[ai][bj][m][1] * s);
;                         u32x4 w; w.x = o0.x; w.y = o0.y; w.z = o1.x; w.w = o1.y; *(u32x4*)(Z + off) = w; }
	global_store_dwordx4 v[32:33], v[36:39], off sc1
	v_cvt_f32_f16_e32 v32, v92
	v_cvt_f32_f16_sdwa v33, v92 dst_sel:DWORD dst_unused:UNUSED_PAD src0_sel:WORD_1
	v_cvt_f32_f16_e32 v34, v93
	v_cvt_f32_f16_sdwa v35, v93 dst_sel:DWORD dst_unused:UNUSED_PAD src0_sel:WORD_1
	v_cvt_f32_f16_e32 v36, v94
	v_cvt_f32_f16_sdwa v37, v94 dst_sel:DWORD dst_unused:UNUSED_PAD src0_sel:WORD_1
	v_cvt_f32_f16_e32 v38, v95
	v_cvt_f32_f16_sdwa v39, v95 dst_sel:DWORD dst_unused:UNUSED_PAD src0_sel:WORD_1
	v_sub_f32_e32 v32, v32, v106
	v_sub_f32_e32 v33, v33, v106
	v_sub_f32_e32 v34, v34, v106
	v_sub_f32_e32 v35, v35, v106
	v_pk_mul_f32 v[34:35], v[106:107], v[34:35] op_sel:[1,0]
	v_pk_mul_f32 v[32:33], v[106:107], v[32:33] op_sel:[1,0]
	v_pk_fma_f32 v[34:35], v[78:79], v[34:35], v[74:75]
	v_pk_fma_f32 v[32:33], v[76:77], v[32:33], v[72:73]
	v_sub_f32_e32 v36, v36, v106
	v_sub_f32_e32 v37, v37, v106
	v_sub_f32_e32 v38, v38, v106
	v_sub_f32_e32 v39, v39, v106
	v_pk_mul_f32 v[38:39], v[106:107], v[38:39] op_sel:[1,0]
	v_pk_mul_f32 v[36:37], v[106:107], v[36:37] op_sel:[1,0]
	v_pk_mul_f32 v[34:35], v[34:35], s[36:37] op_sel_hi:[1,0]
	v_pk_mul_f32 v[32:33], v[32:33], s[36:37] op_sel_hi:[1,0]
	v_pk_fma_f32 v[36:37], v[64:65], v[36:37], v[68:69]
	v_pk_fma_f32 v[38:39], v[66:67], v[38:39], v[70:71]
	v_pk_fma_f32 v[32:33], v[28:29], 0.5, v[32:33] op_sel_hi:[1,0,1]
	v_pk_fma_f32 v[28:29], v[30:31], 0.5, v[34:35] op_sel_hi:[1,0,1]
	v_pk_mul_f32 v[30:31], v[38:39], s[36:37] op_sel_hi:[1,0]
	v_cvt_pk_f16_f32 v29, v28, v29
	v_cvt_pk_f16_f32 v28, v32, v33
	v_pk_mul_f32 v[32:33], v[36:37], s[36:37] op_sel_hi:[1,0]
	v_add_u32_e32 v172, 0x40080, v186
	v_pk_fma_f32 v[24:25], v[24:25], 0.5, v[32:33] op_sel_hi:[1,0,1]
	v_pk_fma_f32 v[26:27], v[26:27], 0.5, v[30:31] op_sel_hi:[1,0,1]
	v_cvt_pk_f16_f32 v30, v24, v25
	v_cvt_pk_f16_f32 v31, v26, v27
	v_lshl_add_u64 v[24:25], v[172:173], 1, s[26:27]
	global_store_dwordx4 v[24:25], v[28:31], off sc1
	v_cvt_f32_f16_e32 v24, v88
	v_cvt_f32_f16_sdwa v25, v88 dst_sel:DWORD dst_unused:UNUSED_PAD src0_sel:WORD_1
	v_cvt_f32_f16_e32 v26, v89
	v_cvt_f32_f16_sdwa v27, v89 dst_sel:DWORD dst_unused:UNUSED_PAD src0_sel:WORD_1
	v_cvt_f32_f16_e32 v28, v90
	v_cvt_f32_f16_sdwa v29, v90 dst_sel:DWORD dst_unused:UNUSED_PAD src0_sel:WORD_1
	v_cvt_f32_f16_e32 v30, v91
	v_cvt_f32_f16_sdwa v31, v91 dst_sel:DWORD dst_unused:UNUSED_PAD src0_sel:WORD_1
	v_sub_f32_e32 v24, v24, v104
	v_sub_f32_e32 v25, v25, v104
	v_sub_f32_e32 v26, v26, v104
	v_sub_f32_e32 v27, v27, v104
	v_pk_mul_f32 v[26:27], v[104:105], v[26:27] op_sel:[1,0]
	v_pk_mul_f32 v[24:25], v[104:105], v[24:25] op_sel:[1,0]
	v_pk_fma_f32 v[26:27], v[78:79], v[26:27], v[74:75]
	v_pk_fma_f32 v[24:25], v[76:77], v[24:25], v[72:73]
	v_sub_f32_e32 v28, v28, v104
	v_sub_f32_e32 v29, v29, v104
	v_sub_f32_e32 v30, v30, v104
	v_sub_f32_e32 v31, v31, v104
	v_pk_mul_f32 v[30:31], v[104:105], v[30:31] op_sel:[1,0]
	v_pk_mul_f32 v[28:29], v[104:105], v[28:29] op_sel:[1,0]
	v_pk_mul_f32 v[26:27], v[26:27], s[36:37] op_sel_hi:[1,0]
	v_pk_mul_f32 v[24:25], v[24:25], s[36:37] op_sel_hi:[1,0]
	v_pk_fma_f32 v[28:29], v[64:65], v[28:29], v[68:69]
	v_pk_fma_f32 v[30:31], v[66:67], v[30:31], v[70:71]
	v_pk_fma_f32 v[24:25], v[20:21], 0.5, v[24:25] op_sel_hi:[1,0,1]
	v_pk_fma_f32 v[20:21], v[22:23], 0.5, v[26:27] op_sel_hi:[1,0,1]
	v_pk_mul_f32 v[22:23], v[30:31], s[36:37] op_sel_hi:[1,0]
	v_cvt_pk_f16_f32 v21, v20, v21
	v_cvt_pk_f16_f32 v20, v24, v25
	v_pk_mul_f32 v[24:25], v[28:29], s[36:37] op_sel_hi:[1,0]
	v_add_u32_e32 v172, 0x48080, v186
	v_pk_fma_f32 v[16:17], v[16:17], 0.5, v[24:25] op_sel_hi:[1,0,1]
	v_pk_fma_f32 v[18:19], v[18:19], 0.5, v[22:23] op_sel_hi:[1,0,1]
	v_cvt_pk_f16_f32 v22, v16, v17
	v_cvt_pk_f16_f32 v23, v18, v19
	v_lshl_add_u64 v[16:17], v[172:173], 1, s[26:27]
; __device__ __forceinline__ u32x2 pack4h(f32x4 v) { const h16x4 h = __builtin_convertvector(v, h16x4); return __builtin_bit_cast(u32x2, h); }
; __device__ __forceinline__ f32x4 unpack4h(u32x2 w) { return __builtin_convertvector(__builtin_bit_cast(h16x4, w), f32x4); }
;     __device__ __forceinline__ void operator()(const f32x4 (&acc)[2][2][4][2], const pg8::Unit& u, int wr, int wc, int fr_, int fq_) const {
;     ...
; #pragma unroll
;                 for (int ai = 0; ai < 2; ++ai)
; #pragma unroll
;                     for (int m = 0; m < 4; ++m) { const unsigned off = (unsigned)(row0 + ai * 128 + m * 16) * DM + (unsigned)(col0 + bj * 128);
;                         u32x2 lo, hi; lo.x = r[ai][m].x; lo.y = r[ai][m].y; hi.x = r[ai][m].z; hi.y = r[ai][m].w;
;                         const f32x4 x0 = (unpack4h(lo) - mu[ai][m]) * rs[ai][m] * gv[0] + bv[0], x1 = (unpack4h(hi) - mu[ai][m]) * rs[ai][m] * gv[1] + bv[1];
;                         const u32x2 o0 = pack4h(x0 * ALPHA + acc[ai][bj][m][0] * s), o1 = pack4h(x1 * ALPHA + acc[ai][bj][m][1] * s);
;                         u32x4 w; w.x = o0.x; w.y = o0.y; w.z = o1.x; w.w = o1.y; *(u32x4*)(Z + off) = w; }
	global_store_dwordx4 v[16:17], v[20:23], off sc1
	v_cvt_f32_f16_e32 v16, v84
	v_cvt_f32_f16_sdwa v17, v84 dst_sel:DWORD dst_unused:UNUSED_PAD src0_sel:WORD_1
	v_cvt_f32_f16_e32 v18, v85
	v_cvt_f32_f16_sdwa v19, v85 dst_sel:DWORD dst_unused:UNUSED_PAD src0_sel:WORD_1
	v_cvt_f32_f16_e32 v20, v86
	v_cvt_f32_f16_sdwa v21, v86 dst_sel:DWORD dst_unused:UNUSED_PAD src0_sel:WORD_1
	v_cvt_f32_f16_e32 v22, v87
	v_cvt_f32_f16_sdwa v23, v87 dst_sel:DWORD dst_unused:UNUSED_PAD src0_sel:WORD_1
	v_sub_f32_e32 v16, v16, v102
	v_sub_f32_e32 v17, v17, v102
	v_sub_f32_e32 v18, v18, v102
	v_sub_f32_e32 v19, v19, v102
	v_pk_mul_f32 v[18:19], v[102:103], v[18:19] op_sel:[1,0]
	v_pk_mul_f32 v[16:17], v[102:103], v[16:17] op_sel:[1,0]
	v_pk_fma_f32 v[18:19], v[78:79], v[18:19], v[74:75]
	v_pk_fma_f32 v[16:17], v[76:77], v[16:17], v[72:73]
	v_sub_f32_e32 v20, v20, v102
	v_sub_f32_e32 v21, v21, v102
	v_sub_f32_e32 v22, v22, v102
	v_sub_f32_e32 v23, v23, v102
	v_pk_mul_f32 v[22:23], v[102:103], v[22:23] op_sel:[1,0]
	v_pk_mul_f32 v[20:21], v[102:103], v[20:21] op_sel:[1,0]
	v_pk_mul_f32 v[18:19], v[18:19], s[36:37] op_sel_hi:[1,0]
	v_pk_mul_f32 v[16:17], v[16:17], s[36:37] op_sel_hi:[1,0]
	v_pk_fma_f32 v[20:21], v[64:65], v[20:21], v[68:69]
	v_pk_fma_f32 v[22:23], v[66:67], v[22:23], v[70:71]
	v_pk_fma_f32 v[16:17], v[12:13], 0.5, v[16:17] op_sel_hi:[1,0,1]
	v_pk_fma_f32 v[12:13], v[14:15], 0.5, v[18:19] op_sel_hi:[1,0,1]
	v_pk_mul_f32 v[14:15], v[22:23], s[36:37] op_sel_hi:[1,0]
	v_cvt_pk_f16_f32 v13, v12, v13
	v_cvt_pk_f16_f32 v12, v16, v17
	v_pk_mul_f32 v[16:17], v[20:21], s[36:37] op_sel_hi:[1,0]
	v_add_u32_e32 v172, 0x50080, v186
	v_pk_fma_f32 v[8:9], v[8:9], 0.5, v[16:17] op_sel_hi:[1,0,1]
	v_pk_fma_f32 v[10:11], v[10:11], 0.5, v[14:15] op_sel_hi:[1,0,1]
	v_cvt_pk_f16_f32 v14, v8, v9
	v_cvt_pk_f16_f32 v15, v10, v11
	v_lshl_add_u64 v[8:9], v[172:173], 1, s[26:27]
	global_store_dwordx4 v[8:9], v[12:15], off sc1
	v_cvt_f32_f16_e32 v8, v80
	v_cvt_f32_f16_sdwa v9, v80 dst_sel:DWORD dst_unused:UNUSED_PAD src0_sel:WORD_1
	v_cvt_f32_f16_e32 v10, v81
	v_cvt_f32_f16_sdwa v11, v81 dst_sel:DWORD dst_unused:UNUSED_PAD src0_sel:WORD_1
	v_cvt_f32_f16_e32 v12, v82
	v_cvt_f32_f16_sdwa v13, v82 dst_sel:DWORD dst_unused:UNUSED_PAD src0_sel:WORD_1
	v_cvt_f32_f16_e32 v14, v83
	v_cvt_f32_f16_sdwa v15, v83 dst_sel:DWORD dst_unused:UNUSED_PAD src0_sel:WORD_1
	v_sub_f32_e32 v8, v8, v100
	v_sub_f32_e32 v9, v9, v100
	v_sub_f32_e32 v10, v10, v100
	v_sub_f32_e32 v11, v11, v100
	v_pk_mul_f32 v[10:11], v[100:101], v[10:11] op_sel:[1,0]
	v_pk_mul_f32 v[8:9], v[100:101], v[8:9] op_sel:[1,0]
	v_pk_fma_f32 v[10:11], v[78:79], v[10:11], v[74:75]
	v_pk_fma_f32 v[8:9], v[76:77], v[8:9], v[72:73]
	v_sub_f32_e32 v12, v12, v100
	v_sub_f32_e32 v13, v13, v100
	v_sub_f32_e32 v14, v14, v100
	v_sub_f32_e32 v15, v15, v100
	v_pk_mul_f32 v[14:15], v[100:101], v[14:15] op_sel:[1,0]
	v_pk_mul_f32 v[12:13], v[100:101], v[12:13] op_sel:[1,0]
	v_pk_mul_f32 v[10:11], v[10:11], s[36:37] op_sel_hi:[1,0]
	v_pk_mul_f32 v[8:9], v[8:9], s[36:37] op_sel_hi:[1,0]
	v_pk_fma_f32 v[12:13], v[64:65], v[12:13], v[68:69]
	v_pk_fma_f32 v[14:15], v[66:67], v[14:15], v[70:71]
	v_pk_fma_f32 v[8:9], v[4:5], 0.5, v[8:9] op_sel_hi:[1,0,1]
	v_pk_fma_f32 v[4:5], v[6:7], 0.5, v[10:11] op_sel_hi:[1,0,1]
	v_pk_mul_f32 v[6:7], v[14:15], s[36:37] op_sel_hi:[1,0]
	v_cvt_pk_f16_f32 v5, v4, v5
	v_cvt_pk_f16_f32 v4, v8, v9
	v_pk_mul_f32 v[8:9], v[12:13], s[36:37] op_sel_hi:[1,0]
	v_add_u32_e32 v172, 0x58080, v186
	v_pk_fma_f32 v[0:1], v[0:1], 0.5, v[8:9] op_sel_hi:[1,0,1]
	v_pk_fma_f32 v[2:3], v[2:3], 0.5, v[6:7] op_sel_hi:[1,0,1]
	v_cvt_pk_f16_f32 v6, v0, v1
	v_cvt_pk_f16_f32 v7, v2, v3
	v_lshl_add_u64 v[0:1], v[172:173], 1, s[26:27]
	global_store_dwordx4 v[0:1], v[4:7], off sc1

; #define PG8_STAGE(bufoff, gbase, voff) do { _Pragma("unroll") for (int _i = 0; _i < 2; ++_i) \
;         __builtin_amdgcn_global_load_lds((const unsigned*)((const char*)(gbase) + (voff)[_i]), (PG8_LAS unsigned*)(lds + (bufoff) + ldsw + _i * 8192), 16, 0, 0); } while (0)
; #define PG8_LDA(dst, b, h) do { _Pragma("unroll") for (int m = 0; m < 4; ++m) _Pragma("unroll") for (int k = 0; k < 2; ++k) dst[m][k] = *(const PG8_LAS bf16x8*)(lds + PG8_SA(b, h) + aoff + m * 2048 + k * 1024); } while (0)
; #define PG8_LDB(dst, b, h) do { _Pragma("unroll") for (int n = 0; n < 2; ++n) _Pragma("unroll") for (int k = 0; k < 2; ++k) dst[n][k] = *(const PG8_LAS bf16x8*)(lds + PG8_SB(b, h) + boff + n * 2048 + k * 1024); } while (0)
; #define PG8_MMA(ai, bj, At, Bt) do { __builtin_amdgcn_s_setprio(1); _Pragma("unroll") for (int m = 0; m < 4; ++m) _Pragma("unroll") for (int n = 0; n < 2; ++n) _Pragma("unroll") for (int k = 0; k < 2; ++k) \
;         acc[ai][bj][m][n] = __builtin_amdgcn_mfma_f32_16x16x32_bf16(Bt[n][k], At[m][k], acc[ai][bj][m][n], 0, 0, 0); __builtin_amdgcn_s_setprio(0); } while (0)
; #define PG8_WAIT_V(n) asm volatile("s_waitcnt vmcnt(" #n ")" ::: "memory")
; #define PG8_WAIT_L(n) asm volatile("s_waitcnt lgkmcnt(" #n ")" ::: "memory")
; #define PG8_BAR __builtin_amdgcn_s_barrier()
; #define PG8_SCHED __builtin_amdgcn_sched_barrier(0)
; template <class Epi, class Sched>
; __device__ __forceinline__ void gemm_phase(PG8_LAS unsigned char* lds, const Gemm g, const Sched& S, const Epi& E) {
;     ...
;             PG8_LDB(B0, 0, 0); PG8_SCHED; PG8_LDA(At, 0, 0); PG8_STAGE(PG8_SA(1, 1), a1 + hstep, voffA);
;             PG8_WAIT_L(8); PG8_BAR; PG8_WAIT_L(0); PG8_MMA(0, 0, At, B0); PG8_BAR; PG8_SCHED;
;             PG8_LDB(B1, 0, 1); PG8_STAGE(PG8_SB(0, 0), b2, voffB);
;             PG8_BAR; PG8_WAIT_L(0); PG8_MMA(0, 1, At, B1); PG8_BAR;
;             PG8_LDA(At, 0, 1); PG8_STAGE(PG8_SA(0, 0), a2, voffA);
;             PG8_BAR; PG8_WAIT_L(0); PG8_MMA(1, 0, At, B0); PG8_BAR; PG8_SCHED;
;             PG8_STAGE(PG8_SB(0, 1), b2 + hstep, voffB);
;             PG8_WAIT_V(6); PG8_BAR; PG8_MMA(1, 1, At, B1); PG8_BAR;
.LBB0_600:
	s_add_u32 s44, s50, 0x100
	s_addc_u32 s45, s51, 0
	s_add_i32 s26, 0, 0x10000
	v_add_u32_e32 v140, s26, v219
	ds_read_b128 v[128:131], v140
	ds_read_b128 v[132:135], v140 offset:1024
	ds_read_b128 v[136:139], v140 offset:2048
	ds_read_b128 v[140:143], v140 offset:3072
	s_cmpk_eq_i32 s29, 0x54
	s_cselect_b32 s55, s1, s45
	s_cselect_b32 s54, s0, s44
	s_cselect_b32 s53, s43, s28
	s_cselect_b32 s52, s42, s9
	v_lshl_add_u64 v[176:177], s[50:51], 0, v[180:181]
	s_add_i32 m0, s59, 0xc000
	ds_read_b128 v[144:147], v220
	ds_read_b128 v[148:151], v220 offset:1024
	ds_read_b128 v[152:155], v220 offset:2048
	ds_read_b128 v[156:159], v220 offset:3072
	ds_read_b128 v[160:163], v220 offset:4096
	ds_read_b128 v[184:187], v220 offset:5120
	ds_read_b128 v[188:191], v220 offset:6144
	ds_read_b128 v[192:195], v220 offset:7168
	global_load_lds_dwordx4 v[176:177], off
	v_lshl_add_u64 v[176:177], s[50:51], 0, v[182:183]
	s_add_i32 m0, s59, 0xe000
	s_nop 0
	global_load_lds_dwordx4 v[176:177], off
	s_waitcnt lgkmcnt(8)
	s_barrier
	s_waitcnt lgkmcnt(0)
	s_setprio 1
	s_waitcnt lgkmcnt(0)
	v_mfma_f32_16x16x32_bf16 v[124:127], v[128:131], v[144:147], v[124:127]
	v_mfma_f32_16x16x32_bf16 v[120:123], v[136:139], v[144:147], v[120:123]
	v_mfma_f32_16x16x32_bf16 v[116:119], v[128:131], v[152:155], v[116:119]
	v_mfma_f32_16x16x32_bf16 v[112:115], v[136:139], v[152:155], v[112:115]
	v_mfma_f32_16x16x32_bf16 v[108:111], v[128:131], v[160:163], v[108:111]
	v_mfma_f32_16x16x32_bf16 v[104:107], v[136:139], v[160:163], v[104:107]
	v_mfma_f32_16x16x32_bf16 v[100:103], v[128:131], v[188:191], v[100:103]
	v_mfma_f32_16x16x32_bf16 v[96:99], v[136:139], v[188:191], v[96:99]
	v_mfma_f32_16x16x32_bf16 v[124:127], v[132:135], v[148:151], v[124:127]
	v_mfma_f32_16x16x32_bf16 v[120:123], v[140:143], v[148:151], v[120:123]
	v_mfma_f32_16x16x32_bf16 v[116:119], v[132:135], v[156:159], v[116:119]
	v_mfma_f32_16x16x32_bf16 v[112:115], v[140:143], v[156:159], v[112:115]
	v_mfma_f32_16x16x32_bf16 v[108:111], v[132:135], v[184:187], v[108:111]
	v_mfma_f32_16x16x32_bf16 v[104:107], v[140:143], v[184:187], v[104:107]
	v_mfma_f32_16x16x32_bf16 v[100:103], v[132:135], v[192:195], v[100:103]
	v_mfma_f32_16x16x32_bf16 v[96:99], v[140:143], v[192:195], v[96:99]
	s_setprio 0
	s_barrier
	s_add_i32 s27, 0, 0x14000
	s_add_i32 s26, s26, s58
	v_add_u32_e32 v172, s27, v219
	v_lshl_add_u64 v[176:177], s[52:53], 0, v[168:169]
	s_mov_b32 m0, s26
	ds_read_b128 v[196:199], v172
	ds_read_b128 v[200:203], v172 offset:1024
	ds_read_b128 v[204:207], v172 offset:2048
	ds_read_b128 v[208:211], v172 offset:3072
	global_load_lds_dwordx4 v[176:177], off
	v_lshl_add_u64 v[178:179], s[52:53], 0, v[164:165]
	s_add_i32 m0, s26, 0x2000
	s_nop 0
	global_load_lds_dwordx4 v[178:179], off
	s_barrier
	s_waitcnt lgkmcnt(0)
	s_setprio 1
	s_waitcnt lgkmcnt(0)
	v_mfma_f32_16x16x32_bf16 v[60:63], v[196:199], v[144:147], v[60:63]
	v_mfma_f32_16x16x32_bf16 v[56:59], v[204:207], v[144:147], v[56:59]
	v_mfma_f32_16x16x32_bf16 v[52:55], v[196:199], v[152:155], v[52:55]
	v_mfma_f32_16x16x32_bf16 v[48:51], v[204:207], v[152:155], v[48:51]
	v_mfma_f32_16x16x32_bf16 v[44:47], v[196:199], v[160:163], v[44:47]
	v_mfma_f32_16x16x32_bf16 v[40:43], v[204:207], v[160:163], v[40:43]
	v_mfma_f32_16x16x32_bf16 v[36:39], v[196:199], v[188:191], v[36:39]
	v_mfma_f32_16x16x32_bf16 v[32:35], v[204:207], v[188:191], v[32:35]
	v_mfma_f32_16x16x32_bf16 v[60:63], v[200:203], v[148:151], v[60:63]
	v_mfma_f32_16x16x32_bf16 v[56:59], v[208:211], v[148:151], v[56:59]
	v_mfma_f32_16x16x32_bf16 v[52:55], v[200:203], v[156:159], v[52:55]
	v_mfma_f32_16x16x32_bf16 v[48:51], v[208:211], v[156:159], v[48:51]
	v_mfma_f32_16x16x32_bf16 v[44:47], v[200:203], v[184:187], v[44:47]
	v_mfma_f32_16x16x32_bf16 v[40:43], v[208:211], v[184:187], v[40:43]
	v_mfma_f32_16x16x32_bf16 v[36:39], v[200:203], v[192:195], v[36:39]
	v_mfma_f32_16x16x32_bf16 v[32:35], v[208:211], v[192:195], v[32:35]
	s_setprio 0
	s_mov_b32 m0, s59
	v_lshl_add_u64 v[212:213], s[54:55], 0, v[170:171]
	s_barrier
	ds_read_b128 v[144:147], v220 offset:16384
	ds_read_b128 v[148:151], v220 offset:17408
	ds_read_b128 v[152:155], v220 offset:18432
	ds_read_b128 v[156:159], v220 offset:19456
	ds_read_b128 v[160:163], v220 offset:20480
	ds_read_b128 v[184:187], v220 offset:21504
	ds_read_b128 v[188:191], v220 offset:22528
	ds_read_b128 v[192:195], v220 offset:23552
	global_load_lds_dwordx4 v[212:213], off
	v_lshl_add_u64 v[214:215], s[54:55], 0, v[166:167]
	s_mov_b32 m0, s62
	s_nop 0
	global_load_lds_dwordx4 v[214:215], off
	s_barrier
	s_waitcnt lgkmcnt(0)
	s_setprio 1
	s_waitcnt lgkmcnt(0)
	v_mfma_f32_16x16x32_bf16 v[92:95], v[128:131], v[144:147], v[92:95]
	v_mfma_f32_16x16x32_bf16 v[88:91], v[136:139], v[144:147], v[88:91]
	v_mfma_f32_16x16x32_bf16 v[84:87], v[128:131], v[152:155], v[84:87]
	v_mfma_f32_16x16x32_bf16 v[80:83], v[136:139], v[152:155], v[80:83]
	v_mfma_f32_16x16x32_bf16 v[76:79], v[128:131], v[160:163], v[76:79]
	v_mfma_f32_16x16x32_bf16 v[72:75], v[136:139], v[160:163], v[72:75]
	v_mfma_f32_16x16x32_bf16 v[68:71], v[128:131], v[188:191], v[68:71]
	v_mfma_f32_16x16x32_bf16 v[64:67], v[136:139], v[188:191], v[64:67]
	v_mfma_f32_16x16x32_bf16 v[92:95], v[132:135], v[148:151], v[92:95]
	v_mfma_f32_16x16x32_bf16 v[88:91], v[140:143], v[148:151], v[88:91]
	v_mfma_f32_16x16x32_bf16 v[84:87], v[132:135], v[156:159], v[84:87]
	v_mfma_f32_16x16x32_bf16 v[80:83], v[140:143], v[156:159], v[80:83]
	v_mfma_f32_16x16x32_bf16 v[76:79], v[132:135], v[184:187], v[76:79]
	v_mfma_f32_16x16x32_bf16 v[72:75], v[140:143], v[184:187], v[72:75]
	v_mfma_f32_16x16x32_bf16 v[68:71], v[132:135], v[192:195], v[68:71]
	v_mfma_f32_16x16x32_bf16 v[64:67], v[140:143], v[192:195], v[64:67]
	s_setprio 0
	s_barrier
; #define PG8_STAGE(bufoff, gbase, voff) do { _Pragma("unroll") for (int _i = 0; _i < 2; ++_i) \
;         __builtin_amdgcn_global_load_lds((const unsigned*)((const char*)(gbase) + (voff)[_i]), (PG8_LAS unsigned*)(lds + (bufoff) + ldsw + _i * 8192), 16, 0, 0); } while (0)
; #define PG8_LDA(dst, b, h) do { _Pragma("unroll") for (int m = 0; m < 4; ++m) _Pragma("unroll") for (int k = 0; k < 2; ++k) dst[m][k] = *(const PG8_LAS bf16x8*)(lds + PG8_SA(b, h) + aoff + m * 2048 + k * 1024); } while (0)
; #define PG8_LDB(dst, b, h) do { _Pragma("unroll") for (int n = 0; n < 2; ++n) _Pragma("unroll") for (int k = 0; k < 2; ++k) dst[n][k] = *(const PG8_LAS bf16x8*)(lds + PG8_SB(b, h) + boff + n * 2048 + k * 1024); } while (0)
; #define PG8_MMA(ai, bj, At, Bt) do { __builtin_amdgcn_s_setprio(1); _Pragma("unroll") for (int m = 0; m < 4; ++m) _Pragma("unroll") for (int n = 0; n < 2; ++n) _Pragma("unroll") for (int k = 0; k < 2; ++k) \
;         acc[ai][bj][m][n] = __builtin_amdgcn_mfma_f32_16x16x32_bf16(Bt[n][k], At[m][k], acc[ai][bj][m][n], 0, 0, 0); __builtin_amdgcn_s_setprio(0); } while (0)
; #define PG8_WAIT_V(n) asm volatile("s_waitcnt vmcnt(" #n ")" ::: "memory")
; #define PG8_WAIT_L(n) asm volatile("s_waitcnt lgkmcnt(" #n ")" ::: "memory")
; #define PG8_BAR __builtin_amdgcn_s_barrier()
; #define PG8_SCHED __builtin_amdgcn_sched_barrier(0)
; template <class Epi, class Sched>
; __device__ __forceinline__ void gemm_phase(PG8_LAS unsigned char* lds, const Gemm g, const Sched& S, const Epi& E) {
;     ...
;             PG8_BAR; PG8_WAIT_L(0); PG8_MMA(1, 0, At, B0); PG8_BAR; PG8_SCHED;
;             PG8_STAGE(PG8_SB(0, 1), b2 + hstep, voffB);
;             PG8_WAIT_V(6); PG8_BAR; PG8_MMA(1, 1, At, B1); PG8_BAR;
;             PG8_LDB(B0, 1, 0); PG8_SCHED; PG8_LDA(At, 1, 0); PG8_STAGE(PG8_SA(0, 1), a2 + hstep, voffA);
;             PG8_WAIT_L(8); PG8_BAR; PG8_WAIT_L(0); PG8_MMA(0, 0, At, B0); PG8_BAR; PG8_SCHED;
;             PG8_LDB(B1, 1, 1); PG8_STAGE(PG8_SB(1, 0), b3, voffB);
;             PG8_BAR; PG8_WAIT_L(0); PG8_MMA(0, 1, At, B1); PG8_BAR;
;             PG8_LDA(At, 1, 1); PG8_STAGE(PG8_SA(1, 0), a3, voffA);
;             PG8_BAR; PG8_WAIT_L(0); PG8_MMA(1, 0, At, B0); PG8_BAR; PG8_SCHED;
	s_add_u32 s50, s52, 0x160000
	s_addc_u32 s51, s53, 0
	s_add_i32 s26, s27, s58
	v_lshl_add_u64 v[128:129], s[50:51], 0, v[168:169]
	s_mov_b32 m0, s26
	s_nop 0
	global_load_lds_dwordx4 v[128:129], off
	v_lshl_add_u64 v[128:129], s[50:51], 0, v[164:165]
	s_add_i32 m0, s26, 0x2000
	s_nop 0
	global_load_lds_dwordx4 v[128:129], off
	s_waitcnt vmcnt(6)
	s_barrier
	s_setprio 1
	v_mfma_f32_16x16x32_bf16 v[28:31], v[196:199], v[144:147], v[28:31]
	v_mfma_f32_16x16x32_bf16 v[24:27], v[204:207], v[144:147], v[24:27]
	v_mfma_f32_16x16x32_bf16 v[20:23], v[196:199], v[152:155], v[20:23]
	v_mfma_f32_16x16x32_bf16 v[16:19], v[204:207], v[152:155], v[16:19]
	v_mfma_f32_16x16x32_bf16 v[12:15], v[196:199], v[160:163], v[12:15]
	v_mfma_f32_16x16x32_bf16 v[8:11], v[204:207], v[160:163], v[8:11]
	v_mfma_f32_16x16x32_bf16 v[4:7], v[196:199], v[188:191], v[4:7]
	v_mfma_f32_16x16x32_bf16 v[0:3], v[204:207], v[188:191], v[0:3]
	v_mfma_f32_16x16x32_bf16 v[28:31], v[200:203], v[148:151], v[28:31]
	v_mfma_f32_16x16x32_bf16 v[24:27], v[208:211], v[148:151], v[24:27]
	v_mfma_f32_16x16x32_bf16 v[20:23], v[200:203], v[156:159], v[20:23]
	v_mfma_f32_16x16x32_bf16 v[16:19], v[208:211], v[156:159], v[16:19]
	v_mfma_f32_16x16x32_bf16 v[12:15], v[200:203], v[184:187], v[12:15]
	v_mfma_f32_16x16x32_bf16 v[8:11], v[208:211], v[184:187], v[8:11]
	v_mfma_f32_16x16x32_bf16 v[4:7], v[200:203], v[192:195], v[4:7]
	v_mfma_f32_16x16x32_bf16 v[0:3], v[208:211], v[192:195], v[0:3]
	s_setprio 0
	s_add_i32 s26, 0, 0x18000
	v_add_u32_e32 v140, s26, v219
	s_barrier
	ds_read_b128 v[128:131], v140
	ds_read_b128 v[132:135], v140 offset:1024
	ds_read_b128 v[136:139], v140 offset:2048
	ds_read_b128 v[140:143], v140 offset:3072
	s_add_u32 s50, s54, 0x160000
	s_addc_u32 s51, s55, 0
	s_mov_b32 m0, s63
	v_lshl_add_u64 v[196:197], s[50:51], 0, v[170:171]
	ds_read_b128 v[144:147], v220 offset:32768
	ds_read_b128 v[148:151], v220 offset:33792
	ds_read_b128 v[152:155], v220 offset:34816
	ds_read_b128 v[156:159], v220 offset:35840
	ds_read_b128 v[160:163], v220 offset:36864
	ds_read_b128 v[184:187], v220 offset:37888
	ds_read_b128 v[188:191], v220 offset:38912
	ds_read_b128 v[192:195], v220 offset:39936
	global_load_lds_dwordx4 v[196:197], off
	v_lshl_add_u64 v[196:197], s[50:51], 0, v[166:167]
	s_mov_b32 m0, s2
	s_nop 0
	global_load_lds_dwordx4 v[196:197], off
	s_waitcnt lgkmcnt(8)
	s_barrier
	s_waitcnt lgkmcnt(0)
	s_setprio 1
	s_waitcnt lgkmcnt(0)
	v_mfma_f32_16x16x32_bf16 v[124:127], v[128:131], v[144:147], v[124:127]
	v_mfma_f32_16x16x32_bf16 v[120:123], v[136:139], v[144:147], v[120:123]
	v_mfma_f32_16x16x32_bf16 v[116:119], v[128:131], v[152:155], v[116:119]
	v_mfma_f32_16x16x32_bf16 v[112:115], v[136:139], v[152:155], v[112:115]
	v_mfma_f32_16x16x32_bf16 v[108:111], v[128:131], v[160:163], v[108:111]
	v_mfma_f32_16x16x32_bf16 v[104:107], v[136:139], v[160:163], v[104:107]
	v_mfma_f32_16x16x32_bf16 v[100:103], v[128:131], v[188:191], v[100:103]
	v_mfma_f32_16x16x32_bf16 v[96:99], v[136:139], v[188:191], v[96:99]
	v_mfma_f32_16x16x32_bf16 v[124:127], v[132:135], v[148:151], v[124:127]
	v_mfma_f32_16x16x32_bf16 v[120:123], v[140:143], v[148:151], v[120:123]
	v_mfma_f32_16x16x32_bf16 v[116:119], v[132:135], v[156:159], v[116:119]
	v_mfma_f32_16x16x32_bf16 v[112:115], v[140:143], v[156:159], v[112:115]
	v_mfma_f32_16x16x32_bf16 v[108:111], v[132:135], v[184:187], v[108:111]
	v_mfma_f32_16x16x32_bf16 v[104:107], v[140:143], v[184:187], v[104:107]
	v_mfma_f32_16x16x32_bf16 v[100:103], v[132:135], v[192:195], v[100:103]
	v_mfma_f32_16x16x32_bf16 v[96:99], v[140:143], v[192:195], v[96:99]
	s_setprio 0
	s_barrier
	s_add_i32 s27, 0, 0x1c000
	s_add_i32 s26, s26, s58
	v_add_u32_e32 v172, s27, v219
	v_lshl_add_u64 v[176:177], v[176:177], 0, s[38:39]
	s_mov_b32 m0, s26
	ds_read_b128 v[196:199], v172
	ds_read_b128 v[200:203], v172 offset:1024
	ds_read_b128 v[204:207], v172 offset:2048
	ds_read_b128 v[208:211], v172 offset:3072
	global_load_lds_dwordx4 v[176:177], off
	v_lshl_add_u64 v[176:177], v[178:179], 0, s[38:39]
	s_add_i32 m0, s26, 0x2000
	s_nop 0
	global_load_lds_dwordx4 v[176:177], off
	s_barrier
	s_waitcnt lgkmcnt(0)
	s_setprio 1
	s_waitcnt lgkmcnt(0)
	v_mfma_f32_16x16x32_bf16 v[60:63], v[196:199], v[144:147], v[60:63]
	v_mfma_f32_16x16x32_bf16 v[56:59], v[204:207], v[144:147], v[56:59]
	v_mfma_f32_16x16x32_bf16 v[52:55], v[196:199], v[152:155], v[52:55]
	v_mfma_f32_16x16x32_bf16 v[48:51], v[204:207], v[152:155], v[48:51]
	v_mfma_f32_16x16x32_bf16 v[44:47], v[196:199], v[160:163], v[44:47]
	v_mfma_f32_16x16x32_bf16 v[40:43], v[204:207], v[160:163], v[40:43]
	v_mfma_f32_16x16x32_bf16 v[36:39], v[196:199], v[188:191], v[36:39]
	v_mfma_f32_16x16x32_bf16 v[32:35], v[204:207], v[188:191], v[32:35]
	v_mfma_f32_16x16x32_bf16 v[60:63], v[200:203], v[148:151], v[60:63]
	v_mfma_f32_16x16x32_bf16 v[56:59], v[208:211], v[148:151], v[56:59]
	v_mfma_f32_16x16x32_bf16 v[52:55], v[200:203], v[156:159], v[52:55]
	v_mfma_f32_16x16x32_bf16 v[48:51], v[208:211], v[156:159], v[48:51]
	v_mfma_f32_16x16x32_bf16 v[44:47], v[200:203], v[184:187], v[44:47]
	v_mfma_f32_16x16x32_bf16 v[40:43], v[208:211], v[184:187], v[40:43]
	v_mfma_f32_16x16x32_bf16 v[36:39], v[200:203], v[192:195], v[36:39]
	v_mfma_f32_16x16x32_bf16 v[32:35], v[208:211], v[192:195], v[32:35]
	s_setprio 0
	s_mov_b32 m0, s56
	v_lshl_add_u64 v[176:177], v[212:213], 0, s[38:39]
	s_barrier
	ds_read_b128 v[144:147], v220 offset:49152
	ds_read_b128 v[148:151], v220 offset:50176
	ds_read_b128 v[152:155], v220 offset:51200
	ds_read_b128 v[156:159], v220 offset:52224
	ds_read_b128 v[160:163], v220 offset:53248
	ds_read_b128 v[184:187], v220 offset:54272
	ds_read_b128 v[188:191], v220 offset:55296
	ds_read_b128 v[192:195], v220 offset:56320
	global_load_lds_dwordx4 v[176:177], off
	v_lshl_add_u64 v[176:177], v[214:215], 0, s[38:39]
	s_mov_b32 m0, s46
	s_nop 0
	global_load_lds_dwordx4 v[176:177], off
	s_barrier
; #define PG8_STAGE(bufoff, gbase, voff) do { _Pragma("unroll") for (int _i = 0; _i < 2; ++_i) \
;         __builtin_amdgcn_global_load_lds((const unsigned*)((const char*)(gbase) + (voff)[_i]), (PG8_LAS unsigned*)(lds + (bufoff) + ldsw + _i * 8192), 16, 0, 0); } while (0)
; #define PG8_LDA(dst, b, h) do { _Pragma("unroll") for (int m = 0; m < 4; ++m) _Pragma("unroll") for (int k = 0; k < 2; ++k) dst[m][k] = *(const PG8_LAS bf16x8*)(lds + PG8_SA(b, h) + aoff + m * 2048 + k * 1024); } while (0)
; #define PG8_MMA(ai, bj, At, Bt) do { __builtin_amdgcn_s_setprio(1); _Pragma("unroll") for (int m = 0; m < 4; ++m) _Pragma("unroll") for (int n = 0; n < 2; ++n) _Pragma("unroll") for (int k = 0; k < 2; ++k) \
;         acc[ai][bj][m][n] = __builtin_amdgcn_mfma_f32_16x16x32_bf16(Bt[n][k], At[m][k], acc[ai][bj][m][n], 0, 0, 0); __builtin_amdgcn_s_setprio(0); } while (0)
; #define PG8_WAIT_V(n) asm volatile("s_waitcnt vmcnt(" #n ")" ::: "memory")
; #define PG8_WAIT_L(n) asm volatile("s_waitcnt lgkmcnt(" #n ")" ::: "memory")
; #define PG8_BAR __builtin_amdgcn_s_barrier()
; #define PG8_SCHED __builtin_amdgcn_sched_barrier(0)
; template <class Epi, class Sched>
; __device__ __forceinline__ void gemm_phase(PG8_LAS unsigned char* lds, const Gemm g, const Sched& S, const Epi& E) {
;     ...
;             PG8_LDA(At, 1, 1); PG8_STAGE(PG8_SA(1, 0), a3, voffA);
;             PG8_BAR; PG8_WAIT_L(0); PG8_MMA(1, 0, At, B0); PG8_BAR; PG8_SCHED;
;             PG8_STAGE(PG8_SB(1, 1), b3 + hstep, voffB);
;             PG8_WAIT_V(6); PG8_BAR; PG8_MMA(1, 1, At, B1); PG8_BAR;
;     __device__ __forceinline__ void operator()(const f32x4 (&acc)[2][2][4][2], const pg8::Unit& u, int wr, int wc, int fr_, int fq_) const {
;     ...
; #pragma unroll
;             for (int bj = 0; bj < 2; ++bj)
; #pragma unroll
;                 for (int ai = 0; ai < 2; ++ai) {
;                     f32x4 r[4][2];
; #pragma unroll
;                     for (int m = 0; m < 4; ++m) { const size_t off = (size_t)(row0 + ai * 128 + m * 16) * DM + col0 + bj * 128;
; #pragma unroll
;                         for (int n = 0; n < 2; ++n) r[m][n] = *(const f32x4*)(Rraw + off + 4 * n); }
	s_waitcnt lgkmcnt(0)
	s_setprio 1
	s_waitcnt lgkmcnt(0)
	v_mfma_f32_16x16x32_bf16 v[92:95], v[128:131], v[144:147], v[92:95]
	v_mfma_f32_16x16x32_bf16 v[88:91], v[136:139], v[144:147], v[88:91]
	v_mfma_f32_16x16x32_bf16 v[84:87], v[128:131], v[152:155], v[84:87]
	v_mfma_f32_16x16x32_bf16 v[80:83], v[136:139], v[152:155], v[80:83]
	v_mfma_f32_16x16x32_bf16 v[76:79], v[128:131], v[160:163], v[76:79]
	v_mfma_f32_16x16x32_bf16 v[72:75], v[136:139], v[160:163], v[72:75]
	v_mfma_f32_16x16x32_bf16 v[68:71], v[128:131], v[188:191], v[68:71]
	v_mfma_f32_16x16x32_bf16 v[64:67], v[136:139], v[188:191], v[64:67]
	v_mfma_f32_16x16x32_bf16 v[92:95], v[132:135], v[148:151], v[92:95]
	v_mfma_f32_16x16x32_bf16 v[88:91], v[140:143], v[148:151], v[88:91]
	v_mfma_f32_16x16x32_bf16 v[84:87], v[132:135], v[156:159], v[84:87]
	v_mfma_f32_16x16x32_bf16 v[80:83], v[140:143], v[156:159], v[80:83]
	v_mfma_f32_16x16x32_bf16 v[76:79], v[132:135], v[184:187], v[76:79]
	v_mfma_f32_16x16x32_bf16 v[72:75], v[140:143], v[184:187], v[72:75]
	v_mfma_f32_16x16x32_bf16 v[68:71], v[132:135], v[192:195], v[68:71]
	v_mfma_f32_16x16x32_bf16 v[64:67], v[140:143], v[192:195], v[64:67]
	s_setprio 0
	s_barrier
	s_add_u32 s50, s52, 0x160080
	s_addc_u32 s51, s53, 0
	s_add_i32 s26, s27, s58
	v_lshl_add_u64 v[128:129], s[50:51], 0, v[168:169]
	s_mov_b32 m0, s26
	s_nop 0
	global_load_lds_dwordx4 v[128:129], off
	v_lshl_add_u64 v[128:129], s[50:51], 0, v[164:165]
	s_add_i32 m0, s26, 0x2000
	s_nop 0
	global_load_lds_dwordx4 v[128:129], off
	s_waitcnt vmcnt(6)
	s_barrier
	s_setprio 1
	v_mfma_f32_16x16x32_bf16 v[28:31], v[196:199], v[144:147], v[28:31]
	v_mfma_f32_16x16x32_bf16 v[24:27], v[204:207], v[144:147], v[24:27]
	v_mfma_f32_16x16x32_bf16 v[20:23], v[196:199], v[152:155], v[20:23]
	v_mfma_f32_16x16x32_bf16 v[16:19], v[204:207], v[152:155], v[16:19]
	v_mfma_f32_16x16x32_bf16 v[12:15], v[196:199], v[160:163], v[12:15]
	v_mfma_f32_16x16x32_bf16 v[8:11], v[204:207], v[160:163], v[8:11]
	v_mfma_f32_16x16x32_bf16 v[4:7], v[196:199], v[188:191], v[4:7]
	v_mfma_f32_16x16x32_bf16 v[0:3], v[204:207], v[188:191], v[0:3]
	v_mfma_f32_16x16x32_bf16 v[28:31], v[200:203], v[148:151], v[28:31]
	v_mfma_f32_16x16x32_bf16 v[24:27], v[208:211], v[148:151], v[24:27]
	v_mfma_f32_16x16x32_bf16 v[20:23], v[200:203], v[156:159], v[20:23]
	v_mfma_f32_16x16x32_bf16 v[16:19], v[208:211], v[156:159], v[16:19]
	v_mfma_f32_16x16x32_bf16 v[12:15], v[200:203], v[184:187], v[12:15]
	v_mfma_f32_16x16x32_bf16 v[8:11], v[208:211], v[184:187], v[8:11]
	v_mfma_f32_16x16x32_bf16 v[4:7], v[200:203], v[192:195], v[4:7]
	v_mfma_f32_16x16x32_bf16 v[0:3], v[208:211], v[192:195], v[0:3]
	s_setprio 0
	s_add_i32 s29, s29, 2
	s_add_u32 s9, s9, 0x100
	s_addc_u32 s28, s28, 0
	s_cmpk_gt_u32 s29, 0x55
	s_mov_b64 s[50:51], s[44:45]
	s_barrier
	s_cbranch_scc0 .LBB0_600
	s_lshl_b32 s9, s49, 8
	v_readlane_b32 s26, v255, 52
	v_mov_b32_e32 v128, v218
	v_mov_b32_e32 v129, v174
	s_add_i32 s9, s9, s26
	v_readlane_b32 s26, v255, 46
	v_add_u32_e32 v138, s9, v128
	s_lshl_b32 s9, s48, 8
	s_or_b32 s9, s9, s26
	v_readlane_b32 s26, v255, 50
	v_lshl_add_u32 v184, v129, 3, s9
	v_readlane_b32 s27, v255, 51
	v_ashrrev_i32_e32 v185, 31, v184
	s_andn2_b64 vcc, exec, s[26:27]
	v_add_u32_e32 v150, 0x80, v138
	v_add_u32_e32 v156, 16, v138
	v_add_u32_e32 v154, 32, v138
	v_add_u32_e32 v152, 48, v138
	v_add_u32_e32 v148, 0x90, v138
	v_add_u32_e32 v146, 0xa0, v138
	v_add_u32_e32 v144, 0xb0, v138
	s_cbranch_vccnz .LBB0_603
	v_readlane_b32 s26, v253, 22
	v_readlane_b32 s27, v253, 23
	v_ashrrev_i32_e32 v139, 31, v138
	v_lshlrev_b64 v[128:129], 13, v[138:139]
	v_lshl_add_u64 v[194:195], v[184:185], 1, s[26:27]
	v_readlane_b32 s26, v255, 44
	v_readlane_b32 s27, v255, 45
	v_ashrrev_i32_e32 v157, 31, v156
	v_ashrrev_i32_e32 v155, 31, v154
	v_lshl_add_u64 v[136:137], v[184:185], 2, s[26:27]
	v_lshl_add_u64 v[162:163], v[136:137], 0, v[128:129]
	global_load_dwordx4 v[186:189], v[162:163], off offset:16
	global_load_dwordx4 v[190:193], v[162:163], off
	v_lshlrev_b64 v[128:129], 13, v[156:157]
	v_lshl_add_u64 v[160:161], v[136:137], 0, v[128:129]
	global_load_dwordx4 v[196:199], v[160:161], off offset:16
	global_load_dwordx4 v[200:203], v[160:161], off
	v_lshlrev_b64 v[128:129], 13, v[154:155]
	v_lshl_add_u64 v[158:159], v[136:137], 0, v[128:129]
	global_load_dwordx4 v[204:207], v[158:159], off offset:16
	global_load_dwordx4 v[208:211], v[158:159], off
	v_ashrrev_i32_e32 v153, 31, v152
	v_lshlrev_b64 v[128:129], 13, v[152:153]
	v_lshl_add_u64 v[142:143], v[136:137], 0, v[128:129]
	global_load_dwordx4 v[128:131], v[142:143], off offset:16
	global_load_dwordx4 v[132:135], v[142:143], off
	v_ashrrev_i32_e32 v151, 31, v150
	v_ashrrev_i32_e32 v149, 31, v148
	v_ashrrev_i32_e32 v147, 31, v146
	v_ashrrev_i32_e32 v145, 31, v144
	s_waitcnt vmcnt(0)
; __device__ __forceinline__ u32x2 pack4h(f32x4 v) { const h16x4 h = __builtin_convertvector(v, h16x4); return __builtin_bit_cast(u32x2, h); }
;     __device__ __forceinline__ void operator()(const f32x4 (&acc)[2][2][4][2], const pg8::Unit& u, int wr, int wc, int fr_, int fq_) const {
;     ...
;                     for (int m = 0; m < 4; ++m) { const size_t off = (size_t)(row0 + ai * 128 + m * 16) * DM + col0 + bj * 128;
; #pragma unroll
;                         for (int n = 0; n < 2; ++n) r[m][n] = *(const f32x4*)(Rraw + off + 4 * n); }
;                     asm volatile("" ::: "memory");
; #pragma unroll
;                     for (int m = 0; m < 4; ++m) { const size_t off = (size_t)(row0 + ai * 128 + m * 16) * DM + col0 + bj * 128;
;                         const u32x2 o0 = pack4h(r[m][0] * ALPHA + acc[ai][bj][m][0] * s), o1 = pack4h(r[m][1] * ALPHA + acc[ai][bj][m][1] * s);
;                         u32x4 w; w.x = o0.x; w.y = o0.y; w.z = o1.x; w.w = o1.y; *(u32x4*)(Z + off) = w; }
	v_pk_mul_f32 v[140:141], v[192:193], s[36:37] op_sel_hi:[1,0]
	s_nop 0
	v_pk_fma_f32 v[140:141], v[126:127], 0.5, v[140:141] op_sel_hi:[1,0,1]
	v_pk_mul_f32 v[176:177], v[190:191], s[36:37] op_sel_hi:[1,0]
	v_cvt_pk_f16_f32 v191, v140, v141
	v_pk_mul_f32 v[140:141], v[188:189], s[36:37] op_sel_hi:[1,0]
	v_pk_fma_f32 v[176:177], v[124:125], 0.5, v[176:177] op_sel_hi:[1,0,1]
	v_pk_fma_f32 v[140:141], v[122:123], 0.5, v[140:141] op_sel_hi:[1,0,1]
	v_cvt_pk_f16_f32 v190, v176, v177
	v_cvt_pk_f16_f32 v193, v140, v141
	v_lshlrev_b64 v[140:141], 12, v[138:139]
	v_pk_mul_f32 v[176:177], v[186:187], s[36:37] op_sel_hi:[1,0]
	v_lshl_add_u64 v[188:189], v[194:195], 0, v[140:141]
	v_pk_mul_f32 v[140:141], v[202:203], s[36:37] op_sel_hi:[1,0]
	v_pk_fma_f32 v[176:177], v[120:121], 0.5, v[176:177] op_sel_hi:[1,0,1]
	v_pk_fma_f32 v[140:141], v[118:119], 0.5, v[140:141] op_sel_hi:[1,0,1]
	v_cvt_pk_f16_f32 v192, v176, v177
	v_pk_mul_f32 v[176:177], v[200:201], s[36:37] op_sel_hi:[1,0]
	v_cvt_pk_f16_f32 v201, v140, v141
	v_pk_mul_f32 v[140:141], v[198:199], s[36:37] op_sel_hi:[1,0]
	v_pk_fma_f32 v[176:177], v[116:117], 0.5, v[176:177] op_sel_hi:[1,0,1]
	v_pk_fma_f32 v[140:141], v[114:115], 0.5, v[140:141] op_sel_hi:[1,0,1]
	global_store_dwordx4 v[188:189], v[190:193], off sc1
	v_cvt_pk_f16_f32 v203, v140, v141
	v_lshlrev_b64 v[140:141], 12, v[156:157]
	v_cvt_pk_f16_f32 v200, v176, v177
	v_pk_mul_f32 v[176:177], v[196:197], s[36:37] op_sel_hi:[1,0]
	v_lshl_add_u64 v[190:191], v[194:195], 0, v[140:141]
	v_pk_mul_f32 v[140:141], v[210:211], s[36:37] op_sel_hi:[1,0]
	v_pk_fma_f32 v[176:177], v[112:113], 0.5, v[176:177] op_sel_hi:[1,0,1]
	v_pk_fma_f32 v[140:141], v[110:111], 0.5, v[140:141] op_sel_hi:[1,0,1]
	v_cvt_pk_f16_f32 v202, v176, v177
	v_pk_mul_f32 v[176:177], v[208:209], s[36:37] op_sel_hi:[1,0]
	v_cvt_pk_f16_f32 v197, v140, v141
	v_pk_mul_f32 v[140:141], v[206:207], s[36:37] op_sel_hi:[1,0]
	v_pk_fma_f32 v[176:177], v[108:109], 0.5, v[176:177] op_sel_hi:[1,0,1]
	v_pk_fma_f32 v[140:141], v[106:107], 0.5, v[140:141] op_sel_hi:[1,0,1]
	v_pk_mul_f32 v[134:135], v[134:135], s[36:37] op_sel_hi:[1,0]
	v_pk_mul_f32 v[128:129], v[128:129], s[36:37] op_sel_hi:[1,0]
	v_cvt_pk_f16_f32 v196, v176, v177
	v_pk_mul_f32 v[176:177], v[204:205], s[36:37] op_sel_hi:[1,0]
	v_cvt_pk_f16_f32 v199, v140, v141
	v_lshlrev_b64 v[140:141], 12, v[154:155]
	v_pk_mul_f32 v[132:133], v[132:133], s[36:37] op_sel_hi:[1,0]
	v_pk_fma_f32 v[134:135], v[102:103], 0.5, v[134:135] op_sel_hi:[1,0,1]
	v_pk_mul_f32 v[130:131], v[130:131], s[36:37] op_sel_hi:[1,0]
	v_pk_fma_f32 v[128:129], v[96:97], 0.5, v[128:129] op_sel_hi:[1,0,1]
	v_pk_fma_f32 v[176:177], v[104:105], 0.5, v[176:177] op_sel_hi:[1,0,1]
	v_lshl_add_u64 v[192:193], v[194:195], 0, v[140:141]
	v_pk_fma_f32 v[140:141], v[100:101], 0.5, v[132:133] op_sel_hi:[1,0,1]
	v_cvt_pk_f16_f32 v133, v134, v135
	v_pk_fma_f32 v[130:131], v[98:99], 0.5, v[130:131] op_sel_hi:[1,0,1]
	v_cvt_pk_f16_f32 v134, v128, v129
	v_lshlrev_b64 v[128:129], 12, v[152:153]
	v_cvt_pk_f16_f32 v198, v176, v177
	v_cvt_pk_f16_f32 v132, v140, v141
	v_cvt_pk_f16_f32 v135, v130, v131
	v_lshl_add_u64 v[140:141], v[194:195], 0, v[128:129]
	v_lshlrev_b64 v[128:129], 13, v[150:151]
	global_store_dwordx4 v[190:191], v[200:203], off sc1
	global_store_dwordx4 v[192:193], v[196:199], off sc1
	global_store_dwordx4 v[140:141], v[132:135], off sc1
	v_lshl_add_u64 v[186:187], v[136:137], 0, v[128:129]
	global_load_dwordx4 v[202:205], v[186:187], off offset:16
	global_load_dwordx4 v[206:209], v[186:187], off
	v_lshlrev_b64 v[128:129], 13, v[148:149]
	v_lshl_add_u64 v[200:201], v[136:137], 0, v[128:129]
	global_load_dwordx4 v[210:213], v[200:201], off offset:16
	global_load_dwordx4 v[214:217], v[200:201], off
	v_lshlrev_b64 v[128:129], 13, v[146:147]
	v_lshl_add_u64 v[198:199], v[136:137], 0, v[128:129]
	global_load_dwordx4 v[222:225], v[198:199], off offset:16
	global_load_dwordx4 v[226:229], v[198:199], off
	v_lshlrev_b64 v[128:129], 13, v[144:145]
	v_lshl_add_u64 v[196:197], v[136:137], 0, v[128:129]
	global_load_dwordx4 v[130:133], v[196:197], off offset:16
	global_load_dwordx4 v[134:137], v[196:197], off
	s_waitcnt vmcnt(0)
	v_pk_mul_f32 v[128:129], v[208:209], s[36:37] op_sel_hi:[1,0]
	s_nop 0
	v_pk_fma_f32 v[128:129], v[94:95], 0.5, v[128:129] op_sel_hi:[1,0,1]
	v_pk_mul_f32 v[176:177], v[206:207], s[36:37] op_sel_hi:[1,0]
	v_cvt_pk_f16_f32 v207, v128, v129
	v_pk_mul_f32 v[128:129], v[204:205], s[36:37] op_sel_hi:[1,0]
	v_pk_fma_f32 v[176:177], v[92:93], 0.5, v[176:177] op_sel_hi:[1,0,1]
	v_pk_fma_f32 v[128:129], v[90:91], 0.5, v[128:129] op_sel_hi:[1,0,1]
	v_cvt_pk_f16_f32 v206, v176, v177
	v_pk_mul_f32 v[176:177], v[202:203], s[36:37] op_sel_hi:[1,0]
	v_cvt_pk_f16_f32 v209, v128, v129
	v_lshlrev_b64 v[128:129], 12, v[150:151]
	v_pk_fma_f32 v[176:177], v[88:89], 0.5, v[176:177] op_sel_hi:[1,0,1]
	v_lshl_add_u64 v[202:203], v[194:195], 0, v[128:129]
	v_pk_mul_f32 v[128:129], v[216:217], s[36:37] op_sel_hi:[1,0]
	v_cvt_pk_f16_f32 v208, v176, v177
	v_pk_fma_f32 v[128:129], v[86:87], 0.5, v[128:129] op_sel_hi:[1,0,1]
	global_store_dwordx4 v[202:203], v[206:209], off sc1
	v_pk_mul_f32 v[176:177], v[214:215], s[36:37] op_sel_hi:[1,0]
	v_pk_mul_f32 v[134:135], v[134:135], s[36:37] op_sel_hi:[1,0]
	v_cvt_pk_f16_f32 v207, v128, v129
	v_pk_mul_f32 v[128:129], v[212:213], s[36:37] op_sel_hi:[1,0]
	v_pk_fma_f32 v[176:177], v[84:85], 0.5, v[176:177] op_sel_hi:[1,0,1]
	v_pk_fma_f32 v[128:129], v[82:83], 0.5, v[128:129] op_sel_hi:[1,0,1]
	v_cvt_pk_f16_f32 v206, v176, v177
	v_pk_mul_f32 v[176:177], v[210:211], s[36:37] op_sel_hi:[1,0]
	v_cvt_pk_f16_f32 v209, v128, v129
; __device__ __forceinline__ u32x2 pack4h(f32x4 v) { const h16x4 h = __builtin_convertvector(v, h16x4); return __builtin_bit_cast(u32x2, h); }
;     __device__ __forceinline__ void operator()(const f32x4 (&acc)[2][2][4][2], const pg8::Unit& u, int wr, int wc, int fr_, int fq_) const {
;     ...
;                     for (int m = 0; m < 4; ++m) { const size_t off = (size_t)(row0 + ai * 128 + m * 16) * DM + col0 + bj * 128;
; #pragma unroll
;                         for (int n = 0; n < 2; ++n) r[m][n] = *(const f32x4*)(Rraw + off + 4 * n); }
;                     asm volatile("" ::: "memory");
; #pragma unroll
;                     for (int m = 0; m < 4; ++m) { const size_t off = (size_t)(row0 + ai * 128 + m * 16) * DM + col0 + bj * 128;
;                         const u32x2 o0 = pack4h(r[m][0] * ALPHA + acc[ai][bj][m][0] * s), o1 = pack4h(r[m][1] * ALPHA + acc[ai][bj][m][1] * s);
;                         u32x4 w; w.x = o0.x; w.y = o0.y; w.z = o1.x; w.w = o1.y; *(u32x4*)(Z + off) = w; }
	v_lshlrev_b64 v[128:129], 12, v[148:149]
	v_pk_fma_f32 v[176:177], v[80:81], 0.5, v[176:177] op_sel_hi:[1,0,1]
	v_lshl_add_u64 v[204:205], v[194:195], 0, v[128:129]
	v_pk_mul_f32 v[128:129], v[228:229], s[36:37] op_sel_hi:[1,0]
	v_cvt_pk_f16_f32 v208, v176, v177
	v_pk_fma_f32 v[128:129], v[78:79], 0.5, v[128:129] op_sel_hi:[1,0,1]
	global_store_dwordx4 v[204:205], v[206:209], off sc1
	v_pk_mul_f32 v[176:177], v[226:227], s[36:37] op_sel_hi:[1,0]
	v_pk_mul_f32 v[132:133], v[132:133], s[36:37] op_sel_hi:[1,0]
	v_cvt_pk_f16_f32 v209, v128, v129
	v_pk_mul_f32 v[128:129], v[224:225], s[36:37] op_sel_hi:[1,0]
	v_pk_fma_f32 v[176:177], v[76:77], 0.5, v[176:177] op_sel_hi:[1,0,1]
	v_pk_fma_f32 v[128:129], v[74:75], 0.5, v[128:129] op_sel_hi:[1,0,1]
	v_cvt_pk_f16_f32 v208, v176, v177
	v_cvt_pk_f16_f32 v211, v128, v129
	v_lshlrev_b64 v[128:129], 12, v[146:147]
	v_lshl_add_u64 v[206:207], v[194:195], 0, v[128:129]
	v_pk_mul_f32 v[128:129], v[136:137], s[36:37] op_sel_hi:[1,0]
	v_pk_mul_f32 v[176:177], v[222:223], s[36:37] op_sel_hi:[1,0]
	v_pk_fma_f32 v[128:129], v[70:71], 0.5, v[128:129] op_sel_hi:[1,0,1]
	v_pk_fma_f32 v[134:135], v[68:69], 0.5, v[134:135] op_sel_hi:[1,0,1]
	v_pk_mul_f32 v[130:131], v[130:131], s[36:37] op_sel_hi:[1,0]
	v_pk_fma_f32 v[132:133], v[66:67], 0.5, v[132:133] op_sel_hi:[1,0,1]
	v_pk_fma_f32 v[176:177], v[72:73], 0.5, v[176:177] op_sel_hi:[1,0,1]
	v_cvt_pk_f16_f32 v129, v128, v129
	v_cvt_pk_f16_f32 v128, v134, v135
	v_pk_fma_f32 v[134:135], v[64:65], 0.5, v[130:131] op_sel_hi:[1,0,1]
	v_cvt_pk_f16_f32 v131, v132, v133
	v_lshlrev_b64 v[132:133], 12, v[144:145]
	v_cvt_pk_f16_f32 v210, v176, v177
	v_cvt_pk_f16_f32 v130, v134, v135
	v_lshl_add_u64 v[132:133], v[194:195], 0, v[132:133]
	global_store_dwordx4 v[206:207], v[208:211], off sc1
	global_store_dwordx4 v[132:133], v[128:131], off sc1
	global_load_dwordx4 v[128:131], v[162:163], off offset:528
	s_nop 0
	global_load_dwordx4 v[134:137], v[162:163], off offset:512
	global_load_dwordx4 v[208:211], v[160:161], off offset:528
	s_nop 0
	global_load_dwordx4 v[160:163], v[160:161], off offset:512
	s_nop 0
	global_load_dwordx4 v[212:215], v[158:159], off offset:528
	global_load_dwordx4 v[222:225], v[158:159], off offset:512
	global_load_dwordx4 v[226:229], v[142:143], off offset:528
	global_load_dwordx4 v[230:233], v[142:143], off offset:512
	s_waitcnt vmcnt(0)
	v_pk_mul_f32 v[130:131], v[130:131], s[36:37] op_sel_hi:[1,0]
	v_pk_mul_f32 v[136:137], v[136:137], s[36:37] op_sel_hi:[1,0]
	v_pk_mul_f32 v[128:129], v[128:129], s[36:37] op_sel_hi:[1,0]
	v_pk_mul_f32 v[134:135], v[134:135], s[36:37] op_sel_hi:[1,0]
	v_pk_fma_f32 v[136:137], v[62:63], 0.5, v[136:137] op_sel_hi:[1,0,1]
	v_pk_fma_f32 v[130:131], v[58:59], 0.5, v[130:131] op_sel_hi:[1,0,1]
	v_pk_fma_f32 v[128:129], v[56:57], 0.5, v[128:129] op_sel_hi:[1,0,1]
	v_pk_fma_f32 v[142:143], v[60:61], 0.5, v[134:135] op_sel_hi:[1,0,1]
	v_cvt_pk_f16_f32 v135, v136, v137
	v_cvt_pk_f16_f32 v137, v130, v131
	v_cvt_pk_f16_f32 v136, v128, v129
	v_pk_mul_f32 v[128:129], v[162:163], s[36:37] op_sel_hi:[1,0]
	v_pk_mul_f32 v[130:131], v[160:161], s[36:37] op_sel_hi:[1,0]
	v_cvt_pk_f16_f32 v134, v142, v143
	v_pk_fma_f32 v[128:129], v[54:55], 0.5, v[128:129] op_sel_hi:[1,0,1]
	v_pk_fma_f32 v[130:131], v[52:53], 0.5, v[130:131] op_sel_hi:[1,0,1]
	global_store_dwordx4 v[188:189], v[134:137], off offset:256 sc1
	v_cvt_pk_f16_f32 v129, v128, v129
	v_cvt_pk_f16_f32 v128, v130, v131
	v_pk_mul_f32 v[130:131], v[210:211], s[36:37] op_sel_hi:[1,0]
	v_pk_mul_f32 v[134:135], v[208:209], s[36:37] op_sel_hi:[1,0]
	v_pk_fma_f32 v[130:131], v[50:51], 0.5, v[130:131] op_sel_hi:[1,0,1]
	v_pk_fma_f32 v[134:135], v[48:49], 0.5, v[134:135] op_sel_hi:[1,0,1]
	v_cvt_pk_f16_f32 v131, v130, v131
	v_cvt_pk_f16_f32 v130, v134, v135
	global_store_dwordx4 v[190:191], v[128:131], off offset:256 sc1
	v_pk_mul_f32 v[134:135], v[212:213], s[36:37] op_sel_hi:[1,0]
	s_nop 0
	v_pk_mul_f32 v[128:129], v[224:225], s[36:37] op_sel_hi:[1,0]
	v_pk_mul_f32 v[130:131], v[222:223], s[36:37] op_sel_hi:[1,0]
	v_pk_fma_f32 v[128:129], v[46:47], 0.5, v[128:129] op_sel_hi:[1,0,1]
	v_pk_fma_f32 v[130:131], v[44:45], 0.5, v[130:131] op_sel_hi:[1,0,1]
	v_cvt_pk_f16_f32 v129, v128, v129
	v_cvt_pk_f16_f32 v128, v130, v131
	v_pk_mul_f32 v[130:131], v[214:215], s[36:37] op_sel_hi:[1,0]
	v_pk_fma_f32 v[134:135], v[40:41], 0.5, v[134:135] op_sel_hi:[1,0,1]
	v_pk_fma_f32 v[130:131], v[42:43], 0.5, v[130:131] op_sel_hi:[1,0,1]
	s_nop 0
	v_cvt_pk_f16_f32 v131, v130, v131
	v_cvt_pk_f16_f32 v130, v134, v135
	global_store_dwordx4 v[192:193], v[128:131], off offset:256 sc1
	v_pk_mul_f32 v[134:135], v[226:227], s[36:37] op_sel_hi:[1,0]
	s_nop 0
	v_pk_mul_f32 v[128:129], v[232:233], s[36:37] op_sel_hi:[1,0]
	v_pk_mul_f32 v[130:131], v[230:231], s[36:37] op_sel_hi:[1,0]
	v_pk_fma_f32 v[128:129], v[38:39], 0.5, v[128:129] op_sel_hi:[1,0,1]
	v_pk_fma_f32 v[130:131], v[36:37], 0.5, v[130:131] op_sel_hi:[1,0,1]
	v_cvt_pk_f16_f32 v129, v128, v129
	v_cvt_pk_f16_f32 v128, v130, v131
	v_pk_mul_f32 v[130:131], v[228:229], s[36:37] op_sel_hi:[1,0]
	v_pk_fma_f32 v[134:135], v[32:33], 0.5, v[134:135] op_sel_hi:[1,0,1]
	v_pk_fma_f32 v[130:131], v[34:35], 0.5, v[130:131] op_sel_hi:[1,0,1]
	s_nop 0
	v_cvt_pk_f16_f32 v131, v130, v131
	v_cvt_pk_f16_f32 v130, v134, v135
	global_store_dwordx4 v[140:141], v[128:131], off offset:256 sc1
	global_load_dwordx4 v[128:131], v[186:187], off offset:528
	s_nop 0
	global_load_dwordx4 v[134:137], v[186:187], off offset:512
	global_load_dwordx4 v[140:143], v[200:201], off offset:528
	global_load_dwordx4 v[158:161], v[200:201], off offset:512
	s_nop 0
	global_load_dwordx4 v[186:189], v[198:199], off offset:528
	global_load_dwordx4 v[190:193], v[198:199], off offset:512
	s_nop 0
	global_load_dwordx4 v[198:201], v[196:197], off offset:528
	s_nop 0
	global_load_dwordx4 v[194:197], v[196:197], off offset:512
	s_waitcnt vmcnt(0)
; __device__ __forceinline__ u32x2 pack4h(f32x4 v) { const h16x4 h = __builtin_convertvector(v, h16x4); return __builtin_bit_cast(u32x2, h); }
;     __device__ __forceinline__ void operator()(const f32x4 (&acc)[2][2][4][2], const pg8::Unit& u, int wr, int wc, int fr_, int fq_) const {
;     ...
; #pragma unroll
;                     for (int m = 0; m < 4; ++m) { const size_t off = (size_t)(row0 + ai * 128 + m * 16) * DM + col0 + bj * 128;
;                         const u32x2 o0 = pack4h(r[m][0] * ALPHA + acc[ai][bj][m][0] * s), o1 = pack4h(r[m][1] * ALPHA + acc[ai][bj][m][1] * s);
;                         u32x4 w; w.x = o0.x; w.y = o0.y; w.z = o1.x; w.w = o1.y; *(u32x4*)(Z + off) = w; }
	v_pk_mul_f32 v[130:131], v[130:131], s[36:37] op_sel_hi:[1,0]
	v_pk_mul_f32 v[136:137], v[136:137], s[36:37] op_sel_hi:[1,0]
	v_pk_mul_f32 v[128:129], v[128:129], s[36:37] op_sel_hi:[1,0]
	v_pk_mul_f32 v[134:135], v[134:135], s[36:37] op_sel_hi:[1,0]
	v_pk_fma_f32 v[136:137], v[30:31], 0.5, v[136:137] op_sel_hi:[1,0,1]
	v_pk_fma_f32 v[130:131], v[26:27], 0.5, v[130:131] op_sel_hi:[1,0,1]
	v_pk_fma_f32 v[128:129], v[24:25], 0.5, v[128:129] op_sel_hi:[1,0,1]
	v_pk_fma_f32 v[162:163], v[28:29], 0.5, v[134:135] op_sel_hi:[1,0,1]
	v_cvt_pk_f16_f32 v135, v136, v137
	v_cvt_pk_f16_f32 v137, v130, v131
	v_cvt_pk_f16_f32 v136, v128, v129
	v_pk_mul_f32 v[128:129], v[160:161], s[36:37] op_sel_hi:[1,0]
	v_pk_mul_f32 v[130:131], v[158:159], s[36:37] op_sel_hi:[1,0]
	v_cvt_pk_f16_f32 v134, v162, v163
	v_pk_fma_f32 v[128:129], v[22:23], 0.5, v[128:129] op_sel_hi:[1,0,1]
	v_pk_fma_f32 v[130:131], v[20:21], 0.5, v[130:131] op_sel_hi:[1,0,1]
	global_store_dwordx4 v[202:203], v[134:137], off offset:256 sc1
	v_cvt_pk_f16_f32 v129, v128, v129
	v_cvt_pk_f16_f32 v128, v130, v131
	v_pk_mul_f32 v[130:131], v[142:143], s[36:37] op_sel_hi:[1,0]
	v_pk_mul_f32 v[134:135], v[140:141], s[36:37] op_sel_hi:[1,0]
	v_pk_fma_f32 v[130:131], v[18:19], 0.5, v[130:131] op_sel_hi:[1,0,1]
	v_pk_fma_f32 v[134:135], v[16:17], 0.5, v[134:135] op_sel_hi:[1,0,1]
	v_cvt_pk_f16_f32 v131, v130, v131
	v_cvt_pk_f16_f32 v130, v134, v135
	global_store_dwordx4 v[204:205], v[128:131], off offset:256 sc1
	v_pk_mul_f32 v[134:135], v[186:187], s[36:37] op_sel_hi:[1,0]
	s_nop 0
	v_pk_mul_f32 v[128:129], v[192:193], s[36:37] op_sel_hi:[1,0]
	v_pk_mul_f32 v[130:131], v[190:191], s[36:37] op_sel_hi:[1,0]
	v_pk_fma_f32 v[128:129], v[14:15], 0.5, v[128:129] op_sel_hi:[1,0,1]
	v_pk_fma_f32 v[130:131], v[12:13], 0.5, v[130:131] op_sel_hi:[1,0,1]
	v_cvt_pk_f16_f32 v129, v128, v129
	v_cvt_pk_f16_f32 v128, v130, v131
	v_pk_mul_f32 v[130:131], v[188:189], s[36:37] op_sel_hi:[1,0]
	v_pk_fma_f32 v[134:135], v[8:9], 0.5, v[134:135] op_sel_hi:[1,0,1]
	v_pk_fma_f32 v[130:131], v[10:11], 0.5, v[130:131] op_sel_hi:[1,0,1]
	s_nop 0
	v_cvt_pk_f16_f32 v131, v130, v131
	v_cvt_pk_f16_f32 v130, v134, v135
	global_store_dwordx4 v[206:207], v[128:131], off offset:256 sc1
	v_pk_mul_f32 v[134:135], v[198:199], s[36:37] op_sel_hi:[1,0]
	s_nop 0
	v_pk_mul_f32 v[128:129], v[196:197], s[36:37] op_sel_hi:[1,0]
	v_pk_mul_f32 v[130:131], v[194:195], s[36:37] op_sel_hi:[1,0]
	v_pk_fma_f32 v[128:129], v[6:7], 0.5, v[128:129] op_sel_hi:[1,0,1]
	v_pk_fma_f32 v[130:131], v[4:5], 0.5, v[130:131] op_sel_hi:[1,0,1]
	v_cvt_pk_f16_f32 v129, v128, v129
	v_cvt_pk_f16_f32 v128, v130, v131
	v_pk_mul_f32 v[130:131], v[200:201], s[36:37] op_sel_hi:[1,0]
	v_pk_fma_f32 v[134:135], v[0:1], 0.5, v[134:135] op_sel_hi:[1,0,1]
	v_pk_fma_f32 v[130:131], v[2:3], 0.5, v[130:131] op_sel_hi:[1,0,1]
	s_nop 0
	v_cvt_pk_f16_f32 v131, v130, v131
	v_cvt_pk_f16_f32 v130, v134, v135
	global_store_dwordx4 v[132:133], v[128:131], off offset:256 sc1
	s_cbranch_execnz .LBB0_588
	s_branch .LBB0_587

; #define PG8_STAGE(bufoff, gbase, voff) do { _Pragma("unroll") for (int _i = 0; _i < 2; ++_i) \
;         __builtin_amdgcn_global_load_lds((const unsigned*)((const char*)(gbase) + (voff)[_i]), (PG8_LAS unsigned*)(lds + (bufoff) + ldsw + _i * 8192), 16, 0, 0); } while (0)
; #define PG8_LDA(dst, b, h) do { _Pragma("unroll") for (int m = 0; m < 4; ++m) _Pragma("unroll") for (int k = 0; k < 2; ++k) dst[m][k] = *(const PG8_LAS bf16x8*)(lds + PG8_SA(b, h) + aoff + m * 2048 + k * 1024); } while (0)
; #define PG8_LDB(dst, b, h) do { _Pragma("unroll") for (int n = 0; n < 2; ++n) _Pragma("unroll") for (int k = 0; k < 2; ++k) dst[n][k] = *(const PG8_LAS bf16x8*)(lds + PG8_SB(b, h) + boff + n * 2048 + k * 1024); } while (0)
; #define PG8_MMA(ai, bj, At, Bt) do { __builtin_amdgcn_s_setprio(1); _Pragma("unroll") for (int m = 0; m < 4; ++m) _Pragma("unroll") for (int n = 0; n < 2; ++n) _Pragma("unroll") for (int k = 0; k < 2; ++k) \
;         acc[ai][bj][m][n] = __builtin_amdgcn_mfma_f32_16x16x32_bf16(Bt[n][k], At[m][k], acc[ai][bj][m][n], 0, 0, 0); __builtin_amdgcn_s_setprio(0); } while (0)
; #define PG8_WAIT_V(n) asm volatile("s_waitcnt vmcnt(" #n ")" ::: "memory")
; #define PG8_WAIT_L(n) asm volatile("s_waitcnt lgkmcnt(" #n ")" ::: "memory")
; #define PG8_BAR __builtin_amdgcn_s_barrier()
; #define PG8_SCHED __builtin_amdgcn_sched_barrier(0)
; template <class Epi, class Sched>
; __device__ __forceinline__ void gemm_phase(PG8_LAS unsigned char* lds, const Gemm g, const Sched& S, const Epi& E) {
;     ...
;             PG8_LDB(B0, 0, 0); PG8_SCHED; PG8_LDA(At, 0, 0); PG8_STAGE(PG8_SA(1, 1), a1 + hstep, voffA);
;             PG8_WAIT_L(8); PG8_BAR; PG8_WAIT_L(0); PG8_MMA(0, 0, At, B0); PG8_BAR; PG8_SCHED;
;             PG8_LDB(B1, 0, 1); PG8_STAGE(PG8_SB(0, 0), b2, voffB);
;             PG8_BAR; PG8_WAIT_L(0); PG8_MMA(0, 1, At, B1); PG8_BAR;
;             PG8_LDA(At, 0, 1); PG8_STAGE(PG8_SA(0, 0), a2, voffA);
;             PG8_BAR; PG8_WAIT_L(0); PG8_MMA(1, 0, At, B0); PG8_BAR; PG8_SCHED;
;             PG8_STAGE(PG8_SB(0, 1), b2 + hstep, voffB);
;             PG8_WAIT_V(6); PG8_BAR; PG8_MMA(1, 1, At, B1); PG8_BAR;
.LBB0_617:
	s_add_u32 s40, s48, 0xfff80080
	s_addc_u32 s41, s49, -1
	s_add_i32 s26, 0, 0x10000
	v_add_u32_e32 v138, s26, v141
	ds_read_b128 v[144:147], v138
	ds_read_b128 v[148:151], v138 offset:1024
	ds_read_b128 v[152:155], v138 offset:2048
	ds_read_b128 v[156:159], v138 offset:3072
	s_cmp_eq_u32 s29, 28
	s_cselect_b32 s53, s43, s41
	s_cselect_b32 s52, s9, s40
	s_cselect_b32 s51, s1, s28
	s_cselect_b32 s50, vcc_lo, vcc_hi
	v_lshl_add_u64 v[138:139], s[48:49], 0, v[134:135]
	s_add_i32 m0, s57, 0xc000
	ds_read_b128 v[160:163], v143
	ds_read_b128 v[164:167], v143 offset:1024
	ds_read_b128 v[168:171], v143 offset:2048
	ds_read_b128 v[180:183], v143 offset:3072
	ds_read_b128 v[184:187], v143 offset:4096
	ds_read_b128 v[188:191], v143 offset:5120
	ds_read_b128 v[192:195], v143 offset:6144
	ds_read_b128 v[196:199], v143 offset:7168
	global_load_lds_dwordx4 v[138:139], off
	v_lshl_add_u64 v[138:139], s[48:49], 0, v[136:137]
	s_add_i32 m0, s57, 0xe000
	s_nop 0
	global_load_lds_dwordx4 v[138:139], off
	s_waitcnt lgkmcnt(8)
	s_barrier
	s_waitcnt lgkmcnt(0)
	s_setprio 1
	s_waitcnt lgkmcnt(0)
	v_mfma_f32_16x16x32_bf16 v[124:127], v[144:147], v[160:163], v[124:127]
	v_mfma_f32_16x16x32_bf16 v[116:119], v[152:155], v[160:163], v[116:119]
	v_mfma_f32_16x16x32_bf16 v[108:111], v[144:147], v[168:171], v[108:111]
	v_mfma_f32_16x16x32_bf16 v[100:103], v[152:155], v[168:171], v[100:103]
	v_mfma_f32_16x16x32_bf16 v[92:95], v[144:147], v[184:187], v[92:95]
	v_mfma_f32_16x16x32_bf16 v[84:87], v[152:155], v[184:187], v[84:87]
	v_mfma_f32_16x16x32_bf16 v[76:79], v[144:147], v[192:195], v[76:79]
	v_mfma_f32_16x16x32_bf16 v[68:71], v[152:155], v[192:195], v[68:71]
	v_mfma_f32_16x16x32_bf16 v[124:127], v[148:151], v[164:167], v[124:127]
	v_mfma_f32_16x16x32_bf16 v[116:119], v[156:159], v[164:167], v[116:119]
	v_mfma_f32_16x16x32_bf16 v[108:111], v[148:151], v[180:183], v[108:111]
	v_mfma_f32_16x16x32_bf16 v[100:103], v[156:159], v[180:183], v[100:103]
	v_mfma_f32_16x16x32_bf16 v[92:95], v[148:151], v[188:191], v[92:95]
	v_mfma_f32_16x16x32_bf16 v[84:87], v[156:159], v[188:191], v[84:87]
	v_mfma_f32_16x16x32_bf16 v[76:79], v[148:151], v[196:199], v[76:79]
	v_mfma_f32_16x16x32_bf16 v[68:71], v[156:159], v[196:199], v[68:71]
	s_setprio 0
	s_barrier
	s_add_i32 s27, 0, 0x14000
	v_add_u32_e32 v138, s27, v141
	s_add_i32 s26, s26, s56
	ds_read_b128 v[200:203], v138
	ds_read_b128 v[204:207], v138 offset:1024
	ds_read_b128 v[208:211], v138 offset:2048
	ds_read_b128 v[212:215], v138 offset:3072
	v_lshl_add_u64 v[138:139], s[50:51], 0, v[172:173]
	s_mov_b32 m0, s26
	v_lshl_add_u64 v[176:177], s[50:51], 0, v[128:129]
	global_load_lds_dwordx4 v[138:139], off
	s_add_i32 m0, s26, 0x2000
	s_nop 0
	global_load_lds_dwordx4 v[176:177], off
	s_barrier
	s_waitcnt lgkmcnt(0)
	s_setprio 1
	s_waitcnt lgkmcnt(0)
	v_mfma_f32_16x16x32_bf16 v[120:123], v[200:203], v[160:163], v[120:123]
	v_mfma_f32_16x16x32_bf16 v[112:115], v[208:211], v[160:163], v[112:115]
	v_mfma_f32_16x16x32_bf16 v[104:107], v[200:203], v[168:171], v[104:107]
	v_mfma_f32_16x16x32_bf16 v[96:99], v[208:211], v[168:171], v[96:99]
	v_mfma_f32_16x16x32_bf16 v[88:91], v[200:203], v[184:187], v[88:91]
	v_mfma_f32_16x16x32_bf16 v[80:83], v[208:211], v[184:187], v[80:83]
	v_mfma_f32_16x16x32_bf16 v[72:75], v[200:203], v[192:195], v[72:75]
	v_mfma_f32_16x16x32_bf16 v[64:67], v[208:211], v[192:195], v[64:67]
	v_mfma_f32_16x16x32_bf16 v[120:123], v[204:207], v[164:167], v[120:123]
	v_mfma_f32_16x16x32_bf16 v[112:115], v[212:215], v[164:167], v[112:115]
	v_mfma_f32_16x16x32_bf16 v[104:107], v[204:207], v[180:183], v[104:107]
	v_mfma_f32_16x16x32_bf16 v[96:99], v[212:215], v[180:183], v[96:99]
	v_mfma_f32_16x16x32_bf16 v[88:91], v[204:207], v[188:191], v[88:91]
	v_mfma_f32_16x16x32_bf16 v[80:83], v[212:215], v[188:191], v[80:83]
	v_mfma_f32_16x16x32_bf16 v[72:75], v[204:207], v[196:199], v[72:75]
	v_mfma_f32_16x16x32_bf16 v[64:67], v[212:215], v[196:199], v[64:67]
	s_setprio 0
	s_mov_b32 m0, s57
	v_lshl_add_u64 v[178:179], s[52:53], 0, v[132:133]
	s_barrier
	ds_read_b128 v[160:163], v143 offset:16384
	ds_read_b128 v[164:167], v143 offset:17408
	ds_read_b128 v[168:171], v143 offset:18432
	ds_read_b128 v[180:183], v143 offset:19456
	ds_read_b128 v[184:187], v143 offset:20480
	ds_read_b128 v[188:191], v143 offset:21504
	ds_read_b128 v[192:195], v143 offset:22528
	ds_read_b128 v[196:199], v143 offset:23552
	global_load_lds_dwordx4 v[178:179], off
	v_lshl_add_u64 v[216:217], s[52:53], 0, v[130:131]
	s_mov_b32 m0, s58
	s_nop 0
	global_load_lds_dwordx4 v[216:217], off
	s_barrier
	s_waitcnt lgkmcnt(0)
	s_setprio 1
	s_waitcnt lgkmcnt(0)
	v_mfma_f32_16x16x32_bf16 v[60:63], v[144:147], v[160:163], v[60:63]
	v_mfma_f32_16x16x32_bf16 v[52:55], v[152:155], v[160:163], v[52:55]
	v_mfma_f32_16x16x32_bf16 v[44:47], v[144:147], v[168:171], v[44:47]
	v_mfma_f32_16x16x32_bf16 v[36:39], v[152:155], v[168:171], v[36:39]
	v_mfma_f32_16x16x32_bf16 v[28:31], v[144:147], v[184:187], v[28:31]
	v_mfma_f32_16x16x32_bf16 v[20:23], v[152:155], v[184:187], v[20:23]
	v_mfma_f32_16x16x32_bf16 v[12:15], v[144:147], v[192:195], v[12:15]
	v_mfma_f32_16x16x32_bf16 v[4:7], v[152:155], v[192:195], v[4:7]
	v_mfma_f32_16x16x32_bf16 v[60:63], v[148:151], v[164:167], v[60:63]
	v_mfma_f32_16x16x32_bf16 v[52:55], v[156:159], v[164:167], v[52:55]
	v_mfma_f32_16x16x32_bf16 v[44:47], v[148:151], v[180:183], v[44:47]
	v_mfma_f32_16x16x32_bf16 v[36:39], v[156:159], v[180:183], v[36:39]
	v_mfma_f32_16x16x32_bf16 v[28:31], v[148:151], v[188:191], v[28:31]
	v_mfma_f32_16x16x32_bf16 v[20:23], v[156:159], v[188:191], v[20:23]
	v_mfma_f32_16x16x32_bf16 v[12:15], v[148:151], v[196:199], v[12:15]
	v_mfma_f32_16x16x32_bf16 v[4:7], v[156:159], v[196:199], v[4:7]
	s_setprio 0
	s_barrier
; #define PG8_STAGE(bufoff, gbase, voff) do { _Pragma("unroll") for (int _i = 0; _i < 2; ++_i) \
;         __builtin_amdgcn_global_load_lds((const unsigned*)((const char*)(gbase) + (voff)[_i]), (PG8_LAS unsigned*)(lds + (bufoff) + ldsw + _i * 8192), 16, 0, 0); } while (0)
; #define PG8_LDA(dst, b, h) do { _Pragma("unroll") for (int m = 0; m < 4; ++m) _Pragma("unroll") for (int k = 0; k < 2; ++k) dst[m][k] = *(const PG8_LAS bf16x8*)(lds + PG8_SA(b, h) + aoff + m * 2048 + k * 1024); } while (0)
; #define PG8_LDB(dst, b, h) do { _Pragma("unroll") for (int n = 0; n < 2; ++n) _Pragma("unroll") for (int k = 0; k < 2; ++k) dst[n][k] = *(const PG8_LAS bf16x8*)(lds + PG8_SB(b, h) + boff + n * 2048 + k * 1024); } while (0)
; #define PG8_MMA(ai, bj, At, Bt) do { __builtin_amdgcn_s_setprio(1); _Pragma("unroll") for (int m = 0; m < 4; ++m) _Pragma("unroll") for (int n = 0; n < 2; ++n) _Pragma("unroll") for (int k = 0; k < 2; ++k) \
;         acc[ai][bj][m][n] = __builtin_amdgcn_mfma_f32_16x16x32_bf16(Bt[n][k], At[m][k], acc[ai][bj][m][n], 0, 0, 0); __builtin_amdgcn_s_setprio(0); } while (0)
; #define PG8_WAIT_V(n) asm volatile("s_waitcnt vmcnt(" #n ")" ::: "memory")
; #define PG8_WAIT_L(n) asm volatile("s_waitcnt lgkmcnt(" #n ")" ::: "memory")
; #define PG8_BAR __builtin_amdgcn_s_barrier()
; #define PG8_SCHED __builtin_amdgcn_sched_barrier(0)
; template <class Epi, class Sched>
; __device__ __forceinline__ void gemm_phase(PG8_LAS unsigned char* lds, const Gemm g, const Sched& S, const Epi& E) {
;     ...
;             PG8_STAGE(PG8_SB(0, 1), b2 + hstep, voffB);
;             PG8_WAIT_V(6); PG8_BAR; PG8_MMA(1, 1, At, B1); PG8_BAR;
;             PG8_LDB(B0, 1, 0); PG8_SCHED; PG8_LDA(At, 1, 0); PG8_STAGE(PG8_SA(0, 1), a2 + hstep, voffA);
;             PG8_WAIT_L(8); PG8_BAR; PG8_WAIT_L(0); PG8_MMA(0, 0, At, B0); PG8_BAR; PG8_SCHED;
;             PG8_LDB(B1, 1, 1); PG8_STAGE(PG8_SB(1, 0), b3, voffB);
;             PG8_BAR; PG8_WAIT_L(0); PG8_MMA(0, 1, At, B1); PG8_BAR;
;             PG8_LDA(At, 1, 1); PG8_STAGE(PG8_SA(1, 0), a3, voffA);
;             PG8_BAR; PG8_WAIT_L(0); PG8_MMA(1, 0, At, B0); PG8_BAR; PG8_SCHED;
	s_add_u32 s40, s50, 0x80000
	s_addc_u32 s41, s51, 0
	s_add_i32 s26, s27, s56
	v_lshl_add_u64 v[144:145], s[40:41], 0, v[172:173]
	s_mov_b32 m0, s26
	s_nop 0
	global_load_lds_dwordx4 v[144:145], off
	v_lshl_add_u64 v[144:145], s[40:41], 0, v[128:129]
	s_add_i32 m0, s26, 0x2000
	s_nop 0
	global_load_lds_dwordx4 v[144:145], off
	s_waitcnt vmcnt(6)
	s_barrier
	s_setprio 1
	v_mfma_f32_16x16x32_bf16 v[56:59], v[200:203], v[160:163], v[56:59]
	v_mfma_f32_16x16x32_bf16 v[48:51], v[208:211], v[160:163], v[48:51]
	v_mfma_f32_16x16x32_bf16 v[40:43], v[200:203], v[168:171], v[40:43]
	v_mfma_f32_16x16x32_bf16 v[32:35], v[208:211], v[168:171], v[32:35]
	v_mfma_f32_16x16x32_bf16 v[24:27], v[200:203], v[184:187], v[24:27]
	v_mfma_f32_16x16x32_bf16 v[16:19], v[208:211], v[184:187], v[16:19]
	v_mfma_f32_16x16x32_bf16 v[8:11], v[200:203], v[192:195], v[8:11]
	v_mfma_f32_16x16x32_bf16 v[0:3], v[208:211], v[192:195], v[0:3]
	v_mfma_f32_16x16x32_bf16 v[56:59], v[204:207], v[164:167], v[56:59]
	v_mfma_f32_16x16x32_bf16 v[48:51], v[212:215], v[164:167], v[48:51]
	v_mfma_f32_16x16x32_bf16 v[40:43], v[204:207], v[180:183], v[40:43]
	v_mfma_f32_16x16x32_bf16 v[32:35], v[212:215], v[180:183], v[32:35]
	v_mfma_f32_16x16x32_bf16 v[24:27], v[204:207], v[188:191], v[24:27]
	v_mfma_f32_16x16x32_bf16 v[16:19], v[212:215], v[188:191], v[16:19]
	v_mfma_f32_16x16x32_bf16 v[8:11], v[204:207], v[196:199], v[8:11]
	v_mfma_f32_16x16x32_bf16 v[0:3], v[212:215], v[196:199], v[0:3]
	s_setprio 0
	s_add_i32 s26, 0, 0x18000
	v_add_u32_e32 v156, s26, v141
	s_barrier
	ds_read_b128 v[144:147], v156
	ds_read_b128 v[148:151], v156 offset:1024
	ds_read_b128 v[152:155], v156 offset:2048
	ds_read_b128 v[156:159], v156 offset:3072
	s_add_u32 s40, s52, 0x80000
	s_addc_u32 s41, s53, 0
	s_mov_b32 m0, s59
	v_lshl_add_u64 v[200:201], s[40:41], 0, v[132:133]
	ds_read_b128 v[160:163], v143 offset:32768
	ds_read_b128 v[164:167], v143 offset:33792
	ds_read_b128 v[168:171], v143 offset:34816
	ds_read_b128 v[180:183], v143 offset:35840
	ds_read_b128 v[184:187], v143 offset:36864
	ds_read_b128 v[188:191], v143 offset:37888
	ds_read_b128 v[192:195], v143 offset:38912
	ds_read_b128 v[196:199], v143 offset:39936
	global_load_lds_dwordx4 v[200:201], off
	v_lshl_add_u64 v[200:201], s[40:41], 0, v[130:131]
	s_mov_b32 m0, s62
	s_nop 0
	global_load_lds_dwordx4 v[200:201], off
	s_waitcnt lgkmcnt(8)
	s_barrier
	s_waitcnt lgkmcnt(0)
	s_setprio 1
	s_waitcnt lgkmcnt(0)
	v_mfma_f32_16x16x32_bf16 v[124:127], v[144:147], v[160:163], v[124:127]
	v_mfma_f32_16x16x32_bf16 v[116:119], v[152:155], v[160:163], v[116:119]
	v_mfma_f32_16x16x32_bf16 v[108:111], v[144:147], v[168:171], v[108:111]
	v_mfma_f32_16x16x32_bf16 v[100:103], v[152:155], v[168:171], v[100:103]
	v_mfma_f32_16x16x32_bf16 v[92:95], v[144:147], v[184:187], v[92:95]
	v_mfma_f32_16x16x32_bf16 v[84:87], v[152:155], v[184:187], v[84:87]
	v_mfma_f32_16x16x32_bf16 v[76:79], v[144:147], v[192:195], v[76:79]
	v_mfma_f32_16x16x32_bf16 v[68:71], v[152:155], v[192:195], v[68:71]
	v_mfma_f32_16x16x32_bf16 v[124:127], v[148:151], v[164:167], v[124:127]
	v_mfma_f32_16x16x32_bf16 v[116:119], v[156:159], v[164:167], v[116:119]
	v_mfma_f32_16x16x32_bf16 v[108:111], v[148:151], v[180:183], v[108:111]
	v_mfma_f32_16x16x32_bf16 v[100:103], v[156:159], v[180:183], v[100:103]
	v_mfma_f32_16x16x32_bf16 v[92:95], v[148:151], v[188:191], v[92:95]
	v_mfma_f32_16x16x32_bf16 v[84:87], v[156:159], v[188:191], v[84:87]
	v_mfma_f32_16x16x32_bf16 v[76:79], v[148:151], v[196:199], v[76:79]
	v_mfma_f32_16x16x32_bf16 v[68:71], v[156:159], v[196:199], v[68:71]
	s_setprio 0
	s_barrier
	s_add_i32 s27, 0, 0x1c000
	s_add_i32 s26, s26, s56
	v_add_u32_e32 v174, s27, v141
	v_lshl_add_u64 v[138:139], v[138:139], 0, s[38:39]
	s_mov_b32 m0, s26
	ds_read_b128 v[200:203], v174
	ds_read_b128 v[204:207], v174 offset:1024
	ds_read_b128 v[208:211], v174 offset:2048
	ds_read_b128 v[212:215], v174 offset:3072
	global_load_lds_dwordx4 v[138:139], off
	v_lshl_add_u64 v[138:139], v[176:177], 0, s[38:39]
	s_add_i32 m0, s26, 0x2000
	s_nop 0
	global_load_lds_dwordx4 v[138:139], off
	s_barrier
	s_waitcnt lgkmcnt(0)
	s_setprio 1
	s_waitcnt lgkmcnt(0)
	v_mfma_f32_16x16x32_bf16 v[120:123], v[200:203], v[160:163], v[120:123]
	v_mfma_f32_16x16x32_bf16 v[112:115], v[208:211], v[160:163], v[112:115]
	v_mfma_f32_16x16x32_bf16 v[104:107], v[200:203], v[168:171], v[104:107]
	v_mfma_f32_16x16x32_bf16 v[96:99], v[208:211], v[168:171], v[96:99]
	v_mfma_f32_16x16x32_bf16 v[88:91], v[200:203], v[184:187], v[88:91]
	v_mfma_f32_16x16x32_bf16 v[80:83], v[208:211], v[184:187], v[80:83]
	v_mfma_f32_16x16x32_bf16 v[72:75], v[200:203], v[192:195], v[72:75]
	v_mfma_f32_16x16x32_bf16 v[64:67], v[208:211], v[192:195], v[64:67]
	v_mfma_f32_16x16x32_bf16 v[120:123], v[204:207], v[164:167], v[120:123]
	v_mfma_f32_16x16x32_bf16 v[112:115], v[212:215], v[164:167], v[112:115]
	v_mfma_f32_16x16x32_bf16 v[104:107], v[204:207], v[180:183], v[104:107]
	v_mfma_f32_16x16x32_bf16 v[96:99], v[212:215], v[180:183], v[96:99]
	v_mfma_f32_16x16x32_bf16 v[88:91], v[204:207], v[188:191], v[88:91]
	v_mfma_f32_16x16x32_bf16 v[80:83], v[212:215], v[188:191], v[80:83]
	v_mfma_f32_16x16x32_bf16 v[72:75], v[204:207], v[196:199], v[72:75]
	v_mfma_f32_16x16x32_bf16 v[64:67], v[212:215], v[196:199], v[64:67]
	s_setprio 0
	s_mov_b32 m0, s2
	v_lshl_add_u64 v[138:139], v[178:179], 0, s[38:39]
	s_barrier
	ds_read_b128 v[160:163], v143 offset:49152
	ds_read_b128 v[164:167], v143 offset:50176
	ds_read_b128 v[168:171], v143 offset:51200
	ds_read_b128 v[180:183], v143 offset:52224
	ds_read_b128 v[184:187], v143 offset:53248
	ds_read_b128 v[188:191], v143 offset:54272
	ds_read_b128 v[192:195], v143 offset:55296
	ds_read_b128 v[196:199], v143 offset:56320
	global_load_lds_dwordx4 v[138:139], off
	v_lshl_add_u64 v[138:139], v[216:217], 0, s[38:39]
	s_mov_b32 m0, s54
	s_nop 0
	global_load_lds_dwordx4 v[138:139], off
	s_barrier
; __device__ __forceinline__ unsigned cvt_pk_bf16(float lo, float hi) { unsigned r; asm volatile("v_cvt_pk_bf16_f32 %0, %1, %2" : "=v"(r) : "v"(lo), "v"(hi)); return r; }
; #define PG8_STAGE(bufoff, gbase, voff) do { _Pragma("unroll") for (int _i = 0; _i < 2; ++_i) \
;         __builtin_amdgcn_global_load_lds((const unsigned*)((const char*)(gbase) + (voff)[_i]), (PG8_LAS unsigned*)(lds + (bufoff) + ldsw + _i * 8192), 16, 0, 0); } while (0)
; #define PG8_MMA(ai, bj, At, Bt) do { __builtin_amdgcn_s_setprio(1); _Pragma("unroll") for (int m = 0; m < 4; ++m) _Pragma("unroll") for (int n = 0; n < 2; ++n) _Pragma("unroll") for (int k = 0; k < 2; ++k) \
;         acc[ai][bj][m][n] = __builtin_amdgcn_mfma_f32_16x16x32_bf16(Bt[n][k], At[m][k], acc[ai][bj][m][n], 0, 0, 0); __builtin_amdgcn_s_setprio(0); } while (0)
; #define PG8_WAIT_V(n) asm volatile("s_waitcnt vmcnt(" #n ")" ::: "memory")
; #define PG8_WAIT_L(n) asm volatile("s_waitcnt lgkmcnt(" #n ")" ::: "memory")
; #define PG8_BAR __builtin_amdgcn_s_barrier()
; #define PG8_SCHED __builtin_amdgcn_sched_barrier(0)
; template <class Epi, class Sched>
; __device__ __forceinline__ void gemm_phase(PG8_LAS unsigned char* lds, const Gemm g, const Sched& S, const Epi& E) {
;     ...
;             PG8_BAR; PG8_WAIT_L(0); PG8_MMA(1, 0, At, B0); PG8_BAR; PG8_SCHED;
;             PG8_STAGE(PG8_SB(1, 1), b3 + hstep, voffB);
;             PG8_WAIT_V(6); PG8_BAR; PG8_MMA(1, 1, At, B1); PG8_BAR;
;     __device__ __forceinline__ void operator()(const f32x4 (&acc)[2][2][4][2], const pg8::Unit& u, int wr, int wc, int fr, int fq) const {
;         const int row0 = u.pm * 256 + wr * 64 + fr, col0 = u.pn * 128 + wc * 32 + 8 * fq;
; #pragma unroll
;         for (int ai = 0; ai < 2; ++ai)
; #pragma unroll
;             for (int m = 0; m < 4; ++m) {
;                 bf16_t* rowp = H + (size_t)(row0 + ai * 128 + m * 16) * DFF + col0;
;                 float hv[8];
; #pragma unroll
;                 for (int n = 0; n < 2; ++n)
; #pragma unroll
;                     for (int j = 0; j < 4; ++j) { const float g = acc[ai][0][m][n][j], up = acc[ai][1][m][n][j]; hv[n * 4 + j] = g * sigm(g) * up; }
;                 u32x4 w; w.x = cvt_pk_bf16(hv[0], hv[1]); w.y = cvt_pk_bf16(hv[2], hv[3]); w.z = cvt_pk_bf16(hv[4], hv[5]); w.w = cvt_pk_bf16(hv[6], hv[7]);
;                 *(u32x4*)rowp = w;
	s_waitcnt lgkmcnt(0)
	s_setprio 1
	s_waitcnt lgkmcnt(0)
	v_mfma_f32_16x16x32_bf16 v[60:63], v[144:147], v[160:163], v[60:63]
	v_mfma_f32_16x16x32_bf16 v[52:55], v[152:155], v[160:163], v[52:55]
	v_mfma_f32_16x16x32_bf16 v[44:47], v[144:147], v[168:171], v[44:47]
	v_mfma_f32_16x16x32_bf16 v[36:39], v[152:155], v[168:171], v[36:39]
	v_mfma_f32_16x16x32_bf16 v[28:31], v[144:147], v[184:187], v[28:31]
	v_mfma_f32_16x16x32_bf16 v[20:23], v[152:155], v[184:187], v[20:23]
	v_mfma_f32_16x16x32_bf16 v[12:15], v[144:147], v[192:195], v[12:15]
	v_mfma_f32_16x16x32_bf16 v[4:7], v[152:155], v[192:195], v[4:7]
	v_mfma_f32_16x16x32_bf16 v[60:63], v[148:151], v[164:167], v[60:63]
	v_mfma_f32_16x16x32_bf16 v[52:55], v[156:159], v[164:167], v[52:55]
	v_mfma_f32_16x16x32_bf16 v[44:47], v[148:151], v[180:183], v[44:47]
	v_mfma_f32_16x16x32_bf16 v[36:39], v[156:159], v[180:183], v[36:39]
	v_mfma_f32_16x16x32_bf16 v[28:31], v[148:151], v[188:191], v[28:31]
	v_mfma_f32_16x16x32_bf16 v[20:23], v[156:159], v[188:191], v[20:23]
	v_mfma_f32_16x16x32_bf16 v[12:15], v[148:151], v[196:199], v[12:15]
	v_mfma_f32_16x16x32_bf16 v[4:7], v[156:159], v[196:199], v[4:7]
	s_setprio 0
	s_barrier
	s_add_u32 s40, s50, 0x80080
	s_addc_u32 s41, s51, 0
	s_add_i32 s26, s27, s56
	v_lshl_add_u64 v[138:139], s[40:41], 0, v[172:173]
	s_mov_b32 m0, s26
	s_nop 0
	global_load_lds_dwordx4 v[138:139], off
	v_lshl_add_u64 v[138:139], s[40:41], 0, v[128:129]
	s_add_i32 m0, s26, 0x2000
	s_nop 0
	global_load_lds_dwordx4 v[138:139], off
	s_waitcnt vmcnt(6)
	s_barrier
	s_setprio 1
	v_mfma_f32_16x16x32_bf16 v[56:59], v[200:203], v[160:163], v[56:59]
	v_mfma_f32_16x16x32_bf16 v[48:51], v[208:211], v[160:163], v[48:51]
	v_mfma_f32_16x16x32_bf16 v[40:43], v[200:203], v[168:171], v[40:43]
	v_mfma_f32_16x16x32_bf16 v[32:35], v[208:211], v[168:171], v[32:35]
	v_mfma_f32_16x16x32_bf16 v[24:27], v[200:203], v[184:187], v[24:27]
	v_mfma_f32_16x16x32_bf16 v[16:19], v[208:211], v[184:187], v[16:19]
	v_mfma_f32_16x16x32_bf16 v[8:11], v[200:203], v[192:195], v[8:11]
	v_mfma_f32_16x16x32_bf16 v[0:3], v[208:211], v[192:195], v[0:3]
	v_mfma_f32_16x16x32_bf16 v[56:59], v[204:207], v[164:167], v[56:59]
	v_mfma_f32_16x16x32_bf16 v[48:51], v[212:215], v[164:167], v[48:51]
	v_mfma_f32_16x16x32_bf16 v[40:43], v[204:207], v[180:183], v[40:43]
	v_mfma_f32_16x16x32_bf16 v[32:35], v[212:215], v[180:183], v[32:35]
	v_mfma_f32_16x16x32_bf16 v[24:27], v[204:207], v[188:191], v[24:27]
	v_mfma_f32_16x16x32_bf16 v[16:19], v[212:215], v[188:191], v[16:19]
	v_mfma_f32_16x16x32_bf16 v[8:11], v[204:207], v[196:199], v[8:11]
	v_mfma_f32_16x16x32_bf16 v[0:3], v[212:215], v[196:199], v[0:3]
	s_setprio 0
	s_add_i32 s29, s29, 2
	s_add_u32 s48, s48, 0x100
	s_addc_u32 s49, s49, 0
	s_add_u32 vcc_hi, vcc_hi, 0x100
	s_addc_u32 s28, s28, 0
	s_cmp_gt_u32 s29, 29
	s_barrier
	s_cbranch_scc0 .LBB0_617
	v_mul_f32_e32 v145, 0xbfb8aa3b, v124
	v_exp_f32_e32 v145, v145
	v_lshl_or_b32 v146, s8, 7, v142
	v_readlane_b32 s8, v254, 50
	v_readlane_b32 s9, v254, 51
	v_add_f32_e32 v145, 1.0, v145
	v_rcp_f32_e32 v145, v145
	v_lshl_add_u32 v144, s55, 8, v140
	v_ashrrev_i32_e32 v147, 31, v146
	v_mov_b64_e32 v[138:139], s[8:9]
	v_mul_f32_e32 v124, v124, v145
	v_mul_f32_e32 v120, v124, v120
	v_mul_f32_e32 v124, 0xbfb8aa3b, v125
	v_exp_f32_e32 v124, v124
	v_mad_i64_i32 v[148:149], s[8:9], v144, s11, v[138:139]
	s_mov_b32 s55, s42
	v_add_f32_e32 v124, 1.0, v124
	v_rcp_f32_e32 v124, v124
	s_mov_b64 s[50:51], s[46:47]
	s_mov_b64 s[48:49], s[44:45]
	v_mul_f32_e32 v124, v125, v124
	v_mul_f32_e32 v121, v124, v121
	v_mul_f32_e32 v124, 0xbfb8aa3b, v126
	v_exp_f32_e32 v124, v124
	s_nop 0
	v_add_f32_e32 v124, 1.0, v124
	v_rcp_f32_e32 v124, v124
	s_nop 0
	v_mul_f32_e32 v124, v126, v124
	v_mul_f32_e32 v122, v124, v122
	v_mul_f32_e32 v124, 0xbfb8aa3b, v127
	v_exp_f32_e32 v124, v124
	s_nop 0
	v_add_f32_e32 v124, 1.0, v124
	v_rcp_f32_e32 v124, v124
	s_nop 0
	v_mul_f32_e32 v124, v127, v124
	v_mul_f32_e32 v123, v124, v123
	v_mul_f32_e32 v124, 0xbfb8aa3b, v116
	v_exp_f32_e32 v124, v124
	s_nop 0
	v_add_f32_e32 v124, 1.0, v124
	v_rcp_f32_e32 v124, v124
	s_nop 0
	v_mul_f32_e32 v116, v116, v124
	v_mul_f32_e32 v116, v116, v112
	v_mul_f32_e32 v112, 0xbfb8aa3b, v117
	v_exp_f32_e32 v112, v112
	s_nop 0
	v_add_f32_e32 v112, 1.0, v112
	v_rcp_f32_e32 v112, v112
	s_nop 0
	v_mul_f32_e32 v112, v117, v112
	v_mul_f32_e32 v117, v112, v113
	v_mul_f32_e32 v112, 0xbfb8aa3b, v118
	v_exp_f32_e32 v112, v112
	s_nop 0
	v_add_f32_e32 v112, 1.0, v112
	v_rcp_f32_e32 v112, v112
	s_nop 0
	v_mul_f32_e32 v112, v118, v112
	v_mul_f32_e32 v124, v112, v114
	v_mul_f32_e32 v112, 0xbfb8aa3b, v119
	v_exp_f32_e32 v112, v112
	v_cvt_pk_bf16_f32 v114, v120, v121
	s_nop 0
	v_add_f32_e32 v112, 1.0, v112
	v_rcp_f32_e32 v112, v112
	s_nop 0
	v_mul_f32_e32 v112, v119, v112
	v_mul_f32_e32 v125, v112, v115
	v_lshlrev_b64 v[112:113], 1, v[146:147]
	v_lshl_add_u64 v[118:119], v[148:149], 0, v[112:113]
	v_cvt_pk_bf16_f32 v115, v122, v123
	v_cvt_pk_bf16_f32 v116, v116, v117
	v_cvt_pk_bf16_f32 v117, v124, v125
	global_store_dwordx4 v[118:119], v[114:117], off sc1
	s_nop 1
	v_mul_f32_e32 v116, 0xbfb8aa3b, v108
	v_exp_f32_e32 v116, v116
	v_or_b32_e32 v114, 16, v144
	v_mad_i64_i32 v[114:115], s[8:9], v114, s11, v[138:139]
	v_add_f32_e32 v116, 1.0, v116
	v_rcp_f32_e32 v116, v116
	s_nop 0
	v_mul_f32_e32 v108, v108, v116
	v_mul_f32_e32 v104, v108, v104
	v_mul_f32_e32 v108, 0xbfb8aa3b, v109
	v_exp_f32_e32 v108, v108
	s_nop 0
	v_add_f32_e32 v108, 1.0, v108
	v_rcp_f32_e32 v108, v108
	s_nop 0
	v_mul_f32_e32 v108, v109, v108
	v_mul_f32_e32 v105, v108, v105
	v_mul_f32_e32 v108, 0xbfb8aa3b, v110
	v_exp_f32_e32 v108, v108
	s_nop 0
	v_add_f32_e32 v108, 1.0, v108
; __device__ __forceinline__ unsigned cvt_pk_bf16(float lo, float hi) { unsigned r; asm volatile("v_cvt_pk_bf16_f32 %0, %1, %2" : "=v"(r) : "v"(lo), "v"(hi)); return r; }
; __device__ __forceinline__ float sigm(float x) { return __builtin_amdgcn_rcpf(1.0f + __expf(-x)); }
;     __device__ __forceinline__ void operator()(const f32x4 (&acc)[2][2][4][2], const pg8::Unit& u, int wr, int wc, int fr, int fq) const {
;     ...
;             for (int m = 0; m < 4; ++m) {
;                 bf16_t* rowp = H + (size_t)(row0 + ai * 128 + m * 16) * DFF + col0;
;                 float hv[8];
; #pragma unroll
;                 for (int n = 0; n < 2; ++n)
; #pragma unroll
;                     for (int j = 0; j < 4; ++j) { const float g = acc[ai][0][m][n][j], up = acc[ai][1][m][n][j]; hv[n * 4 + j] = g * sigm(g) * up; }
;                 u32x4 w; w.x = cvt_pk_bf16(hv[0], hv[1]); w.y = cvt_pk_bf16(hv[2], hv[3]); w.z = cvt_pk_bf16(hv[4], hv[5]); w.w = cvt_pk_bf16(hv[6], hv[7]);
;                 *(u32x4*)rowp = w;
	v_rcp_f32_e32 v108, v108
	s_nop 0
	v_mul_f32_e32 v108, v110, v108
	v_mul_f32_e32 v106, v108, v106
	v_mul_f32_e32 v108, 0xbfb8aa3b, v111
	v_exp_f32_e32 v108, v108
	s_nop 0
	v_add_f32_e32 v108, 1.0, v108
	v_rcp_f32_e32 v108, v108
	s_nop 0
	v_mul_f32_e32 v108, v111, v108
	v_mul_f32_e32 v107, v108, v107
	v_mul_f32_e32 v108, 0xbfb8aa3b, v100
	v_exp_f32_e32 v108, v108
	s_nop 0
	v_add_f32_e32 v108, 1.0, v108
	v_rcp_f32_e32 v108, v108
	s_nop 0
	v_mul_f32_e32 v100, v100, v108
	v_mul_f32_e32 v108, v100, v96
	v_mul_f32_e32 v96, 0xbfb8aa3b, v101
	v_exp_f32_e32 v96, v96
	s_nop 0
	v_add_f32_e32 v96, 1.0, v96
	v_rcp_f32_e32 v96, v96
	s_nop 0
	v_mul_f32_e32 v96, v101, v96
	v_mul_f32_e32 v109, v96, v97
	v_mul_f32_e32 v96, 0xbfb8aa3b, v102
	v_exp_f32_e32 v96, v96
	v_lshl_add_u64 v[100:101], v[114:115], 0, v[112:113]
	v_add_f32_e32 v96, 1.0, v96
	v_rcp_f32_e32 v96, v96
	s_nop 0
	v_mul_f32_e32 v96, v102, v96
	v_mul_f32_e32 v102, v96, v98
	v_mul_f32_e32 v96, 0xbfb8aa3b, v103
	v_exp_f32_e32 v96, v96
	s_nop 0
	v_add_f32_e32 v96, 1.0, v96
	v_rcp_f32_e32 v96, v96
	s_nop 0
	v_mul_f32_e32 v96, v103, v96
	v_mul_f32_e32 v99, v96, v99
	v_cvt_pk_bf16_f32 v96, v104, v105
	v_cvt_pk_bf16_f32 v97, v106, v107
	v_cvt_pk_bf16_f32 v98, v108, v109
	v_cvt_pk_bf16_f32 v99, v102, v99
	global_store_dwordx4 v[100:101], v[96:99], off sc1
	s_nop 1
	v_mul_f32_e32 v98, 0xbfb8aa3b, v92
	v_exp_f32_e32 v98, v98
	v_or_b32_e32 v96, 32, v144
	v_mad_i64_i32 v[96:97], s[8:9], v96, s11, v[138:139]
	v_add_f32_e32 v98, 1.0, v98
	v_rcp_f32_e32 v98, v98
	s_nop 0
	v_mul_f32_e32 v92, v92, v98
	v_mul_f32_e32 v88, v92, v88
	v_mul_f32_e32 v92, 0xbfb8aa3b, v93
	v_exp_f32_e32 v92, v92
	s_nop 0
	v_add_f32_e32 v92, 1.0, v92
	v_rcp_f32_e32 v92, v92
	s_nop 0
	v_mul_f32_e32 v92, v93, v92
	v_mul_f32_e32 v89, v92, v89
	v_mul_f32_e32 v92, 0xbfb8aa3b, v94
	v_exp_f32_e32 v92, v92
	s_nop 0
	v_add_f32_e32 v92, 1.0, v92
	v_rcp_f32_e32 v92, v92
	s_nop 0
	v_mul_f32_e32 v92, v94, v92
	v_mul_f32_e32 v90, v92, v90
	v_mul_f32_e32 v92, 0xbfb8aa3b, v95
	v_exp_f32_e32 v92, v92
	s_nop 0
	v_add_f32_e32 v92, 1.0, v92
	v_rcp_f32_e32 v92, v92
	s_nop 0
	v_mul_f32_e32 v92, v95, v92
	v_mul_f32_e32 v91, v92, v91
	v_mul_f32_e32 v92, 0xbfb8aa3b, v84
	v_exp_f32_e32 v92, v92
	s_nop 0
	v_add_f32_e32 v92, 1.0, v92
	v_rcp_f32_e32 v92, v92
	s_nop 0
	v_mul_f32_e32 v84, v84, v92
	v_mul_f32_e32 v92, v84, v80
	v_mul_f32_e32 v80, 0xbfb8aa3b, v85
	v_exp_f32_e32 v80, v80
	s_nop 0
	v_add_f32_e32 v80, 1.0, v80
	v_rcp_f32_e32 v80, v80
	s_nop 0
	v_mul_f32_e32 v80, v85, v80
	v_mul_f32_e32 v93, v80, v81
	v_mul_f32_e32 v80, 0xbfb8aa3b, v86
	v_exp_f32_e32 v80, v80
	v_lshl_add_u64 v[84:85], v[96:97], 0, v[112:113]
	v_add_f32_e32 v80, 1.0, v80
	v_rcp_f32_e32 v80, v80
	s_nop 0
	v_mul_f32_e32 v80, v86, v80
	v_mul_f32_e32 v86, v80, v82
	v_mul_f32_e32 v80, 0xbfb8aa3b, v87
	v_exp_f32_e32 v80, v80
	s_nop 0
	v_add_f32_e32 v80, 1.0, v80
	v_rcp_f32_e32 v80, v80
	s_nop 0
	v_mul_f32_e32 v80, v87, v80
	v_mul_f32_e32 v83, v80, v83
	v_cvt_pk_bf16_f32 v80, v88, v89
	v_cvt_pk_bf16_f32 v81, v90, v91
	v_cvt_pk_bf16_f32 v82, v92, v93
	v_cvt_pk_bf16_f32 v83, v86, v83
	global_store_dwordx4 v[84:85], v[80:83], off sc1
	s_nop 1
	v_mul_f32_e32 v82, 0xbfb8aa3b, v76
	v_exp_f32_e32 v82, v82
	v_or_b32_e32 v80, 48, v144
	v_mad_i64_i32 v[80:81], s[8:9], v80, s11, v[138:139]
	v_add_f32_e32 v82, 1.0, v82
	v_rcp_f32_e32 v82, v82
	s_nop 0
	v_mul_f32_e32 v76, v76, v82
	v_mul_f32_e32 v72, v76, v72
	v_mul_f32_e32 v76, 0xbfb8aa3b, v77
	v_exp_f32_e32 v76, v76
	s_nop 0
	v_add_f32_e32 v76, 1.0, v76
	v_rcp_f32_e32 v76, v76
	s_nop 0
	v_mul_f32_e32 v76, v77, v76
	v_mul_f32_e32 v73, v76, v73
	v_mul_f32_e32 v76, 0xbfb8aa3b, v78
	v_exp_f32_e32 v76, v76
	s_nop 0
	v_add_f32_e32 v76, 1.0, v76
	v_rcp_f32_e32 v76, v76
	s_nop 0
	v_mul_f32_e32 v76, v78, v76
	v_mul_f32_e32 v74, v76, v74
	v_mul_f32_e32 v76, 0xbfb8aa3b, v79
	v_exp_f32_e32 v76, v76
	s_nop 0
	v_add_f32_e32 v76, 1.0, v76
	v_rcp_f32_e32 v76, v76
	s_nop 0
	v_mul_f32_e32 v76, v79, v76
	v_mul_f32_e32 v75, v76, v75
	v_mul_f32_e32 v76, 0xbfb8aa3b, v68
	v_exp_f32_e32 v76, v76
	s_nop 0
	v_add_f32_e32 v76, 1.0, v76
	v_rcp_f32_e32 v76, v76
	s_nop 0
	v_mul_f32_e32 v68, v68, v76
	v_mul_f32_e32 v76, v68, v64
	v_mul_f32_e32 v64, 0xbfb8aa3b, v69
	v_exp_f32_e32 v64, v64
	s_nop 0
	v_add_f32_e32 v64, 1.0, v64
	v_rcp_f32_e32 v64, v64
	s_nop 0
	v_mul_f32_e32 v64, v69, v64
	v_mul_f32_e32 v77, v64, v65
	v_mul_f32_e32 v64, 0xbfb8aa3b, v70
	v_exp_f32_e32 v64, v64
	v_lshl_add_u64 v[68:69], v[80:81], 0, v[112:113]
	v_add_f32_e32 v64, 1.0, v64
	v_rcp_f32_e32 v64, v64
	s_nop 0
	v_mul_f32_e32 v64, v70, v64
	v_mul_f32_e32 v70, v64, v66
	v_mul_f32_e32 v64, 0xbfb8aa3b, v71
	v_exp_f32_e32 v64, v64
	s_nop 0
	v_add_f32_e32 v64, 1.0, v64
	v_rcp_f32_e32 v64, v64
	s_nop 0
	v_mul_f32_e32 v64, v71, v64
	v_mul_f32_e32 v67, v64, v67
	v_cvt_pk_bf16_f32 v64, v72, v73
	v_cvt_pk_bf16_f32 v65, v74, v75
	v_cvt_pk_bf16_f32 v66, v76, v77
	v_cvt_pk_bf16_f32 v67, v70, v67
	global_store_dwordx4 v[68:69], v[64:67], off sc1
	s_nop 1
	v_mul_f32_e32 v66, 0xbfb8aa3b, v60
	v_exp_f32_e32 v66, v66
	v_add_u32_e32 v64, 0x80, v144
	v_mad_i64_i32 v[64:65], s[8:9], v64, s11, v[138:139]
	v_add_f32_e32 v66, 1.0, v66
	v_rcp_f32_e32 v66, v66
	s_nop 0
	v_mul_f32_e32 v60, v60, v66
	v_mul_f32_e32 v56, v60, v56
	v_mul_f32_e32 v60, 0xbfb8aa3b, v61
	v_exp_f32_e32 v60, v60
	s_nop 0
	v_add_f32_e32 v60, 1.0, v60
	v_rcp_f32_e32 v60, v60
	s_nop 0
	v_mul_f32_e32 v60, v61, v60
	v_mul_f32_e32 v57, v60, v57
	v_mul_f32_e32 v60, 0xbfb8aa3b, v62
	v_exp_f32_e32 v60, v60
	s_nop 0
	v_add_f32_e32 v60, 1.0, v60
	v_rcp_f32_e32 v60, v60
	s_nop 0
	v_mul_f32_e32 v60, v62, v60
	v_mul_f32_e32 v58, v60, v58
	v_mul_f32_e32 v60, 0xbfb8aa3b, v63
; __device__ __forceinline__ unsigned cvt_pk_bf16(float lo, float hi) { unsigned r; asm volatile("v_cvt_pk_bf16_f32 %0, %1, %2" : "=v"(r) : "v"(lo), "v"(hi)); return r; }
; #define PG8_WAIT_V(n) asm volatile("s_waitcnt vmcnt(" #n ")" ::: "memory")
; #define PG8_BAR __builtin_amdgcn_s_barrier()
; __device__ __forceinline__ float sigm(float x) { return __builtin_amdgcn_rcpf(1.0f + __expf(-x)); }
; template <class Epi, class Sched>
; __device__ __forceinline__ void gemm_phase(PG8_LAS unsigned char* lds, const Gemm g, const Sched& S, const Epi& E) {
;     ...
;     PG8_WAIT_V(0);
;     if (wr == 0) PG8_BAR;
;     __device__ __forceinline__ void operator()(const f32x4 (&acc)[2][2][4][2], const pg8::Unit& u, int wr, int wc, int fr, int fq) const {
;     ...
;             for (int m = 0; m < 4; ++m) {
;                 bf16_t* rowp = H + (size_t)(row0 + ai * 128 + m * 16) * DFF + col0;
;                 float hv[8];
; #pragma unroll
;                 for (int n = 0; n < 2; ++n)
; #pragma unroll
;                     for (int j = 0; j < 4; ++j) { const float g = acc[ai][0][m][n][j], up = acc[ai][1][m][n][j]; hv[n * 4 + j] = g * sigm(g) * up; }
;                 u32x4 w; w.x = cvt_pk_bf16(hv[0], hv[1]); w.y = cvt_pk_bf16(hv[2], hv[3]); w.z = cvt_pk_bf16(hv[4], hv[5]); w.w = cvt_pk_bf16(hv[6], hv[7]);
;                 *(u32x4*)rowp = w;
;             }
	v_exp_f32_e32 v60, v60
	s_nop 0
	v_add_f32_e32 v60, 1.0, v60
	v_rcp_f32_e32 v60, v60
	s_nop 0
	v_mul_f32_e32 v60, v63, v60
	v_mul_f32_e32 v59, v60, v59
	v_mul_f32_e32 v60, 0xbfb8aa3b, v52
	v_exp_f32_e32 v60, v60
	s_nop 0
	v_add_f32_e32 v60, 1.0, v60
	v_rcp_f32_e32 v60, v60
	s_nop 0
	v_mul_f32_e32 v52, v52, v60
	v_mul_f32_e32 v60, v52, v48
	v_mul_f32_e32 v48, 0xbfb8aa3b, v53
	v_exp_f32_e32 v48, v48
	s_nop 0
	v_add_f32_e32 v48, 1.0, v48
	v_rcp_f32_e32 v48, v48
	s_nop 0
	v_mul_f32_e32 v48, v53, v48
	v_mul_f32_e32 v61, v48, v49
	v_mul_f32_e32 v48, 0xbfb8aa3b, v54
	v_exp_f32_e32 v48, v48
	v_lshl_add_u64 v[52:53], v[64:65], 0, v[112:113]
	v_add_f32_e32 v48, 1.0, v48
	v_rcp_f32_e32 v48, v48
	s_nop 0
	v_mul_f32_e32 v48, v54, v48
	v_mul_f32_e32 v54, v48, v50
	v_mul_f32_e32 v48, 0xbfb8aa3b, v55
	v_exp_f32_e32 v48, v48
	s_nop 0
	v_add_f32_e32 v48, 1.0, v48
	v_rcp_f32_e32 v48, v48
	s_nop 0
	v_mul_f32_e32 v48, v55, v48
	v_mul_f32_e32 v51, v48, v51
	v_cvt_pk_bf16_f32 v48, v56, v57
	v_cvt_pk_bf16_f32 v49, v58, v59
	v_cvt_pk_bf16_f32 v50, v60, v61
	v_cvt_pk_bf16_f32 v51, v54, v51
	global_store_dwordx4 v[52:53], v[48:51], off sc1
	s_nop 1
	v_mul_f32_e32 v50, 0xbfb8aa3b, v44
	v_exp_f32_e32 v50, v50
	v_add_u32_e32 v48, 0x90, v144
	v_mad_i64_i32 v[48:49], s[8:9], v48, s11, v[138:139]
	v_add_f32_e32 v50, 1.0, v50
	v_rcp_f32_e32 v50, v50
	s_nop 0
	v_mul_f32_e32 v44, v44, v50
	v_mul_f32_e32 v40, v44, v40
	v_mul_f32_e32 v44, 0xbfb8aa3b, v45
	v_exp_f32_e32 v44, v44
	s_nop 0
	v_add_f32_e32 v44, 1.0, v44
	v_rcp_f32_e32 v44, v44
	s_nop 0
	v_mul_f32_e32 v44, v45, v44
	v_mul_f32_e32 v41, v44, v41
	v_mul_f32_e32 v44, 0xbfb8aa3b, v46
	v_exp_f32_e32 v44, v44
	s_nop 0
	v_add_f32_e32 v44, 1.0, v44
	v_rcp_f32_e32 v44, v44
	s_nop 0
	v_mul_f32_e32 v44, v46, v44
	v_mul_f32_e32 v42, v44, v42
	v_mul_f32_e32 v44, 0xbfb8aa3b, v47
	v_exp_f32_e32 v44, v44
	s_nop 0
	v_add_f32_e32 v44, 1.0, v44
	v_rcp_f32_e32 v44, v44
	s_nop 0
	v_mul_f32_e32 v44, v47, v44
	v_mul_f32_e32 v43, v44, v43
	v_mul_f32_e32 v44, 0xbfb8aa3b, v36
	v_exp_f32_e32 v44, v44
	s_nop 0
	v_add_f32_e32 v44, 1.0, v44
	v_rcp_f32_e32 v44, v44
	s_nop 0
	v_mul_f32_e32 v36, v36, v44
	v_mul_f32_e32 v44, v36, v32
	v_mul_f32_e32 v32, 0xbfb8aa3b, v37
	v_exp_f32_e32 v32, v32
	s_nop 0
	v_add_f32_e32 v32, 1.0, v32
	v_rcp_f32_e32 v32, v32
	s_nop 0
	v_mul_f32_e32 v32, v37, v32
	v_mul_f32_e32 v45, v32, v33
	v_mul_f32_e32 v32, 0xbfb8aa3b, v38
	v_exp_f32_e32 v32, v32
	v_lshl_add_u64 v[36:37], v[48:49], 0, v[112:113]
	v_add_f32_e32 v32, 1.0, v32
	v_rcp_f32_e32 v32, v32
	s_nop 0
	v_mul_f32_e32 v32, v38, v32
	v_mul_f32_e32 v38, v32, v34
	v_mul_f32_e32 v32, 0xbfb8aa3b, v39
	v_exp_f32_e32 v32, v32
	s_nop 0
	v_add_f32_e32 v32, 1.0, v32
	v_rcp_f32_e32 v32, v32
	s_nop 0
	v_mul_f32_e32 v32, v39, v32
	v_mul_f32_e32 v35, v32, v35
	v_cvt_pk_bf16_f32 v32, v40, v41
	v_cvt_pk_bf16_f32 v33, v42, v43
	v_cvt_pk_bf16_f32 v34, v44, v45
	v_cvt_pk_bf16_f32 v35, v38, v35
	global_store_dwordx4 v[36:37], v[32:35], off sc1
	s_nop 1
	v_mul_f32_e32 v34, 0xbfb8aa3b, v28
	v_exp_f32_e32 v34, v34
	v_add_u32_e32 v32, 0xa0, v144
	v_mad_i64_i32 v[32:33], s[8:9], v32, s11, v[138:139]
	v_add_f32_e32 v34, 1.0, v34
	v_rcp_f32_e32 v34, v34
	s_nop 0
	v_mul_f32_e32 v28, v28, v34
	v_mul_f32_e32 v24, v28, v24
	v_mul_f32_e32 v28, 0xbfb8aa3b, v29
	v_exp_f32_e32 v28, v28
	s_nop 0
	v_add_f32_e32 v28, 1.0, v28
	v_rcp_f32_e32 v28, v28
	s_nop 0
	v_mul_f32_e32 v28, v29, v28
	v_mul_f32_e32 v25, v28, v25
	v_mul_f32_e32 v28, 0xbfb8aa3b, v30
	v_exp_f32_e32 v28, v28
	s_nop 0
	v_add_f32_e32 v28, 1.0, v28
	v_rcp_f32_e32 v28, v28
	s_nop 0
	v_mul_f32_e32 v28, v30, v28
	v_mul_f32_e32 v26, v28, v26
	v_mul_f32_e32 v28, 0xbfb8aa3b, v31
	v_exp_f32_e32 v28, v28
	s_nop 0
	v_add_f32_e32 v28, 1.0, v28
	v_rcp_f32_e32 v28, v28
	s_nop 0
	v_mul_f32_e32 v28, v31, v28
	v_mul_f32_e32 v27, v28, v27
	v_mul_f32_e32 v28, 0xbfb8aa3b, v20
	v_exp_f32_e32 v28, v28
	s_nop 0
	v_add_f32_e32 v28, 1.0, v28
	v_rcp_f32_e32 v28, v28
	s_nop 0
	v_mul_f32_e32 v20, v20, v28
	v_mul_f32_e32 v28, v20, v16
	v_mul_f32_e32 v16, 0xbfb8aa3b, v21
	v_exp_f32_e32 v16, v16
	s_nop 0
	v_add_f32_e32 v16, 1.0, v16
	v_rcp_f32_e32 v16, v16
	s_nop 0
	v_mul_f32_e32 v16, v21, v16
	v_mul_f32_e32 v29, v16, v17
	v_mul_f32_e32 v16, 0xbfb8aa3b, v22
	v_exp_f32_e32 v16, v16
	v_lshl_add_u64 v[20:21], v[32:33], 0, v[112:113]
	v_add_f32_e32 v16, 1.0, v16
	v_rcp_f32_e32 v16, v16
	s_nop 0
	v_mul_f32_e32 v16, v22, v16
	v_mul_f32_e32 v22, v16, v18
	v_mul_f32_e32 v16, 0xbfb8aa3b, v23
	v_exp_f32_e32 v16, v16
	s_nop 0
	v_add_f32_e32 v16, 1.0, v16
	v_rcp_f32_e32 v16, v16
	s_nop 0
	v_mul_f32_e32 v16, v23, v16
	v_mul_f32_e32 v19, v16, v19
	v_cvt_pk_bf16_f32 v16, v24, v25
	v_cvt_pk_bf16_f32 v17, v26, v27
	v_cvt_pk_bf16_f32 v18, v28, v29
	v_cvt_pk_bf16_f32 v19, v22, v19
	global_store_dwordx4 v[20:21], v[16:19], off sc1
	s_nop 1
	v_mul_f32_e32 v18, 0xbfb8aa3b, v12
	v_exp_f32_e32 v18, v18
	v_add_u32_e32 v16, 0xb0, v144
	v_mad_i64_i32 v[16:17], s[8:9], v16, s11, v[138:139]
	v_add_f32_e32 v18, 1.0, v18
	v_rcp_f32_e32 v18, v18
	v_readlane_b32 s8, v255, 52
	v_readlane_b32 s9, v255, 53
	s_and_b64 vcc, exec, s[8:9]
	v_mul_f32_e32 v12, v12, v18
	v_mul_f32_e32 v8, v12, v8
	v_mul_f32_e32 v12, 0xbfb8aa3b, v13
	v_exp_f32_e32 v12, v12
	s_mov_b32 s8, s0
	v_add_f32_e32 v12, 1.0, v12
	v_rcp_f32_e32 v12, v12
	s_nop 0
	v_mul_f32_e32 v12, v13, v12
	v_mul_f32_e32 v9, v12, v9
	v_mul_f32_e32 v12, 0xbfb8aa3b, v14
	v_exp_f32_e32 v12, v12
	s_nop 0
	v_add_f32_e32 v12, 1.0, v12
	v_rcp_f32_e32 v12, v12
	s_nop 0
	v_mul_f32_e32 v12, v14, v12
	v_mul_f32_e32 v10, v12, v10
	v_mul_f32_e32 v12, 0xbfb8aa3b, v15
	v_exp_f32_e32 v12, v12
	s_nop 0
	v_add_f32_e32 v12, 1.0, v12
	v_rcp_f32_e32 v12, v12
	s_nop 0
	v_mul_f32_e32 v12, v15, v12
	v_mul_f32_e32 v11, v12, v11
	v_mul_f32_e32 v12, 0xbfb8aa3b, v4
	v_exp_f32_e32 v12, v12
	s_nop 0
	v_add_f32_e32 v12, 1.0, v12
	v_rcp_f32_e32 v12, v12
	s_nop 0
	v_mul_f32_e32 v4, v4, v12
	v_mul_f32_e32 v12, v4, v0
	v_mul_f32_e32 v0, 0xbfb8aa3b, v5
	v_exp_f32_e32 v0, v0
	s_nop 0
	v_add_f32_e32 v0, 1.0, v0
	v_rcp_f32_e32 v0, v0
	s_nop 0
	v_mul_f32_e32 v0, v5, v0
	v_mul_f32_e32 v13, v0, v1
	v_mul_f32_e32 v0, 0xbfb8aa3b, v6
	v_exp_f32_e32 v0, v0
	v_lshl_add_u64 v[4:5], v[16:17], 0, v[112:113]
	v_add_f32_e32 v0, 1.0, v0
	v_rcp_f32_e32 v0, v0
	s_nop 0
	v_mul_f32_e32 v0, v6, v0
	v_mul_f32_e32 v6, v0, v2
	v_mul_f32_e32 v0, 0xbfb8aa3b, v7
	v_exp_f32_e32 v0, v0
	s_nop 0
	v_add_f32_e32 v0, 1.0, v0
	v_rcp_f32_e32 v0, v0
	s_nop 0
	v_mul_f32_e32 v0, v7, v0
	v_mul_f32_e32 v3, v0, v3
	v_cvt_pk_bf16_f32 v0, v8, v9
	v_cvt_pk_bf16_f32 v1, v10, v11
	v_cvt_pk_bf16_f32 v2, v12, v13
	v_cvt_pk_bf16_f32 v3, v6, v3
	global_store_dwordx4 v[4:5], v[0:3], off sc1
	s_cbranch_vccz .LBB0_614
	s_waitcnt vmcnt(0)
	v_readlane_b32 s0, v255, 44
	s_cmpk_gt_u32 s0, 0xff
	s_cbranch_scc1 .LBB0_621
	s_barrier
